# K-loop: moved the two A-half LDS-DMA pieces of super-phase 2 into the following super-phase 1 (4/4 instead of 6/2), wait vmcnt(6)
# speedup vs baseline: 1.0014x; 1.0014x over previous
; #define PG8_STAGE(bufoff, gbase, voff) do { _Pragma("unroll") for (int _i = 0; _i < 2; ++_i) \
;         __builtin_amdgcn_global_load_lds((const unsigned*)((const char*)(gbase) + (voff)[_i]), (PG8_LAS unsigned*)(lds + (bufoff) + ldsw + _i * 8192), 16, 0, 0); } while (0)
; #define PG8_LDA(dst, b, h) do { _Pragma("unroll") for (int m = 0; m < 4; ++m) _Pragma("unroll") for (int k = 0; k < 2; ++k) dst[m][k] = *(const PG8_LAS bf16x8*)(lds + PG8_SA(b, h) + aoff + m * 2048 + k * 1024); } while (0)
; #define PG8_LDB(dst, b, h) do { _Pragma("unroll") for (int n = 0; n < 2; ++n) _Pragma("unroll") for (int k = 0; k < 2; ++k) dst[n][k] = *(const PG8_LAS bf16x8*)(lds + PG8_SB(b, h) + boff + n * 2048 + k * 1024); } while (0)
; #define PG8_MMA(ai, bj, At, Bt) do { __builtin_amdgcn_s_setprio(1); _Pragma("unroll") for (int m = 0; m < 4; ++m) _Pragma("unroll") for (int n = 0; n < 2; ++n) _Pragma("unroll") for (int k = 0; k < 2; ++k) \
;         acc[ai][bj][m][n] = __builtin_amdgcn_mfma_f32_16x16x32_bf16(Bt[n][k], At[m][k], acc[ai][bj][m][n], 0, 0, 0); __builtin_amdgcn_s_setprio(0); } while (0)
; #define PG8_WAIT_V(n) asm volatile("s_waitcnt vmcnt(" #n ")" ::: "memory")
; #define PG8_WAIT_L(n) asm volatile("s_waitcnt lgkmcnt(" #n ")" ::: "memory")
; #define PG8_BAR __builtin_amdgcn_s_barrier()
; #define PG8_SCHED __builtin_amdgcn_sched_barrier(0)
; template <class Epi, class Sched, bool ALIGN_EPI = false, bool SP2 = false>
; __device__ __forceinline__ void gemm_phase(PG8_LAS unsigned char* lds, const Gemm g, const Sched S, const Epi E, const int tid) {
;     ...
;             PG8_LDB(B0, 0, 0); PG8_LDB(B1, 0, 1); PG8_SCHED; PG8_LDA(At, 0, 0); PG8_STAGE(PG8_SA(1, 1), a1 + hstepA, voffA);
;             PG8_WAIT_V(8); PG8_WAIT_L(0); PG8_BAR; PG8_MMA(0, 0, At, B0); PG8_MMA(0, 1, At, B1); PG8_BAR; PG8_SCHED;
;             PG8_LDA(At, 0, 1); PG8_STAGE(PG8_SB(0, 0), b2, voffB); PG8_STAGE(PG8_SB(0, 1), b2 + hstepB, voffB); PG8_STAGE(PG8_SA(0, 0), a2, voffA);
;             PG8_WAIT_V(8); PG8_WAIT_L(0); PG8_BAR; PG8_MMA(1, 0, At, B0); PG8_MMA(1, 1, At, B1); PG8_BAR; PG8_SCHED;
.LBB0_157:
	ds_read_b128 v[146:149], v169
	ds_read_b128 v[150:153], v169 offset:1024
	ds_read_b128 v[172:175], v169 offset:2048
	ds_read_b128 v[176:179], v169 offset:3072
	ds_read_b128 v[180:183], v170
	ds_read_b128 v[188:191], v170 offset:1024
	ds_read_b128 v[192:195], v170 offset:2048
	ds_read_b128 v[196:199], v170 offset:3072
	s_add_u32 s34, s30, 0xfffc0080
	s_addc_u32 s35, s31, -1
	s_cmp_eq_u32 s65, 12
	s_cselect_b32 s37, s23, s35
	s_cselect_b32 s36, s61, s34
	s_cselect_b32 s35, s15, s64
	s_cselect_b32 s34, s62, s63
	s_add_i32 m0, s29, 0xc000
	ds_read_b128 v[200:203], v171
	ds_read_b128 v[204:207], v171 offset:1024
	ds_read_b128 v[208:211], v171 offset:2048
	ds_read_b128 v[212:215], v171 offset:3072
	ds_read_b128 v[216:219], v171 offset:4096
	ds_read_b128 v[220:223], v171 offset:5120
	ds_read_b128 v[224:227], v171 offset:6144
	ds_read_b128 v[228:231], v171 offset:7168
	global_load_lds_dwordx4 v138, s[30:31]
	s_add_i32 m0, s29, 0xe000
	s_nop 0
	global_load_lds_dwordx4 v140, s[30:31]
	s_waitcnt vmcnt(8)
	s_waitcnt lgkmcnt(0)
	s_barrier
	s_setprio 1
	s_waitcnt lgkmcnt(0)
	v_mfma_f32_16x16x32_bf16 v[124:127], v[146:149], v[200:203], v[124:127]
	v_mfma_f32_16x16x32_bf16 v[120:123], v[172:175], v[200:203], v[120:123]
	v_mfma_f32_16x16x32_bf16 v[108:111], v[146:149], v[208:211], v[108:111]
	v_mfma_f32_16x16x32_bf16 v[104:107], v[172:175], v[208:211], v[104:107]
	v_mfma_f32_16x16x32_bf16 v[92:95], v[146:149], v[216:219], v[92:95]
	v_mfma_f32_16x16x32_bf16 v[88:91], v[172:175], v[216:219], v[88:91]
	v_mfma_f32_16x16x32_bf16 v[76:79], v[146:149], v[224:227], v[76:79]
	v_mfma_f32_16x16x32_bf16 v[72:75], v[172:175], v[224:227], v[72:75]
	v_mfma_f32_16x16x32_bf16 v[124:127], v[150:153], v[204:207], v[124:127]
	v_mfma_f32_16x16x32_bf16 v[120:123], v[176:179], v[204:207], v[120:123]
	v_mfma_f32_16x16x32_bf16 v[108:111], v[150:153], v[212:215], v[108:111]
	v_mfma_f32_16x16x32_bf16 v[104:107], v[176:179], v[212:215], v[104:107]
	v_mfma_f32_16x16x32_bf16 v[92:95], v[150:153], v[220:223], v[92:95]
	v_mfma_f32_16x16x32_bf16 v[88:91], v[176:179], v[220:223], v[88:91]
	v_mfma_f32_16x16x32_bf16 v[76:79], v[150:153], v[228:231], v[76:79]
	v_mfma_f32_16x16x32_bf16 v[72:75], v[176:179], v[228:231], v[72:75]
	s_setprio 0
	s_setprio 1
	v_mfma_f32_16x16x32_bf16 v[116:119], v[180:183], v[200:203], v[116:119]
	v_mfma_f32_16x16x32_bf16 v[112:115], v[192:195], v[200:203], v[112:115]
	v_mfma_f32_16x16x32_bf16 v[100:103], v[180:183], v[208:211], v[100:103]
	v_mfma_f32_16x16x32_bf16 v[96:99], v[192:195], v[208:211], v[96:99]
	v_mfma_f32_16x16x32_bf16 v[84:87], v[180:183], v[216:219], v[84:87]
	v_mfma_f32_16x16x32_bf16 v[80:83], v[192:195], v[216:219], v[80:83]
	v_mfma_f32_16x16x32_bf16 v[68:71], v[180:183], v[224:227], v[68:71]
	v_mfma_f32_16x16x32_bf16 v[64:67], v[192:195], v[224:227], v[64:67]
	v_mfma_f32_16x16x32_bf16 v[116:119], v[188:191], v[204:207], v[116:119]
	v_mfma_f32_16x16x32_bf16 v[112:115], v[196:199], v[204:207], v[112:115]
	v_mfma_f32_16x16x32_bf16 v[100:103], v[188:191], v[212:215], v[100:103]
	v_mfma_f32_16x16x32_bf16 v[96:99], v[196:199], v[212:215], v[96:99]
	v_mfma_f32_16x16x32_bf16 v[84:87], v[188:191], v[220:223], v[84:87]
	v_mfma_f32_16x16x32_bf16 v[80:83], v[196:199], v[220:223], v[80:83]
	v_mfma_f32_16x16x32_bf16 v[68:71], v[188:191], v[228:231], v[68:71]
	v_mfma_f32_16x16x32_bf16 v[64:67], v[196:199], v[228:231], v[64:67]
	s_setprio 0
	s_barrier
	s_add_u32 s98, s34, 0x80
	s_addc_u32 s99, s35, 0
	s_add_u32 s100, s36, 0x80
	s_addc_u32 s101, s37, 0
	s_add_i32 s66, s52, s13
	s_mov_b32 m0, s66
	ds_read_b128 v[200:203], v171 offset:16384
	ds_read_b128 v[204:207], v171 offset:17408
	ds_read_b128 v[208:211], v171 offset:18432
	ds_read_b128 v[212:215], v171 offset:19456
	ds_read_b128 v[216:219], v171 offset:20480
	ds_read_b128 v[220:223], v171 offset:21504
	ds_read_b128 v[224:227], v171 offset:22528
	ds_read_b128 v[228:231], v171 offset:23552
	global_load_lds_dwordx4 v130, s[34:35]
	s_add_i32 m0, s66, 0x2000
	s_add_u32 s66, s34, 0x40000
	s_addc_u32 s67, s35, 0
	s_add_i32 s69, s53, s13
	global_load_lds_dwordx4 v134, s[34:35]
	s_mov_b32 m0, s69
	s_nop 0
	global_load_lds_dwordx4 v130, s[66:67]
	s_add_i32 m0, s69, 0x2000
	s_nop 0
	global_load_lds_dwordx4 v134, s[66:67]
	s_waitcnt vmcnt(6)
	s_waitcnt lgkmcnt(0)
	s_barrier
	s_setprio 1
	s_waitcnt lgkmcnt(0)
	v_mfma_f32_16x16x32_bf16 v[60:63], v[146:149], v[200:203], v[60:63]
	v_mfma_f32_16x16x32_bf16 v[56:59], v[172:175], v[200:203], v[56:59]
	v_mfma_f32_16x16x32_bf16 v[44:47], v[146:149], v[208:211], v[44:47]
	v_mfma_f32_16x16x32_bf16 v[40:43], v[172:175], v[208:211], v[40:43]
	v_mfma_f32_16x16x32_bf16 v[28:31], v[146:149], v[216:219], v[28:31]
	v_mfma_f32_16x16x32_bf16 v[24:27], v[172:175], v[216:219], v[24:27]
	v_mfma_f32_16x16x32_bf16 v[12:15], v[146:149], v[224:227], v[12:15]
	v_mfma_f32_16x16x32_bf16 v[8:11], v[172:175], v[224:227], v[8:11]
	v_mfma_f32_16x16x32_bf16 v[60:63], v[150:153], v[204:207], v[60:63]
	v_mfma_f32_16x16x32_bf16 v[56:59], v[176:179], v[204:207], v[56:59]
	v_mfma_f32_16x16x32_bf16 v[44:47], v[150:153], v[212:215], v[44:47]
	v_mfma_f32_16x16x32_bf16 v[40:43], v[176:179], v[212:215], v[40:43]
	v_mfma_f32_16x16x32_bf16 v[28:31], v[150:153], v[220:223], v[28:31]
	v_mfma_f32_16x16x32_bf16 v[24:27], v[176:179], v[220:223], v[24:27]
	v_mfma_f32_16x16x32_bf16 v[12:15], v[150:153], v[228:231], v[12:15]
	v_mfma_f32_16x16x32_bf16 v[8:11], v[176:179], v[228:231], v[8:11]
	s_setprio 0
	s_setprio 1
	v_mfma_f32_16x16x32_bf16 v[52:55], v[180:183], v[200:203], v[52:55]
	v_mfma_f32_16x16x32_bf16 v[48:51], v[192:195], v[200:203], v[48:51]
	v_mfma_f32_16x16x32_bf16 v[36:39], v[180:183], v[208:211], v[36:39]
	v_mfma_f32_16x16x32_bf16 v[32:35], v[192:195], v[208:211], v[32:35]
	v_mfma_f32_16x16x32_bf16 v[20:23], v[180:183], v[216:219], v[20:23]
	v_mfma_f32_16x16x32_bf16 v[16:19], v[192:195], v[216:219], v[16:19]
	v_mfma_f32_16x16x32_bf16 v[4:7], v[180:183], v[224:227], v[4:7]
	v_mfma_f32_16x16x32_bf16 v[0:3], v[192:195], v[224:227], v[0:3]
	v_mfma_f32_16x16x32_bf16 v[52:55], v[188:191], v[204:207], v[52:55]
	v_mfma_f32_16x16x32_bf16 v[48:51], v[196:199], v[204:207], v[48:51]
	v_mfma_f32_16x16x32_bf16 v[36:39], v[188:191], v[212:215], v[36:39]
	v_mfma_f32_16x16x32_bf16 v[32:35], v[196:199], v[212:215], v[32:35]
	v_mfma_f32_16x16x32_bf16 v[20:23], v[188:191], v[220:223], v[20:23]
	v_mfma_f32_16x16x32_bf16 v[16:19], v[196:199], v[220:223], v[16:19]
	v_mfma_f32_16x16x32_bf16 v[4:7], v[188:191], v[228:231], v[4:7]
	v_mfma_f32_16x16x32_bf16 v[0:3], v[196:199], v[228:231], v[0:3]
	s_setprio 0
	s_barrier
; #define PG8_STAGE(bufoff, gbase, voff) do { _Pragma("unroll") for (int _i = 0; _i < 2; ++_i) \
;         __builtin_amdgcn_global_load_lds((const unsigned*)((const char*)(gbase) + (voff)[_i]), (PG8_LAS unsigned*)(lds + (bufoff) + ldsw + _i * 8192), 16, 0, 0); } while (0)
; #define PG8_LDA(dst, b, h) do { _Pragma("unroll") for (int m = 0; m < 4; ++m) _Pragma("unroll") for (int k = 0; k < 2; ++k) dst[m][k] = *(const PG8_LAS bf16x8*)(lds + PG8_SA(b, h) + aoff + m * 2048 + k * 1024); } while (0)
; #define PG8_LDB(dst, b, h) do { _Pragma("unroll") for (int n = 0; n < 2; ++n) _Pragma("unroll") for (int k = 0; k < 2; ++k) dst[n][k] = *(const PG8_LAS bf16x8*)(lds + PG8_SB(b, h) + boff + n * 2048 + k * 1024); } while (0)
; #define PG8_MMA(ai, bj, At, Bt) do { __builtin_amdgcn_s_setprio(1); _Pragma("unroll") for (int m = 0; m < 4; ++m) _Pragma("unroll") for (int n = 0; n < 2; ++n) _Pragma("unroll") for (int k = 0; k < 2; ++k) \
;         acc[ai][bj][m][n] = __builtin_amdgcn_mfma_f32_16x16x32_bf16(Bt[n][k], At[m][k], acc[ai][bj][m][n], 0, 0, 0); __builtin_amdgcn_s_setprio(0); } while (0)
; #define PG8_WAIT_V(n) asm volatile("s_waitcnt vmcnt(" #n ")" ::: "memory")
; #define PG8_WAIT_L(n) asm volatile("s_waitcnt lgkmcnt(" #n ")" ::: "memory")
; #define PG8_BAR __builtin_amdgcn_s_barrier()
; #define PG8_SCHED __builtin_amdgcn_sched_barrier(0)
; template <class Epi, class Sched, bool ALIGN_EPI = false, bool SP2 = false>
; __device__ __forceinline__ void gemm_phase(PG8_LAS unsigned char* lds, const Gemm g, const Sched S, const Epi E, const int tid) {
;     ...
;         for (int t = 0; t < nt; t += 2) {
;             const bool last = (t == nt - 2);
;             const char* a1 = cA + (size_t)(t + 1) * kstep;
;             const char* a2 = last ? nA : cA + (size_t)(t + 2) * kstep; const char* b2 = last ? nB : cB + (size_t)(t + 2) * kstep;
;     ...
;             PG8_LDB(B0, 1, 0); PG8_LDB(B1, 1, 1); PG8_SCHED; PG8_LDA(At, 1, 0); PG8_STAGE(PG8_SA(0, 1), a2 + hstepA, voffA);
;             PG8_WAIT_V(8); PG8_WAIT_L(0); PG8_BAR; PG8_MMA(0, 0, At, B0); PG8_MMA(0, 1, At, B1); PG8_BAR; PG8_SCHED;
;             PG8_LDA(At, 1, 1); PG8_STAGE(PG8_SB(1, 0), b3, voffB); PG8_STAGE(PG8_SB(1, 1), b3 + hstepB, voffB); PG8_STAGE(PG8_SA(1, 0), a3, voffA);
;             PG8_WAIT_V(8); PG8_WAIT_L(0); PG8_BAR; PG8_MMA(1, 0, At, B0); PG8_MMA(1, 1, At, B1); PG8_BAR; PG8_SCHED;
	s_add_i32 s66, 0, 0x18000
	s_add_i32 s67, 0, 0x1c000
	v_add_u32_e32 v176, s66, v166
	v_add_u32_e32 v187, s67, v166
	ds_read_b128 v[146:149], v176
	ds_read_b128 v[150:153], v176 offset:1024
	ds_read_b128 v[172:175], v176 offset:2048
	ds_read_b128 v[176:179], v176 offset:3072
	ds_read_b128 v[180:183], v187
	ds_read_b128 v[188:191], v187 offset:1024
	ds_read_b128 v[192:195], v187 offset:2048
	ds_read_b128 v[196:199], v187 offset:3072
	s_mov_b32 m0, s29
	s_nop 0
	global_load_lds_dwordx4 v128, s[36:37]
	s_mov_b32 m0, s47
	s_nop 0
	global_load_lds_dwordx4 v132, s[36:37]
	s_add_u32 s36, s36, 0x40000
	s_addc_u32 s37, s37, 0
	s_mov_b32 m0, s48
	ds_read_b128 v[200:203], v171 offset:32768
	ds_read_b128 v[204:207], v171 offset:33792
	ds_read_b128 v[208:211], v171 offset:34816
	ds_read_b128 v[212:215], v171 offset:35840
	ds_read_b128 v[216:219], v171 offset:36864
	ds_read_b128 v[220:223], v171 offset:37888
	ds_read_b128 v[224:227], v171 offset:38912
	ds_read_b128 v[228:231], v171 offset:39936
	global_load_lds_dwordx4 v128, s[36:37]
	s_mov_b32 m0, s49
	s_nop 0
	global_load_lds_dwordx4 v132, s[36:37]
	s_waitcnt vmcnt(8)
	s_waitcnt lgkmcnt(0)
	s_barrier
	s_setprio 1
	s_waitcnt lgkmcnt(0)
	v_mfma_f32_16x16x32_bf16 v[124:127], v[146:149], v[200:203], v[124:127]
	v_mfma_f32_16x16x32_bf16 v[120:123], v[172:175], v[200:203], v[120:123]
	v_mfma_f32_16x16x32_bf16 v[108:111], v[146:149], v[208:211], v[108:111]
	v_mfma_f32_16x16x32_bf16 v[104:107], v[172:175], v[208:211], v[104:107]
	v_mfma_f32_16x16x32_bf16 v[92:95], v[146:149], v[216:219], v[92:95]
	v_mfma_f32_16x16x32_bf16 v[88:91], v[172:175], v[216:219], v[88:91]
	v_mfma_f32_16x16x32_bf16 v[76:79], v[146:149], v[224:227], v[76:79]
	v_mfma_f32_16x16x32_bf16 v[72:75], v[172:175], v[224:227], v[72:75]
	v_mfma_f32_16x16x32_bf16 v[124:127], v[150:153], v[204:207], v[124:127]
	v_mfma_f32_16x16x32_bf16 v[120:123], v[176:179], v[204:207], v[120:123]
	v_mfma_f32_16x16x32_bf16 v[108:111], v[150:153], v[212:215], v[108:111]
	v_mfma_f32_16x16x32_bf16 v[104:107], v[176:179], v[212:215], v[104:107]
	v_mfma_f32_16x16x32_bf16 v[92:95], v[150:153], v[220:223], v[92:95]
	v_mfma_f32_16x16x32_bf16 v[88:91], v[176:179], v[220:223], v[88:91]
	v_mfma_f32_16x16x32_bf16 v[76:79], v[150:153], v[228:231], v[76:79]
	v_mfma_f32_16x16x32_bf16 v[72:75], v[176:179], v[228:231], v[72:75]
	s_setprio 0
	s_setprio 1
	v_mfma_f32_16x16x32_bf16 v[116:119], v[180:183], v[200:203], v[116:119]
	v_mfma_f32_16x16x32_bf16 v[112:115], v[192:195], v[200:203], v[112:115]
	v_mfma_f32_16x16x32_bf16 v[100:103], v[180:183], v[208:211], v[100:103]
	v_mfma_f32_16x16x32_bf16 v[96:99], v[192:195], v[208:211], v[96:99]
	v_mfma_f32_16x16x32_bf16 v[84:87], v[180:183], v[216:219], v[84:87]
	v_mfma_f32_16x16x32_bf16 v[80:83], v[192:195], v[216:219], v[80:83]
	v_mfma_f32_16x16x32_bf16 v[68:71], v[180:183], v[224:227], v[68:71]
	v_mfma_f32_16x16x32_bf16 v[64:67], v[192:195], v[224:227], v[64:67]
	v_mfma_f32_16x16x32_bf16 v[116:119], v[188:191], v[204:207], v[116:119]
	v_mfma_f32_16x16x32_bf16 v[112:115], v[196:199], v[204:207], v[112:115]
	v_mfma_f32_16x16x32_bf16 v[100:103], v[188:191], v[212:215], v[100:103]
	v_mfma_f32_16x16x32_bf16 v[96:99], v[196:199], v[212:215], v[96:99]
	v_mfma_f32_16x16x32_bf16 v[84:87], v[188:191], v[220:223], v[84:87]
	v_mfma_f32_16x16x32_bf16 v[80:83], v[196:199], v[220:223], v[80:83]
	v_mfma_f32_16x16x32_bf16 v[68:71], v[188:191], v[228:231], v[68:71]
	v_mfma_f32_16x16x32_bf16 v[64:67], v[196:199], v[228:231], v[64:67]
	s_setprio 0
	s_barrier
	s_add_i32 s36, s66, s13
	s_mov_b32 m0, s36
	ds_read_b128 v[200:203], v171 offset:49152
	ds_read_b128 v[204:207], v171 offset:50176
	ds_read_b128 v[208:211], v171 offset:51200
	ds_read_b128 v[212:215], v171 offset:52224
	ds_read_b128 v[216:219], v171 offset:53248
	ds_read_b128 v[220:223], v171 offset:54272
	ds_read_b128 v[224:227], v171 offset:55296
	ds_read_b128 v[228:231], v171 offset:56320
	global_load_lds_dwordx4 v130, s[98:99]
	s_add_i32 m0, s36, 0x2000
	s_add_u32 s34, s34, 0x40080
	s_addc_u32 s35, s35, 0
	s_add_i32 s36, s67, s13
	global_load_lds_dwordx4 v134, s[98:99]
	s_mov_b32 m0, s36
	s_nop 0
	global_load_lds_dwordx4 v130, s[34:35]
	s_add_i32 m0, s36, 0x2000
	s_nop 0
	global_load_lds_dwordx4 v134, s[34:35]
	s_mov_b32 m0, s50
	s_nop 0
	global_load_lds_dwordx4 v128, s[100:101]
	s_mov_b32 m0, s51
	s_nop 0
	global_load_lds_dwordx4 v132, s[100:101]
	s_waitcnt vmcnt(8)
	s_waitcnt lgkmcnt(0)
	s_barrier
	s_setprio 1
	s_waitcnt lgkmcnt(0)
	v_mfma_f32_16x16x32_bf16 v[60:63], v[146:149], v[200:203], v[60:63]
	v_mfma_f32_16x16x32_bf16 v[56:59], v[172:175], v[200:203], v[56:59]
	v_mfma_f32_16x16x32_bf16 v[44:47], v[146:149], v[208:211], v[44:47]
	v_mfma_f32_16x16x32_bf16 v[40:43], v[172:175], v[208:211], v[40:43]
	v_mfma_f32_16x16x32_bf16 v[28:31], v[146:149], v[216:219], v[28:31]
	v_mfma_f32_16x16x32_bf16 v[24:27], v[172:175], v[216:219], v[24:27]
	v_mfma_f32_16x16x32_bf16 v[12:15], v[146:149], v[224:227], v[12:15]
	v_mfma_f32_16x16x32_bf16 v[8:11], v[172:175], v[224:227], v[8:11]
	v_mfma_f32_16x16x32_bf16 v[60:63], v[150:153], v[204:207], v[60:63]
	v_mfma_f32_16x16x32_bf16 v[56:59], v[176:179], v[204:207], v[56:59]
	v_mfma_f32_16x16x32_bf16 v[44:47], v[150:153], v[212:215], v[44:47]
	v_mfma_f32_16x16x32_bf16 v[40:43], v[176:179], v[212:215], v[40:43]
	v_mfma_f32_16x16x32_bf16 v[28:31], v[150:153], v[220:223], v[28:31]
	v_mfma_f32_16x16x32_bf16 v[24:27], v[176:179], v[220:223], v[24:27]
	v_mfma_f32_16x16x32_bf16 v[12:15], v[150:153], v[228:231], v[12:15]
	v_mfma_f32_16x16x32_bf16 v[8:11], v[176:179], v[228:231], v[8:11]
	s_setprio 0
	s_setprio 1
	v_mfma_f32_16x16x32_bf16 v[52:55], v[180:183], v[200:203], v[52:55]
	v_mfma_f32_16x16x32_bf16 v[48:51], v[192:195], v[200:203], v[48:51]
	v_mfma_f32_16x16x32_bf16 v[36:39], v[180:183], v[208:211], v[36:39]
	v_mfma_f32_16x16x32_bf16 v[32:35], v[192:195], v[208:211], v[32:35]
	v_mfma_f32_16x16x32_bf16 v[20:23], v[180:183], v[216:219], v[20:23]
	v_mfma_f32_16x16x32_bf16 v[16:19], v[192:195], v[216:219], v[16:19]
	v_mfma_f32_16x16x32_bf16 v[4:7], v[180:183], v[224:227], v[4:7]
	v_mfma_f32_16x16x32_bf16 v[0:3], v[192:195], v[224:227], v[0:3]
	v_mfma_f32_16x16x32_bf16 v[52:55], v[188:191], v[204:207], v[52:55]
	v_mfma_f32_16x16x32_bf16 v[48:51], v[196:199], v[204:207], v[48:51]
	v_mfma_f32_16x16x32_bf16 v[36:39], v[188:191], v[212:215], v[36:39]
	v_mfma_f32_16x16x32_bf16 v[32:35], v[196:199], v[212:215], v[32:35]
	v_mfma_f32_16x16x32_bf16 v[20:23], v[188:191], v[220:223], v[20:23]
	v_mfma_f32_16x16x32_bf16 v[16:19], v[196:199], v[220:223], v[16:19]
	v_mfma_f32_16x16x32_bf16 v[4:7], v[188:191], v[228:231], v[4:7]
	v_mfma_f32_16x16x32_bf16 v[0:3], v[196:199], v[228:231], v[0:3]
	s_setprio 0
	s_barrier
	s_add_i32 s65, s65, 2
	s_add_u32 s30, s30, 0x100
	s_addc_u32 s31, s31, 0
	s_add_u32 s63, s63, 0x100
	s_addc_u32 s64, s64, 0
	s_cmp_gt_u32 s65, 13
	s_cbranch_scc0 .LBB0_157
	s_and_b64 vcc, exec, s[10:11]
	s_cbranch_vccz .LBB0_160
	s_barrier

; #define PG8_STAGE(bufoff, gbase, voff) do { _Pragma("unroll") for (int _i = 0; _i < 2; ++_i) \
;         __builtin_amdgcn_global_load_lds((const unsigned*)((const char*)(gbase) + (voff)[_i]), (PG8_LAS unsigned*)(lds + (bufoff) + ldsw + _i * 8192), 16, 0, 0); } while (0)
; #define PG8_LDA(dst, b, h) do { _Pragma("unroll") for (int m = 0; m < 4; ++m) _Pragma("unroll") for (int k = 0; k < 2; ++k) dst[m][k] = *(const PG8_LAS bf16x8*)(lds + PG8_SA(b, h) + aoff + m * 2048 + k * 1024); } while (0)
; #define PG8_LDB(dst, b, h) do { _Pragma("unroll") for (int n = 0; n < 2; ++n) _Pragma("unroll") for (int k = 0; k < 2; ++k) dst[n][k] = *(const PG8_LAS bf16x8*)(lds + PG8_SB(b, h) + boff + n * 2048 + k * 1024); } while (0)
; #define PG8_MMA(ai, bj, At, Bt) do { __builtin_amdgcn_s_setprio(1); _Pragma("unroll") for (int m = 0; m < 4; ++m) _Pragma("unroll") for (int n = 0; n < 2; ++n) _Pragma("unroll") for (int k = 0; k < 2; ++k) \
;         acc[ai][bj][m][n] = __builtin_amdgcn_mfma_f32_16x16x32_bf16(Bt[n][k], At[m][k], acc[ai][bj][m][n], 0, 0, 0); __builtin_amdgcn_s_setprio(0); } while (0)
; #define PG8_WAIT_V(n) asm volatile("s_waitcnt vmcnt(" #n ")" ::: "memory")
; #define PG8_WAIT_L(n) asm volatile("s_waitcnt lgkmcnt(" #n ")" ::: "memory")
; #define PG8_BAR __builtin_amdgcn_s_barrier()
; #define PG8_SCHED __builtin_amdgcn_sched_barrier(0)
; template <class Epi, class Sched, bool ALIGN_EPI = false, bool SP2 = false>
; __device__ __forceinline__ void gemm_phase(PG8_LAS unsigned char* lds, const Gemm g, const Sched S, const Epi E, const int tid) {
;     ...
;             PG8_LDB(B0, 0, 0); PG8_LDB(B1, 0, 1); PG8_SCHED; PG8_LDA(At, 0, 0); PG8_STAGE(PG8_SA(1, 1), a1 + hstepA, voffA);
;             PG8_WAIT_V(8); PG8_WAIT_L(0); PG8_BAR; PG8_MMA(0, 0, At, B0); PG8_MMA(0, 1, At, B1); PG8_BAR; PG8_SCHED;
;             PG8_LDA(At, 0, 1); PG8_STAGE(PG8_SB(0, 0), b2, voffB); PG8_STAGE(PG8_SB(0, 1), b2 + hstepB, voffB); PG8_STAGE(PG8_SA(0, 0), a2, voffA);
;             PG8_WAIT_V(8); PG8_WAIT_L(0); PG8_BAR; PG8_MMA(1, 0, At, B0); PG8_MMA(1, 1, At, B1); PG8_BAR; PG8_SCHED;
.LBB0_204:
	ds_read_b128 v[150:153], v147
	ds_read_b128 v[166:169], v147 offset:1024
	ds_read_b128 v[170:173], v147 offset:2048
	ds_read_b128 v[174:177], v147 offset:3072
	ds_read_b128 v[178:181], v148
	ds_read_b128 v[182:185], v148 offset:1024
	ds_read_b128 v[188:191], v148 offset:2048
	ds_read_b128 v[192:195], v148 offset:3072
	s_add_u32 s52, s50, 0xfffc0080
	s_addc_u32 s53, s51, -1
	s_cmp_eq_u32 s80, 12
	s_cselect_b32 s55, s37, s53
	s_cselect_b32 s54, s76, s52
	s_cselect_b32 s53, s35, s79
	s_cselect_b32 s52, s77, s78
	s_add_i32 m0, s49, 0xc000
	ds_read_b128 v[196:199], v149
	ds_read_b128 v[200:203], v149 offset:1024
	ds_read_b128 v[204:207], v149 offset:2048
	ds_read_b128 v[208:211], v149 offset:3072
	ds_read_b128 v[212:215], v149 offset:4096
	ds_read_b128 v[216:219], v149 offset:5120
	ds_read_b128 v[220:223], v149 offset:6144
	ds_read_b128 v[224:227], v149 offset:7168
	global_load_lds_dwordx4 v138, s[50:51]
	s_add_i32 m0, s49, 0xe000
	s_nop 0
	global_load_lds_dwordx4 v140, s[50:51]
	s_waitcnt vmcnt(8)
	s_waitcnt lgkmcnt(0)
	s_barrier
	s_setprio 1
	s_waitcnt lgkmcnt(0)
	v_mfma_f32_16x16x32_bf16 v[124:127], v[150:153], v[196:199], v[124:127]
	v_mfma_f32_16x16x32_bf16 v[120:123], v[170:173], v[196:199], v[120:123]
	v_mfma_f32_16x16x32_bf16 v[112:115], v[150:153], v[204:207], v[112:115]
	v_mfma_f32_16x16x32_bf16 v[104:107], v[170:173], v[204:207], v[104:107]
	v_mfma_f32_16x16x32_bf16 v[96:99], v[150:153], v[212:215], v[96:99]
	v_mfma_f32_16x16x32_bf16 v[88:91], v[170:173], v[212:215], v[88:91]
	v_mfma_f32_16x16x32_bf16 v[80:83], v[150:153], v[220:223], v[80:83]
	v_mfma_f32_16x16x32_bf16 v[72:75], v[170:173], v[220:223], v[72:75]
	v_mfma_f32_16x16x32_bf16 v[124:127], v[166:169], v[200:203], v[124:127]
	v_mfma_f32_16x16x32_bf16 v[120:123], v[174:177], v[200:203], v[120:123]
	v_mfma_f32_16x16x32_bf16 v[112:115], v[166:169], v[208:211], v[112:115]
	v_mfma_f32_16x16x32_bf16 v[104:107], v[174:177], v[208:211], v[104:107]
	v_mfma_f32_16x16x32_bf16 v[96:99], v[166:169], v[216:219], v[96:99]
	v_mfma_f32_16x16x32_bf16 v[88:91], v[174:177], v[216:219], v[88:91]
	v_mfma_f32_16x16x32_bf16 v[80:83], v[166:169], v[224:227], v[80:83]
	v_mfma_f32_16x16x32_bf16 v[72:75], v[174:177], v[224:227], v[72:75]
	s_setprio 0
	s_setprio 1
	v_mfma_f32_16x16x32_bf16 v[116:119], v[178:181], v[196:199], v[116:119]
	v_mfma_f32_16x16x32_bf16 v[108:111], v[188:191], v[196:199], v[108:111]
	v_mfma_f32_16x16x32_bf16 v[100:103], v[178:181], v[204:207], v[100:103]
	v_mfma_f32_16x16x32_bf16 v[92:95], v[188:191], v[204:207], v[92:95]
	v_mfma_f32_16x16x32_bf16 v[84:87], v[178:181], v[212:215], v[84:87]
	v_mfma_f32_16x16x32_bf16 v[76:79], v[188:191], v[212:215], v[76:79]
	v_mfma_f32_16x16x32_bf16 v[68:71], v[178:181], v[220:223], v[68:71]
	v_mfma_f32_16x16x32_bf16 v[64:67], v[188:191], v[220:223], v[64:67]
	v_mfma_f32_16x16x32_bf16 v[116:119], v[182:185], v[200:203], v[116:119]
	v_mfma_f32_16x16x32_bf16 v[108:111], v[192:195], v[200:203], v[108:111]
	v_mfma_f32_16x16x32_bf16 v[100:103], v[182:185], v[208:211], v[100:103]
	v_mfma_f32_16x16x32_bf16 v[92:95], v[192:195], v[208:211], v[92:95]
	v_mfma_f32_16x16x32_bf16 v[84:87], v[182:185], v[216:219], v[84:87]
	v_mfma_f32_16x16x32_bf16 v[76:79], v[192:195], v[216:219], v[76:79]
	v_mfma_f32_16x16x32_bf16 v[68:71], v[182:185], v[224:227], v[68:71]
	v_mfma_f32_16x16x32_bf16 v[64:67], v[192:195], v[224:227], v[64:67]
	s_setprio 0
	s_barrier
	s_add_u32 s98, s52, 0x80
	s_addc_u32 s99, s53, 0
	s_add_u32 s100, s54, 0x80
	s_addc_u32 s101, s55, 0
	s_add_i32 s81, s73, s65
	s_mov_b32 m0, s81
	ds_read_b128 v[196:199], v149 offset:16384
	ds_read_b128 v[200:203], v149 offset:17408
	ds_read_b128 v[204:207], v149 offset:18432
	ds_read_b128 v[208:211], v149 offset:19456
	ds_read_b128 v[212:215], v149 offset:20480
	ds_read_b128 v[216:219], v149 offset:21504
	ds_read_b128 v[220:223], v149 offset:22528
	ds_read_b128 v[224:227], v149 offset:23552
	global_load_lds_dwordx4 v130, s[52:53]
	s_add_i32 m0, s81, 0x2000
	s_add_u32 s82, s52, 0x40000
	s_addc_u32 s83, s53, 0
	s_add_i32 s81, s74, s65
	global_load_lds_dwordx4 v134, s[52:53]
	s_mov_b32 m0, s81
	s_nop 0
	global_load_lds_dwordx4 v130, s[82:83]
	s_add_i32 m0, s81, 0x2000
	s_nop 0
	global_load_lds_dwordx4 v134, s[82:83]
	s_waitcnt vmcnt(6)
	s_waitcnt lgkmcnt(0)
	s_barrier
	s_setprio 1
	s_waitcnt lgkmcnt(0)
	v_mfma_f32_16x16x32_bf16 v[60:63], v[150:153], v[196:199], v[60:63]
	v_mfma_f32_16x16x32_bf16 v[56:59], v[170:173], v[196:199], v[56:59]
	v_mfma_f32_16x16x32_bf16 v[52:55], v[150:153], v[204:207], v[52:55]
	v_mfma_f32_16x16x32_bf16 v[44:47], v[170:173], v[204:207], v[44:47]
	v_mfma_f32_16x16x32_bf16 v[36:39], v[150:153], v[212:215], v[36:39]
	v_mfma_f32_16x16x32_bf16 v[28:31], v[170:173], v[212:215], v[28:31]
	v_mfma_f32_16x16x32_bf16 v[20:23], v[150:153], v[220:223], v[20:23]
	v_mfma_f32_16x16x32_bf16 v[12:15], v[170:173], v[220:223], v[12:15]
	v_mfma_f32_16x16x32_bf16 v[60:63], v[166:169], v[200:203], v[60:63]
	v_mfma_f32_16x16x32_bf16 v[56:59], v[174:177], v[200:203], v[56:59]
	v_mfma_f32_16x16x32_bf16 v[52:55], v[166:169], v[208:211], v[52:55]
	v_mfma_f32_16x16x32_bf16 v[44:47], v[174:177], v[208:211], v[44:47]
	v_mfma_f32_16x16x32_bf16 v[36:39], v[166:169], v[216:219], v[36:39]
	v_mfma_f32_16x16x32_bf16 v[28:31], v[174:177], v[216:219], v[28:31]
	v_mfma_f32_16x16x32_bf16 v[20:23], v[166:169], v[224:227], v[20:23]
	v_mfma_f32_16x16x32_bf16 v[12:15], v[174:177], v[224:227], v[12:15]
	s_setprio 0
	s_setprio 1
	v_mfma_f32_16x16x32_bf16 v[48:51], v[178:181], v[196:199], v[48:51]
	v_mfma_f32_16x16x32_bf16 v[40:43], v[188:191], v[196:199], v[40:43]
	v_mfma_f32_16x16x32_bf16 v[32:35], v[178:181], v[204:207], v[32:35]
	v_mfma_f32_16x16x32_bf16 v[24:27], v[188:191], v[204:207], v[24:27]
	v_mfma_f32_16x16x32_bf16 v[16:19], v[178:181], v[212:215], v[16:19]
	v_mfma_f32_16x16x32_bf16 v[8:11], v[188:191], v[212:215], v[8:11]
	v_mfma_f32_16x16x32_bf16 v[4:7], v[178:181], v[220:223], v[4:7]
	v_mfma_f32_16x16x32_bf16 v[0:3], v[188:191], v[220:223], v[0:3]
	v_mfma_f32_16x16x32_bf16 v[48:51], v[182:185], v[200:203], v[48:51]
	v_mfma_f32_16x16x32_bf16 v[40:43], v[192:195], v[200:203], v[40:43]
	v_mfma_f32_16x16x32_bf16 v[32:35], v[182:185], v[208:211], v[32:35]
	v_mfma_f32_16x16x32_bf16 v[24:27], v[192:195], v[208:211], v[24:27]
	v_mfma_f32_16x16x32_bf16 v[16:19], v[182:185], v[216:219], v[16:19]
	v_mfma_f32_16x16x32_bf16 v[8:11], v[192:195], v[216:219], v[8:11]
	v_mfma_f32_16x16x32_bf16 v[4:7], v[182:185], v[224:227], v[4:7]
	v_mfma_f32_16x16x32_bf16 v[0:3], v[192:195], v[224:227], v[0:3]
	s_setprio 0
	s_barrier
; #define PG8_STAGE(bufoff, gbase, voff) do { _Pragma("unroll") for (int _i = 0; _i < 2; ++_i) \
;         __builtin_amdgcn_global_load_lds((const unsigned*)((const char*)(gbase) + (voff)[_i]), (PG8_LAS unsigned*)(lds + (bufoff) + ldsw + _i * 8192), 16, 0, 0); } while (0)
; #define PG8_LDA(dst, b, h) do { _Pragma("unroll") for (int m = 0; m < 4; ++m) _Pragma("unroll") for (int k = 0; k < 2; ++k) dst[m][k] = *(const PG8_LAS bf16x8*)(lds + PG8_SA(b, h) + aoff + m * 2048 + k * 1024); } while (0)
; #define PG8_LDB(dst, b, h) do { _Pragma("unroll") for (int n = 0; n < 2; ++n) _Pragma("unroll") for (int k = 0; k < 2; ++k) dst[n][k] = *(const PG8_LAS bf16x8*)(lds + PG8_SB(b, h) + boff + n * 2048 + k * 1024); } while (0)
; #define PG8_MMA(ai, bj, At, Bt) do { __builtin_amdgcn_s_setprio(1); _Pragma("unroll") for (int m = 0; m < 4; ++m) _Pragma("unroll") for (int n = 0; n < 2; ++n) _Pragma("unroll") for (int k = 0; k < 2; ++k) \
;         acc[ai][bj][m][n] = __builtin_amdgcn_mfma_f32_16x16x32_bf16(Bt[n][k], At[m][k], acc[ai][bj][m][n], 0, 0, 0); __builtin_amdgcn_s_setprio(0); } while (0)
; #define PG8_WAIT_V(n) asm volatile("s_waitcnt vmcnt(" #n ")" ::: "memory")
; #define PG8_WAIT_L(n) asm volatile("s_waitcnt lgkmcnt(" #n ")" ::: "memory")
; #define PG8_BAR __builtin_amdgcn_s_barrier()
; #define PG8_SCHED __builtin_amdgcn_sched_barrier(0)
; template <class Epi, class Sched, bool ALIGN_EPI = false, bool SP2 = false>
; __device__ __forceinline__ void gemm_phase(PG8_LAS unsigned char* lds, const Gemm g, const Sched S, const Epi E, const int tid) {
;     ...
;         for (int t = 0; t < nt; t += 2) {
;             const bool last = (t == nt - 2);
;             const char* a1 = cA + (size_t)(t + 1) * kstep;
;             const char* a2 = last ? nA : cA + (size_t)(t + 2) * kstep; const char* b2 = last ? nB : cB + (size_t)(t + 2) * kstep;
;     ...
;             PG8_LDB(B0, 1, 0); PG8_LDB(B1, 1, 1); PG8_SCHED; PG8_LDA(At, 1, 0); PG8_STAGE(PG8_SA(0, 1), a2 + hstepA, voffA);
;             PG8_WAIT_V(8); PG8_WAIT_L(0); PG8_BAR; PG8_MMA(0, 0, At, B0); PG8_MMA(0, 1, At, B1); PG8_BAR; PG8_SCHED;
;             PG8_LDA(At, 1, 1); PG8_STAGE(PG8_SB(1, 0), b3, voffB); PG8_STAGE(PG8_SB(1, 1), b3 + hstepB, voffB); PG8_STAGE(PG8_SA(1, 0), a3, voffA);
;             PG8_WAIT_V(8); PG8_WAIT_L(0); PG8_BAR; PG8_MMA(1, 0, At, B0); PG8_MMA(1, 1, At, B1); PG8_BAR; PG8_SCHED;
	s_add_i32 s81, 0, 0x18000
	v_add_u32_e32 v165, s81, v145
	s_add_i32 s82, 0, 0x1c000
	ds_read_b128 v[150:153], v165
	ds_read_b128 v[166:169], v165 offset:1024
	ds_read_b128 v[170:173], v165 offset:2048
	ds_read_b128 v[174:177], v165 offset:3072
	v_add_u32_e32 v165, s82, v145
	ds_read_b128 v[178:181], v165
	ds_read_b128 v[182:185], v165 offset:1024
	ds_read_b128 v[188:191], v165 offset:2048
	ds_read_b128 v[192:195], v165 offset:3072
	s_mov_b32 m0, s49
	s_nop 0
	global_load_lds_dwordx4 v128, s[54:55]
	s_mov_b32 m0, s66
	s_nop 0
	global_load_lds_dwordx4 v132, s[54:55]
	s_add_u32 s54, s54, 0x40000
	s_addc_u32 s55, s55, 0
	s_mov_b32 m0, s67
	ds_read_b128 v[196:199], v149 offset:32768
	ds_read_b128 v[200:203], v149 offset:33792
	ds_read_b128 v[204:207], v149 offset:34816
	ds_read_b128 v[208:211], v149 offset:35840
	ds_read_b128 v[212:215], v149 offset:36864
	ds_read_b128 v[216:219], v149 offset:37888
	ds_read_b128 v[220:223], v149 offset:38912
	ds_read_b128 v[224:227], v149 offset:39936
	global_load_lds_dwordx4 v128, s[54:55]
	s_mov_b32 m0, s69
	s_nop 0
	global_load_lds_dwordx4 v132, s[54:55]
	s_waitcnt vmcnt(8)
	s_waitcnt lgkmcnt(0)
	s_barrier
	s_setprio 1
	s_waitcnt lgkmcnt(0)
	v_mfma_f32_16x16x32_bf16 v[124:127], v[150:153], v[196:199], v[124:127]
	v_mfma_f32_16x16x32_bf16 v[120:123], v[170:173], v[196:199], v[120:123]
	v_mfma_f32_16x16x32_bf16 v[112:115], v[150:153], v[204:207], v[112:115]
	v_mfma_f32_16x16x32_bf16 v[104:107], v[170:173], v[204:207], v[104:107]
	v_mfma_f32_16x16x32_bf16 v[96:99], v[150:153], v[212:215], v[96:99]
	v_mfma_f32_16x16x32_bf16 v[88:91], v[170:173], v[212:215], v[88:91]
	v_mfma_f32_16x16x32_bf16 v[80:83], v[150:153], v[220:223], v[80:83]
	v_mfma_f32_16x16x32_bf16 v[72:75], v[170:173], v[220:223], v[72:75]
	v_mfma_f32_16x16x32_bf16 v[124:127], v[166:169], v[200:203], v[124:127]
	v_mfma_f32_16x16x32_bf16 v[120:123], v[174:177], v[200:203], v[120:123]
	v_mfma_f32_16x16x32_bf16 v[112:115], v[166:169], v[208:211], v[112:115]
	v_mfma_f32_16x16x32_bf16 v[104:107], v[174:177], v[208:211], v[104:107]
	v_mfma_f32_16x16x32_bf16 v[96:99], v[166:169], v[216:219], v[96:99]
	v_mfma_f32_16x16x32_bf16 v[88:91], v[174:177], v[216:219], v[88:91]
	v_mfma_f32_16x16x32_bf16 v[80:83], v[166:169], v[224:227], v[80:83]
	v_mfma_f32_16x16x32_bf16 v[72:75], v[174:177], v[224:227], v[72:75]
	s_setprio 0
	s_setprio 1
	v_mfma_f32_16x16x32_bf16 v[116:119], v[178:181], v[196:199], v[116:119]
	v_mfma_f32_16x16x32_bf16 v[108:111], v[188:191], v[196:199], v[108:111]
	v_mfma_f32_16x16x32_bf16 v[100:103], v[178:181], v[204:207], v[100:103]
	v_mfma_f32_16x16x32_bf16 v[92:95], v[188:191], v[204:207], v[92:95]
	v_mfma_f32_16x16x32_bf16 v[84:87], v[178:181], v[212:215], v[84:87]
	v_mfma_f32_16x16x32_bf16 v[76:79], v[188:191], v[212:215], v[76:79]
	v_mfma_f32_16x16x32_bf16 v[68:71], v[178:181], v[220:223], v[68:71]
	v_mfma_f32_16x16x32_bf16 v[64:67], v[188:191], v[220:223], v[64:67]
	v_mfma_f32_16x16x32_bf16 v[116:119], v[182:185], v[200:203], v[116:119]
	v_mfma_f32_16x16x32_bf16 v[108:111], v[192:195], v[200:203], v[108:111]
	v_mfma_f32_16x16x32_bf16 v[100:103], v[182:185], v[208:211], v[100:103]
	v_mfma_f32_16x16x32_bf16 v[92:95], v[192:195], v[208:211], v[92:95]
	v_mfma_f32_16x16x32_bf16 v[84:87], v[182:185], v[216:219], v[84:87]
	v_mfma_f32_16x16x32_bf16 v[76:79], v[192:195], v[216:219], v[76:79]
	v_mfma_f32_16x16x32_bf16 v[68:71], v[182:185], v[224:227], v[68:71]
	v_mfma_f32_16x16x32_bf16 v[64:67], v[192:195], v[224:227], v[64:67]
	s_setprio 0
	s_barrier
	s_add_i32 s54, s81, s65
	s_mov_b32 m0, s54
	ds_read_b128 v[196:199], v149 offset:49152
	ds_read_b128 v[200:203], v149 offset:50176
	ds_read_b128 v[204:207], v149 offset:51200
	ds_read_b128 v[208:211], v149 offset:52224
	ds_read_b128 v[212:215], v149 offset:53248
	ds_read_b128 v[216:219], v149 offset:54272
	ds_read_b128 v[220:223], v149 offset:55296
	ds_read_b128 v[224:227], v149 offset:56320
	global_load_lds_dwordx4 v130, s[98:99]
	s_add_i32 m0, s54, 0x2000
	s_add_u32 s52, s52, 0x40080
	s_addc_u32 s53, s53, 0
	s_add_i32 s54, s82, s65
	global_load_lds_dwordx4 v134, s[98:99]
	s_mov_b32 m0, s54
	s_nop 0
	global_load_lds_dwordx4 v130, s[52:53]
	s_add_i32 m0, s54, 0x2000
	s_nop 0
	global_load_lds_dwordx4 v134, s[52:53]
	s_mov_b32 m0, s71
	s_nop 0
	global_load_lds_dwordx4 v128, s[100:101]
	s_mov_b32 m0, s72
	s_nop 0
	global_load_lds_dwordx4 v132, s[100:101]
	s_waitcnt vmcnt(8)
	s_waitcnt lgkmcnt(0)
	s_barrier
	s_setprio 1
	s_waitcnt lgkmcnt(0)
	v_mfma_f32_16x16x32_bf16 v[60:63], v[150:153], v[196:199], v[60:63]
	v_mfma_f32_16x16x32_bf16 v[56:59], v[170:173], v[196:199], v[56:59]
	v_mfma_f32_16x16x32_bf16 v[52:55], v[150:153], v[204:207], v[52:55]
	v_mfma_f32_16x16x32_bf16 v[44:47], v[170:173], v[204:207], v[44:47]
	v_mfma_f32_16x16x32_bf16 v[36:39], v[150:153], v[212:215], v[36:39]
	v_mfma_f32_16x16x32_bf16 v[28:31], v[170:173], v[212:215], v[28:31]
	v_mfma_f32_16x16x32_bf16 v[20:23], v[150:153], v[220:223], v[20:23]
	v_mfma_f32_16x16x32_bf16 v[12:15], v[170:173], v[220:223], v[12:15]
	v_mfma_f32_16x16x32_bf16 v[60:63], v[166:169], v[200:203], v[60:63]
	v_mfma_f32_16x16x32_bf16 v[56:59], v[174:177], v[200:203], v[56:59]
	v_mfma_f32_16x16x32_bf16 v[52:55], v[166:169], v[208:211], v[52:55]
	v_mfma_f32_16x16x32_bf16 v[44:47], v[174:177], v[208:211], v[44:47]
	v_mfma_f32_16x16x32_bf16 v[36:39], v[166:169], v[216:219], v[36:39]
	v_mfma_f32_16x16x32_bf16 v[28:31], v[174:177], v[216:219], v[28:31]
	v_mfma_f32_16x16x32_bf16 v[20:23], v[166:169], v[224:227], v[20:23]
	v_mfma_f32_16x16x32_bf16 v[12:15], v[174:177], v[224:227], v[12:15]
	s_setprio 0
	s_setprio 1
	v_mfma_f32_16x16x32_bf16 v[48:51], v[178:181], v[196:199], v[48:51]
	v_mfma_f32_16x16x32_bf16 v[40:43], v[188:191], v[196:199], v[40:43]
	v_mfma_f32_16x16x32_bf16 v[32:35], v[178:181], v[204:207], v[32:35]
	v_mfma_f32_16x16x32_bf16 v[24:27], v[188:191], v[204:207], v[24:27]
	v_mfma_f32_16x16x32_bf16 v[16:19], v[178:181], v[212:215], v[16:19]
	v_mfma_f32_16x16x32_bf16 v[8:11], v[188:191], v[212:215], v[8:11]
	v_mfma_f32_16x16x32_bf16 v[4:7], v[178:181], v[220:223], v[4:7]
	v_mfma_f32_16x16x32_bf16 v[0:3], v[188:191], v[220:223], v[0:3]
	v_mfma_f32_16x16x32_bf16 v[48:51], v[182:185], v[200:203], v[48:51]
	v_mfma_f32_16x16x32_bf16 v[40:43], v[192:195], v[200:203], v[40:43]
	v_mfma_f32_16x16x32_bf16 v[32:35], v[182:185], v[208:211], v[32:35]
	v_mfma_f32_16x16x32_bf16 v[24:27], v[192:195], v[208:211], v[24:27]
	v_mfma_f32_16x16x32_bf16 v[16:19], v[182:185], v[216:219], v[16:19]
	v_mfma_f32_16x16x32_bf16 v[8:11], v[192:195], v[216:219], v[8:11]
	v_mfma_f32_16x16x32_bf16 v[4:7], v[182:185], v[224:227], v[4:7]
	v_mfma_f32_16x16x32_bf16 v[0:3], v[192:195], v[224:227], v[0:3]
	s_setprio 0
	s_barrier
	s_add_i32 s80, s80, 2
	s_add_u32 s50, s50, 0x100
	s_addc_u32 s51, s51, 0
	s_add_u32 s78, s78, 0x100
	s_addc_u32 s79, s79, 0
	s_cmp_gt_u32 s80, 13
	s_cbranch_scc0 .LBB0_204
	s_and_b64 vcc, exec, s[10:11]
	s_cbranch_vccz .LBB0_207
	s_barrier

; #define PG8_STAGE(bufoff, gbase, voff) do { _Pragma("unroll") for (int _i = 0; _i < 2; ++_i) \
;         __builtin_amdgcn_global_load_lds((const unsigned*)((const char*)(gbase) + (voff)[_i]), (PG8_LAS unsigned*)(lds + (bufoff) + ldsw + _i * 8192), 16, 0, 0); } while (0)
; #define PG8_LDA(dst, b, h) do { _Pragma("unroll") for (int m = 0; m < 4; ++m) _Pragma("unroll") for (int k = 0; k < 2; ++k) dst[m][k] = *(const PG8_LAS bf16x8*)(lds + PG8_SA(b, h) + aoff + m * 2048 + k * 1024); } while (0)
; #define PG8_LDB(dst, b, h) do { _Pragma("unroll") for (int n = 0; n < 2; ++n) _Pragma("unroll") for (int k = 0; k < 2; ++k) dst[n][k] = *(const PG8_LAS bf16x8*)(lds + PG8_SB(b, h) + boff + n * 2048 + k * 1024); } while (0)
; #define PG8_MMA(ai, bj, At, Bt) do { __builtin_amdgcn_s_setprio(1); _Pragma("unroll") for (int m = 0; m < 4; ++m) _Pragma("unroll") for (int n = 0; n < 2; ++n) _Pragma("unroll") for (int k = 0; k < 2; ++k) \
;         acc[ai][bj][m][n] = __builtin_amdgcn_mfma_f32_16x16x32_bf16(Bt[n][k], At[m][k], acc[ai][bj][m][n], 0, 0, 0); __builtin_amdgcn_s_setprio(0); } while (0)
; #define PG8_WAIT_V(n) asm volatile("s_waitcnt vmcnt(" #n ")" ::: "memory")
; #define PG8_WAIT_L(n) asm volatile("s_waitcnt lgkmcnt(" #n ")" ::: "memory")
; template <class Epi, class Sched, bool ALIGN_EPI = false, bool SP2 = false>
; __device__ __forceinline__ void gemm_phase(PG8_LAS unsigned char* lds, const Gemm g, const Sched S, const Epi E, const int tid) {
;     ...
;             const bool last = (t == nt - 2);
;             const char* a1 = cA + (size_t)(t + 1) * kstep;
;             const char* a2 = last ? nA : cA + (size_t)(t + 2) * kstep; const char* b2 = last ? nB : cB + (size_t)(t + 2) * kstep;
;             const char* a3 = a2 + kstep; const char* b3 = b2 + kstep;
;             if (last && has_next) S.a_ready(nxt);
;             if constexpr (SP2) {
;             PG8_LDB(B0, 0, 0); PG8_LDB(B1, 0, 1); PG8_SCHED; PG8_LDA(At, 0, 0); PG8_STAGE(PG8_SA(1, 1), a1 + hstepA, voffA);
;             PG8_WAIT_V(8); PG8_WAIT_L(0); PG8_BAR; PG8_MMA(0, 0, At, B0); PG8_MMA(0, 1, At, B1); PG8_BAR; PG8_SCHED;
;             PG8_LDA(At, 0, 1); PG8_STAGE(PG8_SB(0, 0), b2, voffB); PG8_STAGE(PG8_SB(0, 1), b2 + hstepB, voffB); PG8_STAGE(PG8_SA(0, 0), a2, voffA);
;             PG8_WAIT_V(8); PG8_WAIT_L(0); PG8_BAR; PG8_MMA(1, 0, At, B0); PG8_MMA(1, 1, At, B1); PG8_BAR; PG8_SCHED;
.LBB0_220:
	ds_read_b128 v[148:151], v145
	ds_read_b128 v[152:155], v145 offset:1024
	ds_read_b128 v[156:159], v145 offset:2048
	ds_read_b128 v[160:163], v145 offset:3072
	ds_read_b128 v[164:167], v146
	ds_read_b128 v[168:171], v146 offset:1024
	ds_read_b128 v[172:175], v146 offset:2048
	ds_read_b128 v[176:179], v146 offset:3072
	s_add_u32 s52, s50, 0xfffc0080
	s_addc_u32 s53, s51, -1
	s_cmp_eq_u32 s77, 12
	s_cselect_b32 s55, s37, s53
	s_cselect_b32 s54, s73, s52
	s_cselect_b32 s53, s35, s76
	s_cselect_b32 s52, s74, s75
	s_add_i32 m0, s49, 0xc000
	ds_read_b128 v[180:183], v147
	ds_read_b128 v[188:191], v147 offset:1024
	ds_read_b128 v[192:195], v147 offset:2048
	ds_read_b128 v[196:199], v147 offset:3072
	ds_read_b128 v[200:203], v147 offset:4096
	ds_read_b128 v[204:207], v147 offset:5120
	ds_read_b128 v[208:211], v147 offset:6144
	ds_read_b128 v[212:215], v147 offset:7168
	global_load_lds_dwordx4 v136, s[50:51]
	s_add_i32 m0, s49, 0xe000
	s_nop 0
	global_load_lds_dwordx4 v138, s[50:51]
	s_waitcnt vmcnt(8)
	s_waitcnt lgkmcnt(0)
	s_barrier
	s_setprio 1
	s_waitcnt lgkmcnt(0)
	v_mfma_f32_16x16x32_bf16 v[124:127], v[148:151], v[180:183], v[124:127]
	v_mfma_f32_16x16x32_bf16 v[120:123], v[156:159], v[180:183], v[120:123]
	v_mfma_f32_16x16x32_bf16 v[112:115], v[148:151], v[192:195], v[112:115]
	v_mfma_f32_16x16x32_bf16 v[104:107], v[156:159], v[192:195], v[104:107]
	v_mfma_f32_16x16x32_bf16 v[96:99], v[148:151], v[200:203], v[96:99]
	v_mfma_f32_16x16x32_bf16 v[88:91], v[156:159], v[200:203], v[88:91]
	v_mfma_f32_16x16x32_bf16 v[80:83], v[148:151], v[208:211], v[80:83]
	v_mfma_f32_16x16x32_bf16 v[72:75], v[156:159], v[208:211], v[72:75]
	v_mfma_f32_16x16x32_bf16 v[124:127], v[152:155], v[188:191], v[124:127]
	v_mfma_f32_16x16x32_bf16 v[120:123], v[160:163], v[188:191], v[120:123]
	v_mfma_f32_16x16x32_bf16 v[112:115], v[152:155], v[196:199], v[112:115]
	v_mfma_f32_16x16x32_bf16 v[104:107], v[160:163], v[196:199], v[104:107]
	v_mfma_f32_16x16x32_bf16 v[96:99], v[152:155], v[204:207], v[96:99]
	v_mfma_f32_16x16x32_bf16 v[88:91], v[160:163], v[204:207], v[88:91]
	v_mfma_f32_16x16x32_bf16 v[80:83], v[152:155], v[212:215], v[80:83]
	v_mfma_f32_16x16x32_bf16 v[72:75], v[160:163], v[212:215], v[72:75]
	s_setprio 0
	s_setprio 1
	v_mfma_f32_16x16x32_bf16 v[116:119], v[164:167], v[180:183], v[116:119]
	v_mfma_f32_16x16x32_bf16 v[108:111], v[172:175], v[180:183], v[108:111]
	v_mfma_f32_16x16x32_bf16 v[100:103], v[164:167], v[192:195], v[100:103]
	v_mfma_f32_16x16x32_bf16 v[92:95], v[172:175], v[192:195], v[92:95]
	v_mfma_f32_16x16x32_bf16 v[84:87], v[164:167], v[200:203], v[84:87]
	v_mfma_f32_16x16x32_bf16 v[76:79], v[172:175], v[200:203], v[76:79]
	v_mfma_f32_16x16x32_bf16 v[68:71], v[164:167], v[208:211], v[68:71]
	v_mfma_f32_16x16x32_bf16 v[64:67], v[172:175], v[208:211], v[64:67]
	v_mfma_f32_16x16x32_bf16 v[116:119], v[168:171], v[188:191], v[116:119]
	v_mfma_f32_16x16x32_bf16 v[108:111], v[176:179], v[188:191], v[108:111]
	v_mfma_f32_16x16x32_bf16 v[100:103], v[168:171], v[196:199], v[100:103]
	v_mfma_f32_16x16x32_bf16 v[92:95], v[176:179], v[196:199], v[92:95]
	v_mfma_f32_16x16x32_bf16 v[84:87], v[168:171], v[204:207], v[84:87]
	v_mfma_f32_16x16x32_bf16 v[76:79], v[176:179], v[204:207], v[76:79]
	v_mfma_f32_16x16x32_bf16 v[68:71], v[168:171], v[212:215], v[68:71]
	v_mfma_f32_16x16x32_bf16 v[64:67], v[176:179], v[212:215], v[64:67]
	s_setprio 0
	s_barrier
	s_add_u32 s98, s52, 0x80
	s_addc_u32 s99, s53, 0
	s_add_u32 s100, s54, 0x80
	s_addc_u32 s101, s55, 0
	s_add_i32 s78, s70, s62
	s_mov_b32 m0, s78
	ds_read_b128 v[180:183], v147 offset:16384
	ds_read_b128 v[188:191], v147 offset:17408
	ds_read_b128 v[192:195], v147 offset:18432
	ds_read_b128 v[196:199], v147 offset:19456
	ds_read_b128 v[200:203], v147 offset:20480
	ds_read_b128 v[204:207], v147 offset:21504
	ds_read_b128 v[208:211], v147 offset:22528
	ds_read_b128 v[212:215], v147 offset:23552
	global_load_lds_dwordx4 v130, s[52:53]
	s_add_i32 m0, s78, 0x2000
	s_add_u32 s78, s52, 0x40000
	s_addc_u32 s79, s53, 0
	s_add_i32 s80, s71, s62
	global_load_lds_dwordx4 v134, s[52:53]
	s_mov_b32 m0, s80
	s_nop 0
	global_load_lds_dwordx4 v130, s[78:79]
	s_add_i32 m0, s80, 0x2000
	s_nop 0
	global_load_lds_dwordx4 v134, s[78:79]
	s_waitcnt vmcnt(6)
	s_waitcnt lgkmcnt(0)
	s_barrier
	s_setprio 1
	s_waitcnt lgkmcnt(0)
	v_mfma_f32_16x16x32_bf16 v[60:63], v[148:151], v[180:183], v[60:63]
	v_mfma_f32_16x16x32_bf16 v[56:59], v[156:159], v[180:183], v[56:59]
	v_mfma_f32_16x16x32_bf16 v[52:55], v[148:151], v[192:195], v[52:55]
	v_mfma_f32_16x16x32_bf16 v[44:47], v[156:159], v[192:195], v[44:47]
	v_mfma_f32_16x16x32_bf16 v[36:39], v[148:151], v[200:203], v[36:39]
	v_mfma_f32_16x16x32_bf16 v[28:31], v[156:159], v[200:203], v[28:31]
	v_mfma_f32_16x16x32_bf16 v[20:23], v[148:151], v[208:211], v[20:23]
	v_mfma_f32_16x16x32_bf16 v[12:15], v[156:159], v[208:211], v[12:15]
	v_mfma_f32_16x16x32_bf16 v[60:63], v[152:155], v[188:191], v[60:63]
	v_mfma_f32_16x16x32_bf16 v[56:59], v[160:163], v[188:191], v[56:59]
	v_mfma_f32_16x16x32_bf16 v[52:55], v[152:155], v[196:199], v[52:55]
	v_mfma_f32_16x16x32_bf16 v[44:47], v[160:163], v[196:199], v[44:47]
	v_mfma_f32_16x16x32_bf16 v[36:39], v[152:155], v[204:207], v[36:39]
	v_mfma_f32_16x16x32_bf16 v[28:31], v[160:163], v[204:207], v[28:31]
	v_mfma_f32_16x16x32_bf16 v[20:23], v[152:155], v[212:215], v[20:23]
	v_mfma_f32_16x16x32_bf16 v[12:15], v[160:163], v[212:215], v[12:15]
	s_setprio 0
	s_setprio 1
	v_mfma_f32_16x16x32_bf16 v[48:51], v[164:167], v[180:183], v[48:51]
	v_mfma_f32_16x16x32_bf16 v[40:43], v[172:175], v[180:183], v[40:43]
	v_mfma_f32_16x16x32_bf16 v[32:35], v[164:167], v[192:195], v[32:35]
	v_mfma_f32_16x16x32_bf16 v[24:27], v[172:175], v[192:195], v[24:27]
	v_mfma_f32_16x16x32_bf16 v[16:19], v[164:167], v[200:203], v[16:19]
	v_mfma_f32_16x16x32_bf16 v[8:11], v[172:175], v[200:203], v[8:11]
	v_mfma_f32_16x16x32_bf16 v[4:7], v[164:167], v[208:211], v[4:7]
	v_mfma_f32_16x16x32_bf16 v[0:3], v[172:175], v[208:211], v[0:3]
	v_mfma_f32_16x16x32_bf16 v[48:51], v[168:171], v[188:191], v[48:51]
	v_mfma_f32_16x16x32_bf16 v[40:43], v[176:179], v[188:191], v[40:43]
	v_mfma_f32_16x16x32_bf16 v[32:35], v[168:171], v[196:199], v[32:35]
	v_mfma_f32_16x16x32_bf16 v[24:27], v[176:179], v[196:199], v[24:27]
	v_mfma_f32_16x16x32_bf16 v[16:19], v[168:171], v[204:207], v[16:19]
	v_mfma_f32_16x16x32_bf16 v[8:11], v[176:179], v[204:207], v[8:11]
	v_mfma_f32_16x16x32_bf16 v[4:7], v[168:171], v[212:215], v[4:7]
	v_mfma_f32_16x16x32_bf16 v[0:3], v[176:179], v[212:215], v[0:3]
	s_setprio 0
	s_barrier
; #define PG8_STAGE(bufoff, gbase, voff) do { _Pragma("unroll") for (int _i = 0; _i < 2; ++_i) \
;         __builtin_amdgcn_global_load_lds((const unsigned*)((const char*)(gbase) + (voff)[_i]), (PG8_LAS unsigned*)(lds + (bufoff) + ldsw + _i * 8192), 16, 0, 0); } while (0)
; #define PG8_LDA(dst, b, h) do { _Pragma("unroll") for (int m = 0; m < 4; ++m) _Pragma("unroll") for (int k = 0; k < 2; ++k) dst[m][k] = *(const PG8_LAS bf16x8*)(lds + PG8_SA(b, h) + aoff + m * 2048 + k * 1024); } while (0)
; #define PG8_LDB(dst, b, h) do { _Pragma("unroll") for (int n = 0; n < 2; ++n) _Pragma("unroll") for (int k = 0; k < 2; ++k) dst[n][k] = *(const PG8_LAS bf16x8*)(lds + PG8_SB(b, h) + boff + n * 2048 + k * 1024); } while (0)
; #define PG8_MMA(ai, bj, At, Bt) do { __builtin_amdgcn_s_setprio(1); _Pragma("unroll") for (int m = 0; m < 4; ++m) _Pragma("unroll") for (int n = 0; n < 2; ++n) _Pragma("unroll") for (int k = 0; k < 2; ++k) \
;         acc[ai][bj][m][n] = __builtin_amdgcn_mfma_f32_16x16x32_bf16(Bt[n][k], At[m][k], acc[ai][bj][m][n], 0, 0, 0); __builtin_amdgcn_s_setprio(0); } while (0)
; #define PG8_WAIT_V(n) asm volatile("s_waitcnt vmcnt(" #n ")" ::: "memory")
; #define PG8_WAIT_L(n) asm volatile("s_waitcnt lgkmcnt(" #n ")" ::: "memory")
; #define PG8_BAR __builtin_amdgcn_s_barrier()
; #define PG8_SCHED __builtin_amdgcn_sched_barrier(0)
; template <class Epi, class Sched, bool ALIGN_EPI = false, bool SP2 = false>
; __device__ __forceinline__ void gemm_phase(PG8_LAS unsigned char* lds, const Gemm g, const Sched S, const Epi E, const int tid) {
;     ...
;             PG8_LDB(B0, 1, 0); PG8_LDB(B1, 1, 1); PG8_SCHED; PG8_LDA(At, 1, 0); PG8_STAGE(PG8_SA(0, 1), a2 + hstepA, voffA);
;             PG8_WAIT_V(8); PG8_WAIT_L(0); PG8_BAR; PG8_MMA(0, 0, At, B0); PG8_MMA(0, 1, At, B1); PG8_BAR; PG8_SCHED;
;             PG8_LDA(At, 1, 1); PG8_STAGE(PG8_SB(1, 0), b3, voffB); PG8_STAGE(PG8_SB(1, 1), b3 + hstepB, voffB); PG8_STAGE(PG8_SA(1, 0), a3, voffA);
;             PG8_WAIT_V(8); PG8_WAIT_L(0); PG8_BAR; PG8_MMA(1, 0, At, B0); PG8_MMA(1, 1, At, B1); PG8_BAR; PG8_SCHED;
	s_add_i32 s78, 0, 0x18000
	s_add_i32 s79, 0, 0x1c000
	v_add_u32_e32 v160, s78, v143
	v_add_u32_e32 v176, s79, v143
	ds_read_b128 v[148:151], v160
	ds_read_b128 v[152:155], v160 offset:1024
	ds_read_b128 v[156:159], v160 offset:2048
	ds_read_b128 v[160:163], v160 offset:3072
	ds_read_b128 v[164:167], v176
	ds_read_b128 v[168:171], v176 offset:1024
	ds_read_b128 v[172:175], v176 offset:2048
	ds_read_b128 v[176:179], v176 offset:3072
	s_mov_b32 m0, s49
	s_nop 0
	global_load_lds_dwordx4 v128, s[54:55]
	s_mov_b32 m0, s63
	s_nop 0
	global_load_lds_dwordx4 v132, s[54:55]
	s_add_u32 s54, s54, 0x40000
	s_addc_u32 s55, s55, 0
	s_mov_b32 m0, s64
	ds_read_b128 v[180:183], v147 offset:32768
	ds_read_b128 v[188:191], v147 offset:33792
	ds_read_b128 v[192:195], v147 offset:34816
	ds_read_b128 v[196:199], v147 offset:35840
	ds_read_b128 v[200:203], v147 offset:36864
	ds_read_b128 v[204:207], v147 offset:37888
	ds_read_b128 v[208:211], v147 offset:38912
	ds_read_b128 v[212:215], v147 offset:39936
	global_load_lds_dwordx4 v128, s[54:55]
	s_mov_b32 m0, s65
	s_nop 0
	global_load_lds_dwordx4 v132, s[54:55]
	s_waitcnt vmcnt(8)
	s_waitcnt lgkmcnt(0)
	s_barrier
	s_setprio 1
	s_waitcnt lgkmcnt(0)
	v_mfma_f32_16x16x32_bf16 v[124:127], v[148:151], v[180:183], v[124:127]
	v_mfma_f32_16x16x32_bf16 v[120:123], v[156:159], v[180:183], v[120:123]
	v_mfma_f32_16x16x32_bf16 v[112:115], v[148:151], v[192:195], v[112:115]
	v_mfma_f32_16x16x32_bf16 v[104:107], v[156:159], v[192:195], v[104:107]
	v_mfma_f32_16x16x32_bf16 v[96:99], v[148:151], v[200:203], v[96:99]
	v_mfma_f32_16x16x32_bf16 v[88:91], v[156:159], v[200:203], v[88:91]
	v_mfma_f32_16x16x32_bf16 v[80:83], v[148:151], v[208:211], v[80:83]
	v_mfma_f32_16x16x32_bf16 v[72:75], v[156:159], v[208:211], v[72:75]
	v_mfma_f32_16x16x32_bf16 v[124:127], v[152:155], v[188:191], v[124:127]
	v_mfma_f32_16x16x32_bf16 v[120:123], v[160:163], v[188:191], v[120:123]
	v_mfma_f32_16x16x32_bf16 v[112:115], v[152:155], v[196:199], v[112:115]
	v_mfma_f32_16x16x32_bf16 v[104:107], v[160:163], v[196:199], v[104:107]
	v_mfma_f32_16x16x32_bf16 v[96:99], v[152:155], v[204:207], v[96:99]
	v_mfma_f32_16x16x32_bf16 v[88:91], v[160:163], v[204:207], v[88:91]
	v_mfma_f32_16x16x32_bf16 v[80:83], v[152:155], v[212:215], v[80:83]
	v_mfma_f32_16x16x32_bf16 v[72:75], v[160:163], v[212:215], v[72:75]
	s_setprio 0
	s_setprio 1
	v_mfma_f32_16x16x32_bf16 v[116:119], v[164:167], v[180:183], v[116:119]
	v_mfma_f32_16x16x32_bf16 v[108:111], v[172:175], v[180:183], v[108:111]
	v_mfma_f32_16x16x32_bf16 v[100:103], v[164:167], v[192:195], v[100:103]
	v_mfma_f32_16x16x32_bf16 v[92:95], v[172:175], v[192:195], v[92:95]
	v_mfma_f32_16x16x32_bf16 v[84:87], v[164:167], v[200:203], v[84:87]
	v_mfma_f32_16x16x32_bf16 v[76:79], v[172:175], v[200:203], v[76:79]
	v_mfma_f32_16x16x32_bf16 v[68:71], v[164:167], v[208:211], v[68:71]
	v_mfma_f32_16x16x32_bf16 v[64:67], v[172:175], v[208:211], v[64:67]
	v_mfma_f32_16x16x32_bf16 v[116:119], v[168:171], v[188:191], v[116:119]
	v_mfma_f32_16x16x32_bf16 v[108:111], v[176:179], v[188:191], v[108:111]
	v_mfma_f32_16x16x32_bf16 v[100:103], v[168:171], v[196:199], v[100:103]
	v_mfma_f32_16x16x32_bf16 v[92:95], v[176:179], v[196:199], v[92:95]
	v_mfma_f32_16x16x32_bf16 v[84:87], v[168:171], v[204:207], v[84:87]
	v_mfma_f32_16x16x32_bf16 v[76:79], v[176:179], v[204:207], v[76:79]
	v_mfma_f32_16x16x32_bf16 v[68:71], v[168:171], v[212:215], v[68:71]
	v_mfma_f32_16x16x32_bf16 v[64:67], v[176:179], v[212:215], v[64:67]
	s_setprio 0
	s_barrier
	s_add_i32 s54, s78, s62
	s_mov_b32 m0, s54
	ds_read_b128 v[180:183], v147 offset:49152
	ds_read_b128 v[188:191], v147 offset:50176
	ds_read_b128 v[192:195], v147 offset:51200
	ds_read_b128 v[196:199], v147 offset:52224
	ds_read_b128 v[200:203], v147 offset:53248
	ds_read_b128 v[204:207], v147 offset:54272
	ds_read_b128 v[208:211], v147 offset:55296
	ds_read_b128 v[212:215], v147 offset:56320
	global_load_lds_dwordx4 v130, s[98:99]
	s_add_i32 m0, s54, 0x2000
	s_add_u32 s52, s52, 0x40080
	s_addc_u32 s53, s53, 0
	s_add_i32 s54, s79, s62
	global_load_lds_dwordx4 v134, s[98:99]
	s_mov_b32 m0, s54
	s_nop 0
	global_load_lds_dwordx4 v130, s[52:53]
	s_add_i32 m0, s54, 0x2000
	s_nop 0
	global_load_lds_dwordx4 v134, s[52:53]
	s_mov_b32 m0, s67
	s_nop 0
	global_load_lds_dwordx4 v128, s[100:101]
	s_mov_b32 m0, s69
	s_nop 0
	global_load_lds_dwordx4 v132, s[100:101]
	s_waitcnt vmcnt(8)
	s_waitcnt lgkmcnt(0)
	s_barrier
	s_setprio 1
	s_waitcnt lgkmcnt(0)
	v_mfma_f32_16x16x32_bf16 v[60:63], v[148:151], v[180:183], v[60:63]
	v_mfma_f32_16x16x32_bf16 v[56:59], v[156:159], v[180:183], v[56:59]
	v_mfma_f32_16x16x32_bf16 v[52:55], v[148:151], v[192:195], v[52:55]
	v_mfma_f32_16x16x32_bf16 v[44:47], v[156:159], v[192:195], v[44:47]
	v_mfma_f32_16x16x32_bf16 v[36:39], v[148:151], v[200:203], v[36:39]
	v_mfma_f32_16x16x32_bf16 v[28:31], v[156:159], v[200:203], v[28:31]
	v_mfma_f32_16x16x32_bf16 v[20:23], v[148:151], v[208:211], v[20:23]
	v_mfma_f32_16x16x32_bf16 v[12:15], v[156:159], v[208:211], v[12:15]
	v_mfma_f32_16x16x32_bf16 v[60:63], v[152:155], v[188:191], v[60:63]
	v_mfma_f32_16x16x32_bf16 v[56:59], v[160:163], v[188:191], v[56:59]
	v_mfma_f32_16x16x32_bf16 v[52:55], v[152:155], v[196:199], v[52:55]
	v_mfma_f32_16x16x32_bf16 v[44:47], v[160:163], v[196:199], v[44:47]
	v_mfma_f32_16x16x32_bf16 v[36:39], v[152:155], v[204:207], v[36:39]
	v_mfma_f32_16x16x32_bf16 v[28:31], v[160:163], v[204:207], v[28:31]
	v_mfma_f32_16x16x32_bf16 v[20:23], v[152:155], v[212:215], v[20:23]
	v_mfma_f32_16x16x32_bf16 v[12:15], v[160:163], v[212:215], v[12:15]
	s_setprio 0
	s_setprio 1
	v_mfma_f32_16x16x32_bf16 v[48:51], v[164:167], v[180:183], v[48:51]
	v_mfma_f32_16x16x32_bf16 v[40:43], v[172:175], v[180:183], v[40:43]
	v_mfma_f32_16x16x32_bf16 v[32:35], v[164:167], v[192:195], v[32:35]
	v_mfma_f32_16x16x32_bf16 v[24:27], v[172:175], v[192:195], v[24:27]
	v_mfma_f32_16x16x32_bf16 v[16:19], v[164:167], v[200:203], v[16:19]
	v_mfma_f32_16x16x32_bf16 v[8:11], v[172:175], v[200:203], v[8:11]
	v_mfma_f32_16x16x32_bf16 v[4:7], v[164:167], v[208:211], v[4:7]
	v_mfma_f32_16x16x32_bf16 v[0:3], v[172:175], v[208:211], v[0:3]
	v_mfma_f32_16x16x32_bf16 v[48:51], v[168:171], v[188:191], v[48:51]
	v_mfma_f32_16x16x32_bf16 v[40:43], v[176:179], v[188:191], v[40:43]
	v_mfma_f32_16x16x32_bf16 v[32:35], v[168:171], v[196:199], v[32:35]
	v_mfma_f32_16x16x32_bf16 v[24:27], v[176:179], v[196:199], v[24:27]
	v_mfma_f32_16x16x32_bf16 v[16:19], v[168:171], v[204:207], v[16:19]
	v_mfma_f32_16x16x32_bf16 v[8:11], v[176:179], v[204:207], v[8:11]
	v_mfma_f32_16x16x32_bf16 v[4:7], v[168:171], v[212:215], v[4:7]
	v_mfma_f32_16x16x32_bf16 v[0:3], v[176:179], v[212:215], v[0:3]
	s_setprio 0
	s_barrier
	s_add_i32 s77, s77, 2
	s_add_u32 s50, s50, 0x100
	s_addc_u32 s51, s51, 0
	s_add_u32 s75, s75, 0x100
	s_addc_u32 s76, s76, 0
	s_cmp_gt_u32 s77, 13
	s_cbranch_scc0 .LBB0_220
	s_and_b64 vcc, exec, s[8:9]
	s_cbranch_vccz .LBB0_223
	s_barrier

; #define PG8_STAGE(bufoff, gbase, voff) do { _Pragma("unroll") for (int _i = 0; _i < 2; ++_i) \
;         __builtin_amdgcn_global_load_lds((const unsigned*)((const char*)(gbase) + (voff)[_i]), (PG8_LAS unsigned*)(lds + (bufoff) + ldsw + _i * 8192), 16, 0, 0); } while (0)
; #define PG8_LDA(dst, b, h) do { _Pragma("unroll") for (int m = 0; m < 4; ++m) _Pragma("unroll") for (int k = 0; k < 2; ++k) dst[m][k] = *(const PG8_LAS bf16x8*)(lds + PG8_SA(b, h) + aoff + m * 2048 + k * 1024); } while (0)
; #define PG8_LDB(dst, b, h) do { _Pragma("unroll") for (int n = 0; n < 2; ++n) _Pragma("unroll") for (int k = 0; k < 2; ++k) dst[n][k] = *(const PG8_LAS bf16x8*)(lds + PG8_SB(b, h) + boff + n * 2048 + k * 1024); } while (0)
; #define PG8_MMA(ai, bj, At, Bt) do { __builtin_amdgcn_s_setprio(1); _Pragma("unroll") for (int m = 0; m < 4; ++m) _Pragma("unroll") for (int n = 0; n < 2; ++n) _Pragma("unroll") for (int k = 0; k < 2; ++k) \
;         acc[ai][bj][m][n] = __builtin_amdgcn_mfma_f32_16x16x32_bf16(Bt[n][k], At[m][k], acc[ai][bj][m][n], 0, 0, 0); __builtin_amdgcn_s_setprio(0); } while (0)
; #define PG8_WAIT_V(n) asm volatile("s_waitcnt vmcnt(" #n ")" ::: "memory")
; #define PG8_WAIT_L(n) asm volatile("s_waitcnt lgkmcnt(" #n ")" ::: "memory")
; template <class Epi, class Sched, bool ALIGN_EPI = false, bool SP2 = false>
; __device__ __forceinline__ void gemm_phase(PG8_LAS unsigned char* lds, const Gemm g, const Sched S, const Epi E, const int tid) {
;     ...
;             const bool last = (t == nt - 2);
;             const char* a1 = cA + (size_t)(t + 1) * kstep;
;             const char* a2 = last ? nA : cA + (size_t)(t + 2) * kstep; const char* b2 = last ? nB : cB + (size_t)(t + 2) * kstep;
;             const char* a3 = a2 + kstep; const char* b3 = b2 + kstep;
;             if (last && has_next) S.a_ready(nxt);
;             if constexpr (SP2) {
;             PG8_LDB(B0, 0, 0); PG8_LDB(B1, 0, 1); PG8_SCHED; PG8_LDA(At, 0, 0); PG8_STAGE(PG8_SA(1, 1), a1 + hstepA, voffA);
;             PG8_WAIT_V(8); PG8_WAIT_L(0); PG8_BAR; PG8_MMA(0, 0, At, B0); PG8_MMA(0, 1, At, B1); PG8_BAR; PG8_SCHED;
;             PG8_LDA(At, 0, 1); PG8_STAGE(PG8_SB(0, 0), b2, voffB); PG8_STAGE(PG8_SB(0, 1), b2 + hstepB, voffB); PG8_STAGE(PG8_SA(0, 0), a2, voffA);
;             PG8_WAIT_V(8); PG8_WAIT_L(0); PG8_BAR; PG8_MMA(1, 0, At, B0); PG8_MMA(1, 1, At, B1); PG8_BAR; PG8_SCHED;
.LBB0_297:
	v_add_u32_e32 v162, s64, v149
	v_add_u32_e32 v178, s65, v149
	ds_read_b128 v[144:147], v162
	ds_read_b128 v[154:157], v162 offset:1024
	ds_read_b128 v[158:161], v162 offset:2048
	ds_read_b128 v[162:165], v162 offset:3072
	ds_read_b128 v[166:169], v178
	ds_read_b128 v[170:173], v178 offset:1024
	ds_read_b128 v[174:177], v178 offset:2048
	ds_read_b128 v[178:181], v178 offset:3072
	s_add_u32 s34, s30, 0x100
	s_addc_u32 s35, s31, 0
	s_cmp_eq_u32 s73, 40
	s_cselect_b32 s39, s7, s35
	s_cselect_b32 s38, s6, s34
	s_cselect_b32 s37, s29, s72
	s_cselect_b32 s36, s28, s71
	s_add_i32 m0, s54, 0xc000
	ds_read_b128 v[182:185], v153
	ds_read_b128 v[188:191], v153 offset:1024
	ds_read_b128 v[192:195], v153 offset:2048
	ds_read_b128 v[196:199], v153 offset:3072
	ds_read_b128 v[200:203], v153 offset:4096
	ds_read_b128 v[204:207], v153 offset:5120
	ds_read_b128 v[208:211], v153 offset:6144
	ds_read_b128 v[212:215], v153 offset:7168
	global_load_lds_dwordx4 v136, s[30:31]
	s_add_i32 m0, s54, 0xe000
	s_nop 0
	global_load_lds_dwordx4 v138, s[30:31]
	s_waitcnt vmcnt(8)
	s_waitcnt lgkmcnt(0)
	s_barrier
	s_setprio 1
	s_waitcnt lgkmcnt(0)
	v_mfma_f32_16x16x32_bf16 v[112:115], v[144:147], v[182:185], v[112:115]
	v_mfma_f32_16x16x32_bf16 v[120:123], v[158:161], v[182:185], v[120:123]
	v_mfma_f32_16x16x32_bf16 v[96:99], v[144:147], v[192:195], v[96:99]
	v_mfma_f32_16x16x32_bf16 v[104:107], v[158:161], v[192:195], v[104:107]
	v_mfma_f32_16x16x32_bf16 v[80:83], v[144:147], v[200:203], v[80:83]
	v_mfma_f32_16x16x32_bf16 v[88:91], v[158:161], v[200:203], v[88:91]
	v_mfma_f32_16x16x32_bf16 v[64:67], v[144:147], v[208:211], v[64:67]
	v_mfma_f32_16x16x32_bf16 v[72:75], v[158:161], v[208:211], v[72:75]
	v_mfma_f32_16x16x32_bf16 v[112:115], v[154:157], v[188:191], v[112:115]
	v_mfma_f32_16x16x32_bf16 v[120:123], v[162:165], v[188:191], v[120:123]
	v_mfma_f32_16x16x32_bf16 v[96:99], v[154:157], v[196:199], v[96:99]
	v_mfma_f32_16x16x32_bf16 v[104:107], v[162:165], v[196:199], v[104:107]
	v_mfma_f32_16x16x32_bf16 v[80:83], v[154:157], v[204:207], v[80:83]
	v_mfma_f32_16x16x32_bf16 v[88:91], v[162:165], v[204:207], v[88:91]
	v_mfma_f32_16x16x32_bf16 v[64:67], v[154:157], v[212:215], v[64:67]
	v_mfma_f32_16x16x32_bf16 v[72:75], v[162:165], v[212:215], v[72:75]
	s_setprio 0
	s_setprio 1
	v_mfma_f32_16x16x32_bf16 v[116:119], v[166:169], v[182:185], v[116:119]
	v_mfma_f32_16x16x32_bf16 v[124:127], v[174:177], v[182:185], v[124:127]
	v_mfma_f32_16x16x32_bf16 v[100:103], v[166:169], v[192:195], v[100:103]
	v_mfma_f32_16x16x32_bf16 v[108:111], v[174:177], v[192:195], v[108:111]
	v_mfma_f32_16x16x32_bf16 v[84:87], v[166:169], v[200:203], v[84:87]
	v_mfma_f32_16x16x32_bf16 v[92:95], v[174:177], v[200:203], v[92:95]
	v_mfma_f32_16x16x32_bf16 v[68:71], v[166:169], v[208:211], v[68:71]
	v_mfma_f32_16x16x32_bf16 v[76:79], v[174:177], v[208:211], v[76:79]
	v_mfma_f32_16x16x32_bf16 v[116:119], v[170:173], v[188:191], v[116:119]
	v_mfma_f32_16x16x32_bf16 v[124:127], v[178:181], v[188:191], v[124:127]
	v_mfma_f32_16x16x32_bf16 v[100:103], v[170:173], v[196:199], v[100:103]
	v_mfma_f32_16x16x32_bf16 v[108:111], v[178:181], v[196:199], v[108:111]
	v_mfma_f32_16x16x32_bf16 v[84:87], v[170:173], v[204:207], v[84:87]
	v_mfma_f32_16x16x32_bf16 v[92:95], v[178:181], v[204:207], v[92:95]
	v_mfma_f32_16x16x32_bf16 v[68:71], v[170:173], v[212:215], v[68:71]
	v_mfma_f32_16x16x32_bf16 v[76:79], v[178:181], v[212:215], v[76:79]
	s_setprio 0
	s_barrier
	s_add_u32 s98, s36, 0x80
	s_addc_u32 s99, s37, 0
	s_add_u32 s100, s38, 0x80
	s_addc_u32 s101, s39, 0
	s_add_i32 s30, s64, s51
	s_mov_b32 m0, s30
	ds_read_b128 v[182:185], v153 offset:16384
	ds_read_b128 v[188:191], v153 offset:17408
	ds_read_b128 v[192:195], v153 offset:18432
	ds_read_b128 v[196:199], v153 offset:19456
	ds_read_b128 v[200:203], v153 offset:20480
	ds_read_b128 v[204:207], v153 offset:21504
	ds_read_b128 v[208:211], v153 offset:22528
	ds_read_b128 v[212:215], v153 offset:23552
	global_load_lds_dwordx4 v130, s[36:37]
	s_add_i32 m0, s30, 0x2000
	s_add_u32 s30, s36, 0xb0000
	s_addc_u32 s31, s37, 0
	s_add_i32 s74, s65, s51
	global_load_lds_dwordx4 v134, s[36:37]
	s_mov_b32 m0, s74
	s_nop 0
	global_load_lds_dwordx4 v130, s[30:31]
	s_add_i32 m0, s74, 0x2000
	s_nop 0
	global_load_lds_dwordx4 v134, s[30:31]
	s_waitcnt vmcnt(6)
	s_waitcnt lgkmcnt(0)
	s_barrier
	s_setprio 1
	s_waitcnt lgkmcnt(0)
	v_mfma_f32_16x16x32_bf16 v[48:51], v[144:147], v[182:185], v[48:51]
	v_mfma_f32_16x16x32_bf16 v[56:59], v[158:161], v[182:185], v[56:59]
	v_mfma_f32_16x16x32_bf16 v[24:27], v[144:147], v[192:195], v[24:27]
	v_mfma_f32_16x16x32_bf16 v[32:35], v[158:161], v[192:195], v[32:35]
	v_mfma_f32_16x16x32_bf16 v[0:3], v[144:147], v[200:203], v[0:3]
	v_mfma_f32_16x16x32_bf16 v[4:7], v[158:161], v[200:203], v[4:7]
	v_mfma_f32_16x16x32_bf16 v[8:11], v[144:147], v[208:211], v[8:11]
	v_mfma_f32_16x16x32_bf16 v[16:19], v[158:161], v[208:211], v[16:19]
	v_mfma_f32_16x16x32_bf16 v[48:51], v[154:157], v[188:191], v[48:51]
	v_mfma_f32_16x16x32_bf16 v[56:59], v[162:165], v[188:191], v[56:59]
	v_mfma_f32_16x16x32_bf16 v[24:27], v[154:157], v[196:199], v[24:27]
	v_mfma_f32_16x16x32_bf16 v[32:35], v[162:165], v[196:199], v[32:35]
	v_mfma_f32_16x16x32_bf16 v[0:3], v[154:157], v[204:207], v[0:3]
	v_mfma_f32_16x16x32_bf16 v[4:7], v[162:165], v[204:207], v[4:7]
	v_mfma_f32_16x16x32_bf16 v[8:11], v[154:157], v[212:215], v[8:11]
	v_mfma_f32_16x16x32_bf16 v[16:19], v[162:165], v[212:215], v[16:19]
	s_setprio 0
	s_setprio 1
	v_mfma_f32_16x16x32_bf16 v[52:55], v[166:169], v[182:185], v[52:55]
	v_mfma_f32_16x16x32_bf16 v[60:63], v[174:177], v[182:185], v[60:63]
	v_mfma_f32_16x16x32_bf16 v[28:31], v[166:169], v[192:195], v[28:31]
	v_mfma_f32_16x16x32_bf16 v[36:39], v[174:177], v[192:195], v[36:39]
	v_mfma_f32_16x16x32_bf16 v[40:43], v[166:169], v[200:203], v[40:43]
	v_mfma_f32_16x16x32_bf16 v[44:47], v[174:177], v[200:203], v[44:47]
	v_mfma_f32_16x16x32_bf16 v[12:15], v[166:169], v[208:211], v[12:15]
	v_mfma_f32_16x16x32_bf16 v[20:23], v[174:177], v[208:211], v[20:23]
	v_mfma_f32_16x16x32_bf16 v[52:55], v[170:173], v[188:191], v[52:55]
	v_mfma_f32_16x16x32_bf16 v[60:63], v[178:181], v[188:191], v[60:63]
	v_mfma_f32_16x16x32_bf16 v[28:31], v[170:173], v[196:199], v[28:31]
	v_mfma_f32_16x16x32_bf16 v[36:39], v[178:181], v[196:199], v[36:39]
	v_mfma_f32_16x16x32_bf16 v[40:43], v[170:173], v[204:207], v[40:43]
	v_mfma_f32_16x16x32_bf16 v[44:47], v[178:181], v[204:207], v[44:47]
	v_mfma_f32_16x16x32_bf16 v[12:15], v[170:173], v[212:215], v[12:15]
	v_mfma_f32_16x16x32_bf16 v[20:23], v[178:181], v[212:215], v[20:23]
	s_setprio 0
	s_barrier
; #define PG8_STAGE(bufoff, gbase, voff) do { _Pragma("unroll") for (int _i = 0; _i < 2; ++_i) \
;         __builtin_amdgcn_global_load_lds((const unsigned*)((const char*)(gbase) + (voff)[_i]), (PG8_LAS unsigned*)(lds + (bufoff) + ldsw + _i * 8192), 16, 0, 0); } while (0)
; #define PG8_LDA(dst, b, h) do { _Pragma("unroll") for (int m = 0; m < 4; ++m) _Pragma("unroll") for (int k = 0; k < 2; ++k) dst[m][k] = *(const PG8_LAS bf16x8*)(lds + PG8_SA(b, h) + aoff + m * 2048 + k * 1024); } while (0)
; #define PG8_LDB(dst, b, h) do { _Pragma("unroll") for (int n = 0; n < 2; ++n) _Pragma("unroll") for (int k = 0; k < 2; ++k) dst[n][k] = *(const PG8_LAS bf16x8*)(lds + PG8_SB(b, h) + boff + n * 2048 + k * 1024); } while (0)
; #define PG8_MMA(ai, bj, At, Bt) do { __builtin_amdgcn_s_setprio(1); _Pragma("unroll") for (int m = 0; m < 4; ++m) _Pragma("unroll") for (int n = 0; n < 2; ++n) _Pragma("unroll") for (int k = 0; k < 2; ++k) \
;         acc[ai][bj][m][n] = __builtin_amdgcn_mfma_f32_16x16x32_bf16(Bt[n][k], At[m][k], acc[ai][bj][m][n], 0, 0, 0); __builtin_amdgcn_s_setprio(0); } while (0)
; #define PG8_WAIT_V(n) asm volatile("s_waitcnt vmcnt(" #n ")" ::: "memory")
; #define PG8_WAIT_L(n) asm volatile("s_waitcnt lgkmcnt(" #n ")" ::: "memory")
; #define PG8_BAR __builtin_amdgcn_s_barrier()
; #define PG8_SCHED __builtin_amdgcn_sched_barrier(0)
; template <class Epi, class Sched, bool ALIGN_EPI = false, bool SP2 = false>
; __device__ __forceinline__ void gemm_phase(PG8_LAS unsigned char* lds, const Gemm g, const Sched S, const Epi E, const int tid) {
;     ...
;             PG8_LDB(B0, 1, 0); PG8_LDB(B1, 1, 1); PG8_SCHED; PG8_LDA(At, 1, 0); PG8_STAGE(PG8_SA(0, 1), a2 + hstepA, voffA);
;             PG8_WAIT_V(8); PG8_WAIT_L(0); PG8_BAR; PG8_MMA(0, 0, At, B0); PG8_MMA(0, 1, At, B1); PG8_BAR; PG8_SCHED;
;             PG8_LDA(At, 1, 1); PG8_STAGE(PG8_SB(1, 0), b3, voffB); PG8_STAGE(PG8_SB(1, 1), b3 + hstepB, voffB); PG8_STAGE(PG8_SA(1, 0), a3, voffA);
;             PG8_WAIT_V(8); PG8_WAIT_L(0); PG8_BAR; PG8_MMA(1, 0, At, B0); PG8_MMA(1, 1, At, B1); PG8_BAR; PG8_SCHED;
	s_add_i32 s74, 0, 0x18000
	s_add_i32 s75, 0, 0x1c000
	v_add_u32_e32 v162, s74, v149
	v_add_u32_e32 v178, s75, v149
	ds_read_b128 v[144:147], v162
	ds_read_b128 v[154:157], v162 offset:1024
	ds_read_b128 v[158:161], v162 offset:2048
	ds_read_b128 v[162:165], v162 offset:3072
	ds_read_b128 v[166:169], v178
	ds_read_b128 v[170:173], v178 offset:1024
	ds_read_b128 v[174:177], v178 offset:2048
	ds_read_b128 v[178:181], v178 offset:3072
	s_add_u32 s30, s38, 0xb0000
	s_addc_u32 s31, s39, 0
	s_mov_b32 m0, s54
	s_nop 0
	global_load_lds_dwordx4 v128, s[38:39]
	s_mov_b32 m0, s55
	s_nop 0
	global_load_lds_dwordx4 v132, s[38:39]
	s_mov_b32 m0, s56
	ds_read_b128 v[182:185], v153 offset:32768
	ds_read_b128 v[188:191], v153 offset:33792
	ds_read_b128 v[192:195], v153 offset:34816
	ds_read_b128 v[196:199], v153 offset:35840
	ds_read_b128 v[200:203], v153 offset:36864
	ds_read_b128 v[204:207], v153 offset:37888
	ds_read_b128 v[208:211], v153 offset:38912
	ds_read_b128 v[212:215], v153 offset:39936
	global_load_lds_dwordx4 v128, s[30:31]
	s_mov_b32 m0, s57
	s_nop 0
	global_load_lds_dwordx4 v132, s[30:31]
	s_waitcnt vmcnt(8)
	s_waitcnt lgkmcnt(0)
	s_barrier
	s_setprio 1
	s_waitcnt lgkmcnt(0)
	v_mfma_f32_16x16x32_bf16 v[112:115], v[144:147], v[182:185], v[112:115]
	v_mfma_f32_16x16x32_bf16 v[120:123], v[158:161], v[182:185], v[120:123]
	v_mfma_f32_16x16x32_bf16 v[96:99], v[144:147], v[192:195], v[96:99]
	v_mfma_f32_16x16x32_bf16 v[104:107], v[158:161], v[192:195], v[104:107]
	v_mfma_f32_16x16x32_bf16 v[80:83], v[144:147], v[200:203], v[80:83]
	v_mfma_f32_16x16x32_bf16 v[88:91], v[158:161], v[200:203], v[88:91]
	v_mfma_f32_16x16x32_bf16 v[64:67], v[144:147], v[208:211], v[64:67]
	v_mfma_f32_16x16x32_bf16 v[72:75], v[158:161], v[208:211], v[72:75]
	v_mfma_f32_16x16x32_bf16 v[112:115], v[154:157], v[188:191], v[112:115]
	v_mfma_f32_16x16x32_bf16 v[120:123], v[162:165], v[188:191], v[120:123]
	v_mfma_f32_16x16x32_bf16 v[96:99], v[154:157], v[196:199], v[96:99]
	v_mfma_f32_16x16x32_bf16 v[104:107], v[162:165], v[196:199], v[104:107]
	v_mfma_f32_16x16x32_bf16 v[80:83], v[154:157], v[204:207], v[80:83]
	v_mfma_f32_16x16x32_bf16 v[88:91], v[162:165], v[204:207], v[88:91]
	v_mfma_f32_16x16x32_bf16 v[64:67], v[154:157], v[212:215], v[64:67]
	v_mfma_f32_16x16x32_bf16 v[72:75], v[162:165], v[212:215], v[72:75]
	s_setprio 0
	s_setprio 1
	v_mfma_f32_16x16x32_bf16 v[116:119], v[166:169], v[182:185], v[116:119]
	v_mfma_f32_16x16x32_bf16 v[124:127], v[174:177], v[182:185], v[124:127]
	v_mfma_f32_16x16x32_bf16 v[100:103], v[166:169], v[192:195], v[100:103]
	v_mfma_f32_16x16x32_bf16 v[108:111], v[174:177], v[192:195], v[108:111]
	v_mfma_f32_16x16x32_bf16 v[84:87], v[166:169], v[200:203], v[84:87]
	v_mfma_f32_16x16x32_bf16 v[92:95], v[174:177], v[200:203], v[92:95]
	v_mfma_f32_16x16x32_bf16 v[68:71], v[166:169], v[208:211], v[68:71]
	v_mfma_f32_16x16x32_bf16 v[76:79], v[174:177], v[208:211], v[76:79]
	v_mfma_f32_16x16x32_bf16 v[116:119], v[170:173], v[188:191], v[116:119]
	v_mfma_f32_16x16x32_bf16 v[124:127], v[178:181], v[188:191], v[124:127]
	v_mfma_f32_16x16x32_bf16 v[100:103], v[170:173], v[196:199], v[100:103]
	v_mfma_f32_16x16x32_bf16 v[108:111], v[178:181], v[196:199], v[108:111]
	v_mfma_f32_16x16x32_bf16 v[84:87], v[170:173], v[204:207], v[84:87]
	v_mfma_f32_16x16x32_bf16 v[92:95], v[178:181], v[204:207], v[92:95]
	v_mfma_f32_16x16x32_bf16 v[68:71], v[170:173], v[212:215], v[68:71]
	v_mfma_f32_16x16x32_bf16 v[76:79], v[178:181], v[212:215], v[76:79]
	s_setprio 0
	s_barrier
	s_add_i32 s30, s74, s51
	s_mov_b32 m0, s30
	ds_read_b128 v[182:185], v153 offset:49152
	ds_read_b128 v[188:191], v153 offset:50176
	ds_read_b128 v[192:195], v153 offset:51200
	ds_read_b128 v[196:199], v153 offset:52224
	ds_read_b128 v[200:203], v153 offset:53248
	ds_read_b128 v[204:207], v153 offset:54272
	ds_read_b128 v[208:211], v153 offset:55296
	ds_read_b128 v[212:215], v153 offset:56320
	global_load_lds_dwordx4 v130, s[98:99]
	s_add_i32 m0, s30, 0x2000
	s_add_u32 s30, s36, 0xb0080
	s_addc_u32 s31, s37, 0
	s_add_i32 s36, s75, s51
	global_load_lds_dwordx4 v134, s[98:99]
	s_mov_b32 m0, s36
	s_nop 0
	global_load_lds_dwordx4 v130, s[30:31]
	s_add_i32 m0, s36, 0x2000
	s_nop 0
	global_load_lds_dwordx4 v134, s[30:31]
	s_mov_b32 m0, s59
	s_nop 0
	global_load_lds_dwordx4 v128, s[100:101]
	s_mov_b32 m0, s60
	s_nop 0
	global_load_lds_dwordx4 v132, s[100:101]
	s_waitcnt vmcnt(8)
	s_waitcnt lgkmcnt(0)
	s_barrier
	s_setprio 1
	s_waitcnt lgkmcnt(0)
	v_mfma_f32_16x16x32_bf16 v[48:51], v[144:147], v[182:185], v[48:51]
	v_mfma_f32_16x16x32_bf16 v[56:59], v[158:161], v[182:185], v[56:59]
	v_mfma_f32_16x16x32_bf16 v[24:27], v[144:147], v[192:195], v[24:27]
	v_mfma_f32_16x16x32_bf16 v[32:35], v[158:161], v[192:195], v[32:35]
	v_mfma_f32_16x16x32_bf16 v[0:3], v[144:147], v[200:203], v[0:3]
	v_mfma_f32_16x16x32_bf16 v[4:7], v[158:161], v[200:203], v[4:7]
	v_mfma_f32_16x16x32_bf16 v[8:11], v[144:147], v[208:211], v[8:11]
	v_mfma_f32_16x16x32_bf16 v[16:19], v[158:161], v[208:211], v[16:19]
	v_mfma_f32_16x16x32_bf16 v[48:51], v[154:157], v[188:191], v[48:51]
	v_mfma_f32_16x16x32_bf16 v[56:59], v[162:165], v[188:191], v[56:59]
	v_mfma_f32_16x16x32_bf16 v[24:27], v[154:157], v[196:199], v[24:27]
	v_mfma_f32_16x16x32_bf16 v[32:35], v[162:165], v[196:199], v[32:35]
	v_mfma_f32_16x16x32_bf16 v[0:3], v[154:157], v[204:207], v[0:3]
	v_mfma_f32_16x16x32_bf16 v[4:7], v[162:165], v[204:207], v[4:7]
	v_mfma_f32_16x16x32_bf16 v[8:11], v[154:157], v[212:215], v[8:11]
	v_mfma_f32_16x16x32_bf16 v[16:19], v[162:165], v[212:215], v[16:19]
	s_setprio 0
	s_setprio 1
	v_mfma_f32_16x16x32_bf16 v[52:55], v[166:169], v[182:185], v[52:55]
	v_mfma_f32_16x16x32_bf16 v[60:63], v[174:177], v[182:185], v[60:63]
	v_mfma_f32_16x16x32_bf16 v[28:31], v[166:169], v[192:195], v[28:31]
	v_mfma_f32_16x16x32_bf16 v[36:39], v[174:177], v[192:195], v[36:39]
	v_mfma_f32_16x16x32_bf16 v[40:43], v[166:169], v[200:203], v[40:43]
	v_mfma_f32_16x16x32_bf16 v[44:47], v[174:177], v[200:203], v[44:47]
	v_mfma_f32_16x16x32_bf16 v[12:15], v[166:169], v[208:211], v[12:15]
	v_mfma_f32_16x16x32_bf16 v[20:23], v[174:177], v[208:211], v[20:23]
	v_mfma_f32_16x16x32_bf16 v[52:55], v[170:173], v[188:191], v[52:55]
	v_mfma_f32_16x16x32_bf16 v[60:63], v[178:181], v[188:191], v[60:63]
	v_mfma_f32_16x16x32_bf16 v[28:31], v[170:173], v[196:199], v[28:31]
	v_mfma_f32_16x16x32_bf16 v[36:39], v[178:181], v[196:199], v[36:39]
	v_mfma_f32_16x16x32_bf16 v[40:43], v[170:173], v[204:207], v[40:43]
	v_mfma_f32_16x16x32_bf16 v[44:47], v[178:181], v[204:207], v[44:47]
	v_mfma_f32_16x16x32_bf16 v[12:15], v[170:173], v[212:215], v[12:15]
	v_mfma_f32_16x16x32_bf16 v[20:23], v[178:181], v[212:215], v[20:23]
	s_setprio 0
	s_barrier
	s_add_i32 s73, s73, 2
	s_add_u32 s71, s71, 0x100
	s_addc_u32 s72, s72, 0
	s_cmp_gt_u32 s73, 41
	s_mov_b64 s[30:31], s[34:35]
	s_cbranch_scc0 .LBB0_297
	s_and_b64 vcc, exec, s[24:25]
	s_cbranch_vccz .LBB0_300
	s_barrier

; #define PG8_STAGE(bufoff, gbase, voff) do { _Pragma("unroll") for (int _i = 0; _i < 2; ++_i) \
;         __builtin_amdgcn_global_load_lds((const unsigned*)((const char*)(gbase) + (voff)[_i]), (PG8_LAS unsigned*)(lds + (bufoff) + ldsw + _i * 8192), 16, 0, 0); } while (0)
; #define PG8_LDA(dst, b, h) do { _Pragma("unroll") for (int m = 0; m < 4; ++m) _Pragma("unroll") for (int k = 0; k < 2; ++k) dst[m][k] = *(const PG8_LAS bf16x8*)(lds + PG8_SA(b, h) + aoff + m * 2048 + k * 1024); } while (0)
; #define PG8_LDB(dst, b, h) do { _Pragma("unroll") for (int n = 0; n < 2; ++n) _Pragma("unroll") for (int k = 0; k < 2; ++k) dst[n][k] = *(const PG8_LAS bf16x8*)(lds + PG8_SB(b, h) + boff + n * 2048 + k * 1024); } while (0)
; #define PG8_MMA(ai, bj, At, Bt) do { __builtin_amdgcn_s_setprio(1); _Pragma("unroll") for (int m = 0; m < 4; ++m) _Pragma("unroll") for (int n = 0; n < 2; ++n) _Pragma("unroll") for (int k = 0; k < 2; ++k) \
;         acc[ai][bj][m][n] = __builtin_amdgcn_mfma_f32_16x16x32_bf16(Bt[n][k], At[m][k], acc[ai][bj][m][n], 0, 0, 0); __builtin_amdgcn_s_setprio(0); } while (0)
; #define PG8_WAIT_V(n) asm volatile("s_waitcnt vmcnt(" #n ")" ::: "memory")
; #define PG8_WAIT_L(n) asm volatile("s_waitcnt lgkmcnt(" #n ")" ::: "memory")
; template <class Epi, class Sched, bool ALIGN_EPI = false, bool SP2 = false>
; __device__ __forceinline__ void gemm_phase(PG8_LAS unsigned char* lds, const Gemm g, const Sched S, const Epi E, const int tid) {
;     ...
;             const bool last = (t == nt - 2);
;             const char* a1 = cA + (size_t)(t + 1) * kstep;
;             const char* a2 = last ? nA : cA + (size_t)(t + 2) * kstep; const char* b2 = last ? nB : cB + (size_t)(t + 2) * kstep;
;             const char* a3 = a2 + kstep; const char* b3 = b2 + kstep;
;             if (last && has_next) S.a_ready(nxt);
;             if constexpr (SP2) {
;             PG8_LDB(B0, 0, 0); PG8_LDB(B1, 0, 1); PG8_SCHED; PG8_LDA(At, 0, 0); PG8_STAGE(PG8_SA(1, 1), a1 + hstepA, voffA);
;             PG8_WAIT_V(8); PG8_WAIT_L(0); PG8_BAR; PG8_MMA(0, 0, At, B0); PG8_MMA(0, 1, At, B1); PG8_BAR; PG8_SCHED;
;             PG8_LDA(At, 0, 1); PG8_STAGE(PG8_SB(0, 0), b2, voffB); PG8_STAGE(PG8_SB(0, 1), b2 + hstepB, voffB); PG8_STAGE(PG8_SA(0, 0), a2, voffA);
;             PG8_WAIT_V(8); PG8_WAIT_L(0); PG8_BAR; PG8_MMA(1, 0, At, B0); PG8_MMA(1, 1, At, B1); PG8_BAR; PG8_SCHED;
.LBB0_402:
	ds_read_b128 v[146:149], v169
	ds_read_b128 v[150:153], v169 offset:1024
	ds_read_b128 v[154:157], v169 offset:2048
	ds_read_b128 v[174:177], v169 offset:3072
	ds_read_b128 v[178:181], v170
	ds_read_b128 v[182:185], v170 offset:1024
	ds_read_b128 v[188:191], v170 offset:2048
	ds_read_b128 v[192:195], v170 offset:3072
	s_add_u32 s34, s30, 0xfffc0080
	s_addc_u32 s35, s31, -1
	s_cmp_eq_u32 s74, 12
	s_cselect_b32 s37, s25, s35
	s_cselect_b32 s36, s70, s34
	s_cselect_b32 s35, s23, s73
	s_cselect_b32 s34, s71, s72
	s_add_i32 m0, s52, 0xc000
	ds_read_b128 v[196:199], v171
	ds_read_b128 v[200:203], v171 offset:1024
	ds_read_b128 v[204:207], v171 offset:2048
	ds_read_b128 v[208:211], v171 offset:3072
	ds_read_b128 v[212:215], v171 offset:4096
	ds_read_b128 v[216:219], v171 offset:5120
	ds_read_b128 v[220:223], v171 offset:6144
	ds_read_b128 v[224:227], v171 offset:7168
	global_load_lds_dwordx4 v138, s[30:31]
	s_add_i32 m0, s52, 0xe000
	s_nop 0
	global_load_lds_dwordx4 v140, s[30:31]
	s_waitcnt vmcnt(8)
	s_waitcnt lgkmcnt(0)
	s_barrier
	s_setprio 1
	s_waitcnt lgkmcnt(0)
	v_mfma_f32_16x16x32_bf16 v[124:127], v[146:149], v[196:199], v[124:127]
	v_mfma_f32_16x16x32_bf16 v[120:123], v[154:157], v[196:199], v[120:123]
	v_mfma_f32_16x16x32_bf16 v[116:119], v[146:149], v[204:207], v[116:119]
	v_mfma_f32_16x16x32_bf16 v[112:115], v[154:157], v[204:207], v[112:115]
	v_mfma_f32_16x16x32_bf16 v[108:111], v[146:149], v[212:215], v[108:111]
	v_mfma_f32_16x16x32_bf16 v[104:107], v[154:157], v[212:215], v[104:107]
	v_mfma_f32_16x16x32_bf16 v[100:103], v[146:149], v[220:223], v[100:103]
	v_mfma_f32_16x16x32_bf16 v[96:99], v[154:157], v[220:223], v[96:99]
	v_mfma_f32_16x16x32_bf16 v[124:127], v[150:153], v[200:203], v[124:127]
	v_mfma_f32_16x16x32_bf16 v[120:123], v[174:177], v[200:203], v[120:123]
	v_mfma_f32_16x16x32_bf16 v[116:119], v[150:153], v[208:211], v[116:119]
	v_mfma_f32_16x16x32_bf16 v[112:115], v[174:177], v[208:211], v[112:115]
	v_mfma_f32_16x16x32_bf16 v[108:111], v[150:153], v[216:219], v[108:111]
	v_mfma_f32_16x16x32_bf16 v[104:107], v[174:177], v[216:219], v[104:107]
	v_mfma_f32_16x16x32_bf16 v[100:103], v[150:153], v[224:227], v[100:103]
	v_mfma_f32_16x16x32_bf16 v[96:99], v[174:177], v[224:227], v[96:99]
	s_setprio 0
	s_setprio 1
	v_mfma_f32_16x16x32_bf16 v[60:63], v[178:181], v[196:199], v[60:63]
	v_mfma_f32_16x16x32_bf16 v[56:59], v[188:191], v[196:199], v[56:59]
	v_mfma_f32_16x16x32_bf16 v[52:55], v[178:181], v[204:207], v[52:55]
	v_mfma_f32_16x16x32_bf16 v[48:51], v[188:191], v[204:207], v[48:51]
	v_mfma_f32_16x16x32_bf16 v[44:47], v[178:181], v[212:215], v[44:47]
	v_mfma_f32_16x16x32_bf16 v[40:43], v[188:191], v[212:215], v[40:43]
	v_mfma_f32_16x16x32_bf16 v[36:39], v[178:181], v[220:223], v[36:39]
	v_mfma_f32_16x16x32_bf16 v[32:35], v[188:191], v[220:223], v[32:35]
	v_mfma_f32_16x16x32_bf16 v[60:63], v[182:185], v[200:203], v[60:63]
	v_mfma_f32_16x16x32_bf16 v[56:59], v[192:195], v[200:203], v[56:59]
	v_mfma_f32_16x16x32_bf16 v[52:55], v[182:185], v[208:211], v[52:55]
	v_mfma_f32_16x16x32_bf16 v[48:51], v[192:195], v[208:211], v[48:51]
	v_mfma_f32_16x16x32_bf16 v[44:47], v[182:185], v[216:219], v[44:47]
	v_mfma_f32_16x16x32_bf16 v[40:43], v[192:195], v[216:219], v[40:43]
	v_mfma_f32_16x16x32_bf16 v[36:39], v[182:185], v[224:227], v[36:39]
	v_mfma_f32_16x16x32_bf16 v[32:35], v[192:195], v[224:227], v[32:35]
	s_setprio 0
	s_barrier
	s_add_u32 s98, s34, 0x80
	s_addc_u32 s99, s35, 0
	s_add_u32 s100, s36, 0x80
	s_addc_u32 s101, s37, 0
	s_add_i32 s75, s63, s33
	s_mov_b32 m0, s75
	ds_read_b128 v[196:199], v171 offset:16384
	ds_read_b128 v[200:203], v171 offset:17408
	ds_read_b128 v[204:207], v171 offset:18432
	ds_read_b128 v[208:211], v171 offset:19456
	ds_read_b128 v[212:215], v171 offset:20480
	ds_read_b128 v[216:219], v171 offset:21504
	ds_read_b128 v[220:223], v171 offset:22528
	ds_read_b128 v[224:227], v171 offset:23552
	global_load_lds_dwordx4 v134, s[34:35]
	s_add_i32 m0, s75, 0x2000
	s_add_u32 s76, s34, 0x40000
	s_addc_u32 s77, s35, 0
	s_add_i32 s75, s64, s33
	global_load_lds_dwordx4 v130, s[34:35]
	s_mov_b32 m0, s75
	s_nop 0
	global_load_lds_dwordx4 v134, s[76:77]
	s_add_i32 m0, s75, 0x2000
	s_nop 0
	global_load_lds_dwordx4 v130, s[76:77]
	s_waitcnt vmcnt(6)
	s_waitcnt lgkmcnt(0)
	s_barrier
	s_setprio 1
	s_waitcnt lgkmcnt(0)
	v_mfma_f32_16x16x32_bf16 v[92:95], v[146:149], v[196:199], v[92:95]
	v_mfma_f32_16x16x32_bf16 v[88:91], v[154:157], v[196:199], v[88:91]
	v_mfma_f32_16x16x32_bf16 v[84:87], v[146:149], v[204:207], v[84:87]
	v_mfma_f32_16x16x32_bf16 v[80:83], v[154:157], v[204:207], v[80:83]
	v_mfma_f32_16x16x32_bf16 v[76:79], v[146:149], v[212:215], v[76:79]
	v_mfma_f32_16x16x32_bf16 v[72:75], v[154:157], v[212:215], v[72:75]
	v_mfma_f32_16x16x32_bf16 v[68:71], v[146:149], v[220:223], v[68:71]
	v_mfma_f32_16x16x32_bf16 v[64:67], v[154:157], v[220:223], v[64:67]
	v_mfma_f32_16x16x32_bf16 v[92:95], v[150:153], v[200:203], v[92:95]
	v_mfma_f32_16x16x32_bf16 v[88:91], v[174:177], v[200:203], v[88:91]
	v_mfma_f32_16x16x32_bf16 v[84:87], v[150:153], v[208:211], v[84:87]
	v_mfma_f32_16x16x32_bf16 v[80:83], v[174:177], v[208:211], v[80:83]
	v_mfma_f32_16x16x32_bf16 v[76:79], v[150:153], v[216:219], v[76:79]
	v_mfma_f32_16x16x32_bf16 v[72:75], v[174:177], v[216:219], v[72:75]
	v_mfma_f32_16x16x32_bf16 v[68:71], v[150:153], v[224:227], v[68:71]
	v_mfma_f32_16x16x32_bf16 v[64:67], v[174:177], v[224:227], v[64:67]
	s_setprio 0
	s_setprio 1
	v_mfma_f32_16x16x32_bf16 v[28:31], v[178:181], v[196:199], v[28:31]
	v_mfma_f32_16x16x32_bf16 v[24:27], v[188:191], v[196:199], v[24:27]
	v_mfma_f32_16x16x32_bf16 v[20:23], v[178:181], v[204:207], v[20:23]
	v_mfma_f32_16x16x32_bf16 v[16:19], v[188:191], v[204:207], v[16:19]
	v_mfma_f32_16x16x32_bf16 v[12:15], v[178:181], v[212:215], v[12:15]
	v_mfma_f32_16x16x32_bf16 v[8:11], v[188:191], v[212:215], v[8:11]
	v_mfma_f32_16x16x32_bf16 v[4:7], v[178:181], v[220:223], v[4:7]
	v_mfma_f32_16x16x32_bf16 v[0:3], v[188:191], v[220:223], v[0:3]
	v_mfma_f32_16x16x32_bf16 v[28:31], v[182:185], v[200:203], v[28:31]
	v_mfma_f32_16x16x32_bf16 v[24:27], v[192:195], v[200:203], v[24:27]
	v_mfma_f32_16x16x32_bf16 v[20:23], v[182:185], v[208:211], v[20:23]
	v_mfma_f32_16x16x32_bf16 v[16:19], v[192:195], v[208:211], v[16:19]
	v_mfma_f32_16x16x32_bf16 v[12:15], v[182:185], v[216:219], v[12:15]
	v_mfma_f32_16x16x32_bf16 v[8:11], v[192:195], v[216:219], v[8:11]
	v_mfma_f32_16x16x32_bf16 v[4:7], v[182:185], v[224:227], v[4:7]
	v_mfma_f32_16x16x32_bf16 v[0:3], v[192:195], v[224:227], v[0:3]
	s_setprio 0
	s_barrier
; #define PG8_STAGE(bufoff, gbase, voff) do { _Pragma("unroll") for (int _i = 0; _i < 2; ++_i) \
;         __builtin_amdgcn_global_load_lds((const unsigned*)((const char*)(gbase) + (voff)[_i]), (PG8_LAS unsigned*)(lds + (bufoff) + ldsw + _i * 8192), 16, 0, 0); } while (0)
; #define PG8_LDA(dst, b, h) do { _Pragma("unroll") for (int m = 0; m < 4; ++m) _Pragma("unroll") for (int k = 0; k < 2; ++k) dst[m][k] = *(const PG8_LAS bf16x8*)(lds + PG8_SA(b, h) + aoff + m * 2048 + k * 1024); } while (0)
; #define PG8_LDB(dst, b, h) do { _Pragma("unroll") for (int n = 0; n < 2; ++n) _Pragma("unroll") for (int k = 0; k < 2; ++k) dst[n][k] = *(const PG8_LAS bf16x8*)(lds + PG8_SB(b, h) + boff + n * 2048 + k * 1024); } while (0)
; #define PG8_MMA(ai, bj, At, Bt) do { __builtin_amdgcn_s_setprio(1); _Pragma("unroll") for (int m = 0; m < 4; ++m) _Pragma("unroll") for (int n = 0; n < 2; ++n) _Pragma("unroll") for (int k = 0; k < 2; ++k) \
;         acc[ai][bj][m][n] = __builtin_amdgcn_mfma_f32_16x16x32_bf16(Bt[n][k], At[m][k], acc[ai][bj][m][n], 0, 0, 0); __builtin_amdgcn_s_setprio(0); } while (0)
; #define PG8_WAIT_V(n) asm volatile("s_waitcnt vmcnt(" #n ")" ::: "memory")
; #define PG8_WAIT_L(n) asm volatile("s_waitcnt lgkmcnt(" #n ")" ::: "memory")
; #define PG8_BAR __builtin_amdgcn_s_barrier()
; #define PG8_SCHED __builtin_amdgcn_sched_barrier(0)
; template <class Epi, class Sched, bool ALIGN_EPI = false, bool SP2 = false>
; __device__ __forceinline__ void gemm_phase(PG8_LAS unsigned char* lds, const Gemm g, const Sched S, const Epi E, const int tid) {
;     ...
;             PG8_LDB(B0, 1, 0); PG8_LDB(B1, 1, 1); PG8_SCHED; PG8_LDA(At, 1, 0); PG8_STAGE(PG8_SA(0, 1), a2 + hstepA, voffA);
;             PG8_WAIT_V(8); PG8_WAIT_L(0); PG8_BAR; PG8_MMA(0, 0, At, B0); PG8_MMA(0, 1, At, B1); PG8_BAR; PG8_SCHED;
;             PG8_LDA(At, 1, 1); PG8_STAGE(PG8_SB(1, 0), b3, voffB); PG8_STAGE(PG8_SB(1, 1), b3 + hstepB, voffB); PG8_STAGE(PG8_SA(1, 0), a3, voffA);
;             PG8_WAIT_V(8); PG8_WAIT_L(0); PG8_BAR; PG8_MMA(1, 0, At, B0); PG8_MMA(1, 1, At, B1); PG8_BAR; PG8_SCHED;
	s_add_i32 s75, 0, 0x18000
	v_add_u32_e32 v173, s75, v160
	s_add_i32 s76, 0, 0x1c000
	ds_read_b128 v[146:149], v173
	ds_read_b128 v[150:153], v173 offset:1024
	ds_read_b128 v[154:157], v173 offset:2048
	ds_read_b128 v[174:177], v173 offset:3072
	v_add_u32_e32 v173, s76, v160
	ds_read_b128 v[178:181], v173
	ds_read_b128 v[182:185], v173 offset:1024
	ds_read_b128 v[188:191], v173 offset:2048
	ds_read_b128 v[192:195], v173 offset:3072
	s_mov_b32 m0, s52
	s_nop 0
	global_load_lds_dwordx4 v136, s[36:37]
	s_mov_b32 m0, s54
	s_nop 0
	global_load_lds_dwordx4 v132, s[36:37]
	s_add_u32 s36, s36, 0x40000
	s_addc_u32 s37, s37, 0
	s_mov_b32 m0, s55
	ds_read_b128 v[196:199], v171 offset:32768
	ds_read_b128 v[200:203], v171 offset:33792
	ds_read_b128 v[204:207], v171 offset:34816
	ds_read_b128 v[208:211], v171 offset:35840
	ds_read_b128 v[212:215], v171 offset:36864
	ds_read_b128 v[216:219], v171 offset:37888
	ds_read_b128 v[220:223], v171 offset:38912
	ds_read_b128 v[224:227], v171 offset:39936
	global_load_lds_dwordx4 v136, s[36:37]
	s_mov_b32 m0, s57
	s_nop 0
	global_load_lds_dwordx4 v132, s[36:37]
	s_waitcnt vmcnt(8)
	s_waitcnt lgkmcnt(0)
	s_barrier
	s_setprio 1
	s_waitcnt lgkmcnt(0)
	v_mfma_f32_16x16x32_bf16 v[124:127], v[146:149], v[196:199], v[124:127]
	v_mfma_f32_16x16x32_bf16 v[120:123], v[154:157], v[196:199], v[120:123]
	v_mfma_f32_16x16x32_bf16 v[116:119], v[146:149], v[204:207], v[116:119]
	v_mfma_f32_16x16x32_bf16 v[112:115], v[154:157], v[204:207], v[112:115]
	v_mfma_f32_16x16x32_bf16 v[108:111], v[146:149], v[212:215], v[108:111]
	v_mfma_f32_16x16x32_bf16 v[104:107], v[154:157], v[212:215], v[104:107]
	v_mfma_f32_16x16x32_bf16 v[100:103], v[146:149], v[220:223], v[100:103]
	v_mfma_f32_16x16x32_bf16 v[96:99], v[154:157], v[220:223], v[96:99]
	v_mfma_f32_16x16x32_bf16 v[124:127], v[150:153], v[200:203], v[124:127]
	v_mfma_f32_16x16x32_bf16 v[120:123], v[174:177], v[200:203], v[120:123]
	v_mfma_f32_16x16x32_bf16 v[116:119], v[150:153], v[208:211], v[116:119]
	v_mfma_f32_16x16x32_bf16 v[112:115], v[174:177], v[208:211], v[112:115]
	v_mfma_f32_16x16x32_bf16 v[108:111], v[150:153], v[216:219], v[108:111]
	v_mfma_f32_16x16x32_bf16 v[104:107], v[174:177], v[216:219], v[104:107]
	v_mfma_f32_16x16x32_bf16 v[100:103], v[150:153], v[224:227], v[100:103]
	v_mfma_f32_16x16x32_bf16 v[96:99], v[174:177], v[224:227], v[96:99]
	s_setprio 0
	s_setprio 1
	v_mfma_f32_16x16x32_bf16 v[60:63], v[178:181], v[196:199], v[60:63]
	v_mfma_f32_16x16x32_bf16 v[56:59], v[188:191], v[196:199], v[56:59]
	v_mfma_f32_16x16x32_bf16 v[52:55], v[178:181], v[204:207], v[52:55]
	v_mfma_f32_16x16x32_bf16 v[48:51], v[188:191], v[204:207], v[48:51]
	v_mfma_f32_16x16x32_bf16 v[44:47], v[178:181], v[212:215], v[44:47]
	v_mfma_f32_16x16x32_bf16 v[40:43], v[188:191], v[212:215], v[40:43]
	v_mfma_f32_16x16x32_bf16 v[36:39], v[178:181], v[220:223], v[36:39]
	v_mfma_f32_16x16x32_bf16 v[32:35], v[188:191], v[220:223], v[32:35]
	v_mfma_f32_16x16x32_bf16 v[60:63], v[182:185], v[200:203], v[60:63]
	v_mfma_f32_16x16x32_bf16 v[56:59], v[192:195], v[200:203], v[56:59]
	v_mfma_f32_16x16x32_bf16 v[52:55], v[182:185], v[208:211], v[52:55]
	v_mfma_f32_16x16x32_bf16 v[48:51], v[192:195], v[208:211], v[48:51]
	v_mfma_f32_16x16x32_bf16 v[44:47], v[182:185], v[216:219], v[44:47]
	v_mfma_f32_16x16x32_bf16 v[40:43], v[192:195], v[216:219], v[40:43]
	v_mfma_f32_16x16x32_bf16 v[36:39], v[182:185], v[224:227], v[36:39]
	v_mfma_f32_16x16x32_bf16 v[32:35], v[192:195], v[224:227], v[32:35]
	s_setprio 0
	s_barrier
	s_add_i32 s36, s75, s33
	s_mov_b32 m0, s36
	ds_read_b128 v[196:199], v171 offset:49152
	ds_read_b128 v[200:203], v171 offset:50176
	ds_read_b128 v[204:207], v171 offset:51200
	ds_read_b128 v[208:211], v171 offset:52224
	ds_read_b128 v[212:215], v171 offset:53248
	ds_read_b128 v[216:219], v171 offset:54272
	ds_read_b128 v[220:223], v171 offset:55296
	ds_read_b128 v[224:227], v171 offset:56320
	global_load_lds_dwordx4 v134, s[98:99]
	s_add_i32 m0, s36, 0x2000
	s_add_u32 s34, s34, 0x40080
	s_addc_u32 s35, s35, 0
	s_add_i32 s36, s76, s33
	global_load_lds_dwordx4 v130, s[98:99]
	s_mov_b32 m0, s36
	s_nop 0
	global_load_lds_dwordx4 v134, s[34:35]
	s_add_i32 m0, s36, 0x2000
	s_nop 0
	global_load_lds_dwordx4 v130, s[34:35]
	s_mov_b32 m0, s58
	s_nop 0
	global_load_lds_dwordx4 v136, s[100:101]
	s_mov_b32 m0, s59
	s_nop 0
	global_load_lds_dwordx4 v132, s[100:101]
	s_waitcnt vmcnt(8)
	s_waitcnt lgkmcnt(0)
	s_barrier
	s_setprio 1
	s_waitcnt lgkmcnt(0)
	v_mfma_f32_16x16x32_bf16 v[92:95], v[146:149], v[196:199], v[92:95]
	v_mfma_f32_16x16x32_bf16 v[88:91], v[154:157], v[196:199], v[88:91]
	v_mfma_f32_16x16x32_bf16 v[84:87], v[146:149], v[204:207], v[84:87]
	v_mfma_f32_16x16x32_bf16 v[80:83], v[154:157], v[204:207], v[80:83]
	v_mfma_f32_16x16x32_bf16 v[76:79], v[146:149], v[212:215], v[76:79]
	v_mfma_f32_16x16x32_bf16 v[72:75], v[154:157], v[212:215], v[72:75]
	v_mfma_f32_16x16x32_bf16 v[68:71], v[146:149], v[220:223], v[68:71]
	v_mfma_f32_16x16x32_bf16 v[64:67], v[154:157], v[220:223], v[64:67]
	v_mfma_f32_16x16x32_bf16 v[92:95], v[150:153], v[200:203], v[92:95]
	v_mfma_f32_16x16x32_bf16 v[88:91], v[174:177], v[200:203], v[88:91]
	v_mfma_f32_16x16x32_bf16 v[84:87], v[150:153], v[208:211], v[84:87]
	v_mfma_f32_16x16x32_bf16 v[80:83], v[174:177], v[208:211], v[80:83]
	v_mfma_f32_16x16x32_bf16 v[76:79], v[150:153], v[216:219], v[76:79]
	v_mfma_f32_16x16x32_bf16 v[72:75], v[174:177], v[216:219], v[72:75]
	v_mfma_f32_16x16x32_bf16 v[68:71], v[150:153], v[224:227], v[68:71]
	v_mfma_f32_16x16x32_bf16 v[64:67], v[174:177], v[224:227], v[64:67]
	s_setprio 0
	s_setprio 1
	v_mfma_f32_16x16x32_bf16 v[28:31], v[178:181], v[196:199], v[28:31]
	v_mfma_f32_16x16x32_bf16 v[24:27], v[188:191], v[196:199], v[24:27]
	v_mfma_f32_16x16x32_bf16 v[20:23], v[178:181], v[204:207], v[20:23]
	v_mfma_f32_16x16x32_bf16 v[16:19], v[188:191], v[204:207], v[16:19]
	v_mfma_f32_16x16x32_bf16 v[12:15], v[178:181], v[212:215], v[12:15]
	v_mfma_f32_16x16x32_bf16 v[8:11], v[188:191], v[212:215], v[8:11]
	v_mfma_f32_16x16x32_bf16 v[4:7], v[178:181], v[220:223], v[4:7]
	v_mfma_f32_16x16x32_bf16 v[0:3], v[188:191], v[220:223], v[0:3]
	v_mfma_f32_16x16x32_bf16 v[28:31], v[182:185], v[200:203], v[28:31]
	v_mfma_f32_16x16x32_bf16 v[24:27], v[192:195], v[200:203], v[24:27]
	v_mfma_f32_16x16x32_bf16 v[20:23], v[182:185], v[208:211], v[20:23]
	v_mfma_f32_16x16x32_bf16 v[16:19], v[192:195], v[208:211], v[16:19]
	v_mfma_f32_16x16x32_bf16 v[12:15], v[182:185], v[216:219], v[12:15]
	v_mfma_f32_16x16x32_bf16 v[8:11], v[192:195], v[216:219], v[8:11]
	v_mfma_f32_16x16x32_bf16 v[4:7], v[182:185], v[224:227], v[4:7]
	v_mfma_f32_16x16x32_bf16 v[0:3], v[192:195], v[224:227], v[0:3]
	s_setprio 0
	s_barrier
	s_add_i32 s74, s74, 2
	s_add_u32 s30, s30, 0x100
	s_addc_u32 s31, s31, 0
	s_add_u32 s72, s72, 0x100
	s_addc_u32 s73, s73, 0
	s_cmp_gt_u32 s74, 13
	s_cbranch_scc0 .LBB0_402
	s_and_b64 vcc, exec, s[18:19]
	s_cbranch_vccz .LBB0_405
	s_barrier

; #define PG8_STAGE(bufoff, gbase, voff) do { _Pragma("unroll") for (int _i = 0; _i < 2; ++_i) \
;         __builtin_amdgcn_global_load_lds((const unsigned*)((const char*)(gbase) + (voff)[_i]), (PG8_LAS unsigned*)(lds + (bufoff) + ldsw + _i * 8192), 16, 0, 0); } while (0)
; #define PG8_LDA(dst, b, h) do { _Pragma("unroll") for (int m = 0; m < 4; ++m) _Pragma("unroll") for (int k = 0; k < 2; ++k) dst[m][k] = *(const PG8_LAS bf16x8*)(lds + PG8_SA(b, h) + aoff + m * 2048 + k * 1024); } while (0)
; #define PG8_LDB(dst, b, h) do { _Pragma("unroll") for (int n = 0; n < 2; ++n) _Pragma("unroll") for (int k = 0; k < 2; ++k) dst[n][k] = *(const PG8_LAS bf16x8*)(lds + PG8_SB(b, h) + boff + n * 2048 + k * 1024); } while (0)
; #define PG8_MMA(ai, bj, At, Bt) do { __builtin_amdgcn_s_setprio(1); _Pragma("unroll") for (int m = 0; m < 4; ++m) _Pragma("unroll") for (int n = 0; n < 2; ++n) _Pragma("unroll") for (int k = 0; k < 2; ++k) \
;         acc[ai][bj][m][n] = __builtin_amdgcn_mfma_f32_16x16x32_bf16(Bt[n][k], At[m][k], acc[ai][bj][m][n], 0, 0, 0); __builtin_amdgcn_s_setprio(0); } while (0)
; #define PG8_WAIT_V(n) asm volatile("s_waitcnt vmcnt(" #n ")" ::: "memory")
; #define PG8_WAIT_L(n) asm volatile("s_waitcnt lgkmcnt(" #n ")" ::: "memory")
; template <class Epi, class Sched, bool ALIGN_EPI = false, bool SP2 = false>
; __device__ __forceinline__ void gemm_phase(PG8_LAS unsigned char* lds, const Gemm g, const Sched S, const Epi E, const int tid) {
;     ...
;             const bool last = (t == nt - 2);
;             const char* a1 = cA + (size_t)(t + 1) * kstep;
;             const char* a2 = last ? nA : cA + (size_t)(t + 2) * kstep; const char* b2 = last ? nB : cB + (size_t)(t + 2) * kstep;
;             const char* a3 = a2 + kstep; const char* b3 = b2 + kstep;
;             if (last && has_next) S.a_ready(nxt);
;             if constexpr (SP2) {
;             PG8_LDB(B0, 0, 0); PG8_LDB(B1, 0, 1); PG8_SCHED; PG8_LDA(At, 0, 0); PG8_STAGE(PG8_SA(1, 1), a1 + hstepA, voffA);
;             PG8_WAIT_V(8); PG8_WAIT_L(0); PG8_BAR; PG8_MMA(0, 0, At, B0); PG8_MMA(0, 1, At, B1); PG8_BAR; PG8_SCHED;
;             PG8_LDA(At, 0, 1); PG8_STAGE(PG8_SB(0, 0), b2, voffB); PG8_STAGE(PG8_SB(0, 1), b2 + hstepB, voffB); PG8_STAGE(PG8_SA(0, 0), a2, voffA);
;             PG8_WAIT_V(8); PG8_WAIT_L(0); PG8_BAR; PG8_MMA(1, 0, At, B0); PG8_MMA(1, 1, At, B1); PG8_BAR; PG8_SCHED;
.LBB0_672:
	v_add_u32_e32 v162, s69, v149
	v_add_u32_e32 v178, s70, v149
	ds_read_b128 v[144:147], v162
	ds_read_b128 v[154:157], v162 offset:1024
	ds_read_b128 v[158:161], v162 offset:2048
	ds_read_b128 v[162:165], v162 offset:3072
	ds_read_b128 v[166:169], v178
	ds_read_b128 v[170:173], v178 offset:1024
	ds_read_b128 v[174:177], v178 offset:2048
	ds_read_b128 v[178:181], v178 offset:3072
	s_add_u32 s6, s38, 0x100
	s_addc_u32 s7, s39, 0
	s_cmp_eq_u32 s75, 12
	s_cselect_b32 s47, s31, s7
	s_cselect_b32 s46, s30, s6
	s_cselect_b32 s41, s29, s74
	s_cselect_b32 s40, s37, s73
	s_add_i32 m0, s58, 0xc000
	ds_read_b128 v[182:185], v153
	ds_read_b128 v[188:191], v153 offset:1024
	ds_read_b128 v[192:195], v153 offset:2048
	ds_read_b128 v[196:199], v153 offset:3072
	ds_read_b128 v[200:203], v153 offset:4096
	ds_read_b128 v[204:207], v153 offset:5120
	ds_read_b128 v[208:211], v153 offset:6144
	ds_read_b128 v[212:215], v153 offset:7168
	global_load_lds_dwordx4 v136, s[38:39]
	s_add_i32 m0, s58, 0xe000
	s_nop 0
	global_load_lds_dwordx4 v138, s[38:39]
	s_waitcnt vmcnt(8)
	s_waitcnt lgkmcnt(0)
	s_barrier
	s_setprio 1
	s_waitcnt lgkmcnt(0)
	v_mfma_f32_16x16x32_bf16 v[112:115], v[144:147], v[182:185], v[112:115]
	v_mfma_f32_16x16x32_bf16 v[120:123], v[158:161], v[182:185], v[120:123]
	v_mfma_f32_16x16x32_bf16 v[96:99], v[144:147], v[192:195], v[96:99]
	v_mfma_f32_16x16x32_bf16 v[104:107], v[158:161], v[192:195], v[104:107]
	v_mfma_f32_16x16x32_bf16 v[80:83], v[144:147], v[200:203], v[80:83]
	v_mfma_f32_16x16x32_bf16 v[88:91], v[158:161], v[200:203], v[88:91]
	v_mfma_f32_16x16x32_bf16 v[64:67], v[144:147], v[208:211], v[64:67]
	v_mfma_f32_16x16x32_bf16 v[72:75], v[158:161], v[208:211], v[72:75]
	v_mfma_f32_16x16x32_bf16 v[112:115], v[154:157], v[188:191], v[112:115]
	v_mfma_f32_16x16x32_bf16 v[120:123], v[162:165], v[188:191], v[120:123]
	v_mfma_f32_16x16x32_bf16 v[96:99], v[154:157], v[196:199], v[96:99]
	v_mfma_f32_16x16x32_bf16 v[104:107], v[162:165], v[196:199], v[104:107]
	v_mfma_f32_16x16x32_bf16 v[80:83], v[154:157], v[204:207], v[80:83]
	v_mfma_f32_16x16x32_bf16 v[88:91], v[162:165], v[204:207], v[88:91]
	v_mfma_f32_16x16x32_bf16 v[64:67], v[154:157], v[212:215], v[64:67]
	v_mfma_f32_16x16x32_bf16 v[72:75], v[162:165], v[212:215], v[72:75]
	s_setprio 0
	s_setprio 1
	v_mfma_f32_16x16x32_bf16 v[116:119], v[166:169], v[182:185], v[116:119]
	v_mfma_f32_16x16x32_bf16 v[124:127], v[174:177], v[182:185], v[124:127]
	v_mfma_f32_16x16x32_bf16 v[100:103], v[166:169], v[192:195], v[100:103]
	v_mfma_f32_16x16x32_bf16 v[108:111], v[174:177], v[192:195], v[108:111]
	v_mfma_f32_16x16x32_bf16 v[84:87], v[166:169], v[200:203], v[84:87]
	v_mfma_f32_16x16x32_bf16 v[92:95], v[174:177], v[200:203], v[92:95]
	v_mfma_f32_16x16x32_bf16 v[68:71], v[166:169], v[208:211], v[68:71]
	v_mfma_f32_16x16x32_bf16 v[76:79], v[174:177], v[208:211], v[76:79]
	v_mfma_f32_16x16x32_bf16 v[116:119], v[170:173], v[188:191], v[116:119]
	v_mfma_f32_16x16x32_bf16 v[124:127], v[178:181], v[188:191], v[124:127]
	v_mfma_f32_16x16x32_bf16 v[100:103], v[170:173], v[196:199], v[100:103]
	v_mfma_f32_16x16x32_bf16 v[108:111], v[178:181], v[196:199], v[108:111]
	v_mfma_f32_16x16x32_bf16 v[84:87], v[170:173], v[204:207], v[84:87]
	v_mfma_f32_16x16x32_bf16 v[92:95], v[178:181], v[204:207], v[92:95]
	v_mfma_f32_16x16x32_bf16 v[68:71], v[170:173], v[212:215], v[68:71]
	v_mfma_f32_16x16x32_bf16 v[76:79], v[178:181], v[212:215], v[76:79]
	s_setprio 0
	s_barrier
	s_add_u32 s98, s40, 0x80
	s_addc_u32 s99, s41, 0
	s_add_u32 s100, s46, 0x80
	s_addc_u32 s101, s47, 0
	s_add_i32 s38, s69, s33
	s_mov_b32 m0, s38
	ds_read_b128 v[182:185], v153 offset:16384
	ds_read_b128 v[188:191], v153 offset:17408
	ds_read_b128 v[192:195], v153 offset:18432
	ds_read_b128 v[196:199], v153 offset:19456
	ds_read_b128 v[200:203], v153 offset:20480
	ds_read_b128 v[204:207], v153 offset:21504
	ds_read_b128 v[208:211], v153 offset:22528
	ds_read_b128 v[212:215], v153 offset:23552
	global_load_lds_dwordx4 v130, s[40:41]
	s_add_i32 m0, s38, 0x2000
	s_add_u32 s38, s40, 0x40000
	s_addc_u32 s39, s41, 0
	s_add_i32 s76, s70, s33
	global_load_lds_dwordx4 v134, s[40:41]
	s_mov_b32 m0, s76
	s_nop 0
	global_load_lds_dwordx4 v130, s[38:39]
	s_add_i32 m0, s76, 0x2000
	s_nop 0
	global_load_lds_dwordx4 v134, s[38:39]
	s_waitcnt vmcnt(6)
	s_waitcnt lgkmcnt(0)
	s_barrier
	s_setprio 1
	s_waitcnt lgkmcnt(0)
	v_mfma_f32_16x16x32_bf16 v[48:51], v[144:147], v[182:185], v[48:51]
	v_mfma_f32_16x16x32_bf16 v[56:59], v[158:161], v[182:185], v[56:59]
	v_mfma_f32_16x16x32_bf16 v[24:27], v[144:147], v[192:195], v[24:27]
	v_mfma_f32_16x16x32_bf16 v[32:35], v[158:161], v[192:195], v[32:35]
	v_mfma_f32_16x16x32_bf16 v[0:3], v[144:147], v[200:203], v[0:3]
	v_mfma_f32_16x16x32_bf16 v[4:7], v[158:161], v[200:203], v[4:7]
	v_mfma_f32_16x16x32_bf16 v[8:11], v[144:147], v[208:211], v[8:11]
	v_mfma_f32_16x16x32_bf16 v[16:19], v[158:161], v[208:211], v[16:19]
	v_mfma_f32_16x16x32_bf16 v[48:51], v[154:157], v[188:191], v[48:51]
	v_mfma_f32_16x16x32_bf16 v[56:59], v[162:165], v[188:191], v[56:59]
	v_mfma_f32_16x16x32_bf16 v[24:27], v[154:157], v[196:199], v[24:27]
	v_mfma_f32_16x16x32_bf16 v[32:35], v[162:165], v[196:199], v[32:35]
	v_mfma_f32_16x16x32_bf16 v[0:3], v[154:157], v[204:207], v[0:3]
	v_mfma_f32_16x16x32_bf16 v[4:7], v[162:165], v[204:207], v[4:7]
	v_mfma_f32_16x16x32_bf16 v[8:11], v[154:157], v[212:215], v[8:11]
	v_mfma_f32_16x16x32_bf16 v[16:19], v[162:165], v[212:215], v[16:19]
	s_setprio 0
	s_setprio 1
	v_mfma_f32_16x16x32_bf16 v[52:55], v[166:169], v[182:185], v[52:55]
	v_mfma_f32_16x16x32_bf16 v[60:63], v[174:177], v[182:185], v[60:63]
	v_mfma_f32_16x16x32_bf16 v[28:31], v[166:169], v[192:195], v[28:31]
	v_mfma_f32_16x16x32_bf16 v[36:39], v[174:177], v[192:195], v[36:39]
	v_mfma_f32_16x16x32_bf16 v[40:43], v[166:169], v[200:203], v[40:43]
	v_mfma_f32_16x16x32_bf16 v[44:47], v[174:177], v[200:203], v[44:47]
	v_mfma_f32_16x16x32_bf16 v[12:15], v[166:169], v[208:211], v[12:15]
	v_mfma_f32_16x16x32_bf16 v[20:23], v[174:177], v[208:211], v[20:23]
	v_mfma_f32_16x16x32_bf16 v[52:55], v[170:173], v[188:191], v[52:55]
	v_mfma_f32_16x16x32_bf16 v[60:63], v[178:181], v[188:191], v[60:63]
	v_mfma_f32_16x16x32_bf16 v[28:31], v[170:173], v[196:199], v[28:31]
	v_mfma_f32_16x16x32_bf16 v[36:39], v[178:181], v[196:199], v[36:39]
	v_mfma_f32_16x16x32_bf16 v[40:43], v[170:173], v[204:207], v[40:43]
	v_mfma_f32_16x16x32_bf16 v[44:47], v[178:181], v[204:207], v[44:47]
	v_mfma_f32_16x16x32_bf16 v[12:15], v[170:173], v[212:215], v[12:15]
	v_mfma_f32_16x16x32_bf16 v[20:23], v[178:181], v[212:215], v[20:23]
	s_setprio 0
	s_barrier
; #define PG8_STAGE(bufoff, gbase, voff) do { _Pragma("unroll") for (int _i = 0; _i < 2; ++_i) \
;         __builtin_amdgcn_global_load_lds((const unsigned*)((const char*)(gbase) + (voff)[_i]), (PG8_LAS unsigned*)(lds + (bufoff) + ldsw + _i * 8192), 16, 0, 0); } while (0)
; #define PG8_LDA(dst, b, h) do { _Pragma("unroll") for (int m = 0; m < 4; ++m) _Pragma("unroll") for (int k = 0; k < 2; ++k) dst[m][k] = *(const PG8_LAS bf16x8*)(lds + PG8_SA(b, h) + aoff + m * 2048 + k * 1024); } while (0)
; #define PG8_LDB(dst, b, h) do { _Pragma("unroll") for (int n = 0; n < 2; ++n) _Pragma("unroll") for (int k = 0; k < 2; ++k) dst[n][k] = *(const PG8_LAS bf16x8*)(lds + PG8_SB(b, h) + boff + n * 2048 + k * 1024); } while (0)
; #define PG8_MMA(ai, bj, At, Bt) do { __builtin_amdgcn_s_setprio(1); _Pragma("unroll") for (int m = 0; m < 4; ++m) _Pragma("unroll") for (int n = 0; n < 2; ++n) _Pragma("unroll") for (int k = 0; k < 2; ++k) \
;         acc[ai][bj][m][n] = __builtin_amdgcn_mfma_f32_16x16x32_bf16(Bt[n][k], At[m][k], acc[ai][bj][m][n], 0, 0, 0); __builtin_amdgcn_s_setprio(0); } while (0)
; #define PG8_WAIT_V(n) asm volatile("s_waitcnt vmcnt(" #n ")" ::: "memory")
; #define PG8_WAIT_L(n) asm volatile("s_waitcnt lgkmcnt(" #n ")" ::: "memory")
; #define PG8_BAR __builtin_amdgcn_s_barrier()
; #define PG8_SCHED __builtin_amdgcn_sched_barrier(0)
; template <class Epi, class Sched, bool ALIGN_EPI = false, bool SP2 = false>
; __device__ __forceinline__ void gemm_phase(PG8_LAS unsigned char* lds, const Gemm g, const Sched S, const Epi E, const int tid) {
;     ...
;             PG8_LDB(B0, 1, 0); PG8_LDB(B1, 1, 1); PG8_SCHED; PG8_LDA(At, 1, 0); PG8_STAGE(PG8_SA(0, 1), a2 + hstepA, voffA);
;             PG8_WAIT_V(8); PG8_WAIT_L(0); PG8_BAR; PG8_MMA(0, 0, At, B0); PG8_MMA(0, 1, At, B1); PG8_BAR; PG8_SCHED;
;             PG8_LDA(At, 1, 1); PG8_STAGE(PG8_SB(1, 0), b3, voffB); PG8_STAGE(PG8_SB(1, 1), b3 + hstepB, voffB); PG8_STAGE(PG8_SA(1, 0), a3, voffA);
;             PG8_WAIT_V(8); PG8_WAIT_L(0); PG8_BAR; PG8_MMA(1, 0, At, B0); PG8_MMA(1, 1, At, B1); PG8_BAR; PG8_SCHED;
	s_add_i32 s76, 0, 0x18000
	s_add_i32 s77, 0, 0x1c000
	v_add_u32_e32 v162, s76, v149
	v_add_u32_e32 v178, s77, v149
	ds_read_b128 v[144:147], v162
	ds_read_b128 v[154:157], v162 offset:1024
	ds_read_b128 v[158:161], v162 offset:2048
	ds_read_b128 v[162:165], v162 offset:3072
	ds_read_b128 v[166:169], v178
	ds_read_b128 v[170:173], v178 offset:1024
	ds_read_b128 v[174:177], v178 offset:2048
	ds_read_b128 v[178:181], v178 offset:3072
	s_add_u32 s38, s46, 0xc0000
	s_addc_u32 s39, s47, 0
	s_mov_b32 m0, s58
	s_nop 0
	global_load_lds_dwordx4 v128, s[46:47]
	s_mov_b32 m0, s59
	s_nop 0
	global_load_lds_dwordx4 v132, s[46:47]
	s_mov_b32 m0, s60
	ds_read_b128 v[182:185], v153 offset:32768
	ds_read_b128 v[188:191], v153 offset:33792
	ds_read_b128 v[192:195], v153 offset:34816
	ds_read_b128 v[196:199], v153 offset:35840
	ds_read_b128 v[200:203], v153 offset:36864
	ds_read_b128 v[204:207], v153 offset:37888
	ds_read_b128 v[208:211], v153 offset:38912
	ds_read_b128 v[212:215], v153 offset:39936
	global_load_lds_dwordx4 v128, s[38:39]
	s_mov_b32 m0, s61
	s_nop 0
	global_load_lds_dwordx4 v132, s[38:39]
	s_waitcnt vmcnt(8)
	s_waitcnt lgkmcnt(0)
	s_barrier
	s_setprio 1
	s_waitcnt lgkmcnt(0)
	v_mfma_f32_16x16x32_bf16 v[112:115], v[144:147], v[182:185], v[112:115]
	v_mfma_f32_16x16x32_bf16 v[120:123], v[158:161], v[182:185], v[120:123]
	v_mfma_f32_16x16x32_bf16 v[96:99], v[144:147], v[192:195], v[96:99]
	v_mfma_f32_16x16x32_bf16 v[104:107], v[158:161], v[192:195], v[104:107]
	v_mfma_f32_16x16x32_bf16 v[80:83], v[144:147], v[200:203], v[80:83]
	v_mfma_f32_16x16x32_bf16 v[88:91], v[158:161], v[200:203], v[88:91]
	v_mfma_f32_16x16x32_bf16 v[64:67], v[144:147], v[208:211], v[64:67]
	v_mfma_f32_16x16x32_bf16 v[72:75], v[158:161], v[208:211], v[72:75]
	v_mfma_f32_16x16x32_bf16 v[112:115], v[154:157], v[188:191], v[112:115]
	v_mfma_f32_16x16x32_bf16 v[120:123], v[162:165], v[188:191], v[120:123]
	v_mfma_f32_16x16x32_bf16 v[96:99], v[154:157], v[196:199], v[96:99]
	v_mfma_f32_16x16x32_bf16 v[104:107], v[162:165], v[196:199], v[104:107]
	v_mfma_f32_16x16x32_bf16 v[80:83], v[154:157], v[204:207], v[80:83]
	v_mfma_f32_16x16x32_bf16 v[88:91], v[162:165], v[204:207], v[88:91]
	v_mfma_f32_16x16x32_bf16 v[64:67], v[154:157], v[212:215], v[64:67]
	v_mfma_f32_16x16x32_bf16 v[72:75], v[162:165], v[212:215], v[72:75]
	s_setprio 0
	s_setprio 1
	v_mfma_f32_16x16x32_bf16 v[116:119], v[166:169], v[182:185], v[116:119]
	v_mfma_f32_16x16x32_bf16 v[124:127], v[174:177], v[182:185], v[124:127]
	v_mfma_f32_16x16x32_bf16 v[100:103], v[166:169], v[192:195], v[100:103]
	v_mfma_f32_16x16x32_bf16 v[108:111], v[174:177], v[192:195], v[108:111]
	v_mfma_f32_16x16x32_bf16 v[84:87], v[166:169], v[200:203], v[84:87]
	v_mfma_f32_16x16x32_bf16 v[92:95], v[174:177], v[200:203], v[92:95]
	v_mfma_f32_16x16x32_bf16 v[68:71], v[166:169], v[208:211], v[68:71]
	v_mfma_f32_16x16x32_bf16 v[76:79], v[174:177], v[208:211], v[76:79]
	v_mfma_f32_16x16x32_bf16 v[116:119], v[170:173], v[188:191], v[116:119]
	v_mfma_f32_16x16x32_bf16 v[124:127], v[178:181], v[188:191], v[124:127]
	v_mfma_f32_16x16x32_bf16 v[100:103], v[170:173], v[196:199], v[100:103]
	v_mfma_f32_16x16x32_bf16 v[108:111], v[178:181], v[196:199], v[108:111]
	v_mfma_f32_16x16x32_bf16 v[84:87], v[170:173], v[204:207], v[84:87]
	v_mfma_f32_16x16x32_bf16 v[92:95], v[178:181], v[204:207], v[92:95]
	v_mfma_f32_16x16x32_bf16 v[68:71], v[170:173], v[212:215], v[68:71]
	v_mfma_f32_16x16x32_bf16 v[76:79], v[178:181], v[212:215], v[76:79]
	s_setprio 0
	s_barrier
	s_add_i32 s38, s76, s33
	s_mov_b32 m0, s38
	ds_read_b128 v[182:185], v153 offset:49152
	ds_read_b128 v[188:191], v153 offset:50176
	ds_read_b128 v[192:195], v153 offset:51200
	ds_read_b128 v[196:199], v153 offset:52224
	ds_read_b128 v[200:203], v153 offset:53248
	ds_read_b128 v[204:207], v153 offset:54272
	ds_read_b128 v[208:211], v153 offset:55296
	ds_read_b128 v[212:215], v153 offset:56320
	global_load_lds_dwordx4 v130, s[98:99]
	s_add_i32 m0, s38, 0x2000
	s_add_u32 s38, s40, 0x40080
	s_addc_u32 s39, s41, 0
	s_add_i32 s40, s77, s33
	global_load_lds_dwordx4 v134, s[98:99]
	s_mov_b32 m0, s40
	s_nop 0
	global_load_lds_dwordx4 v130, s[38:39]
	s_add_i32 m0, s40, 0x2000
	s_nop 0
	global_load_lds_dwordx4 v134, s[38:39]
	s_mov_b32 m0, s63
	s_nop 0
	global_load_lds_dwordx4 v128, s[100:101]
	s_mov_b32 m0, s64
	s_nop 0
	global_load_lds_dwordx4 v132, s[100:101]
	s_waitcnt vmcnt(8)
	s_waitcnt lgkmcnt(0)
	s_barrier
	s_setprio 1
	s_waitcnt lgkmcnt(0)
	v_mfma_f32_16x16x32_bf16 v[48:51], v[144:147], v[182:185], v[48:51]
	v_mfma_f32_16x16x32_bf16 v[56:59], v[158:161], v[182:185], v[56:59]
	v_mfma_f32_16x16x32_bf16 v[24:27], v[144:147], v[192:195], v[24:27]
	v_mfma_f32_16x16x32_bf16 v[32:35], v[158:161], v[192:195], v[32:35]
	v_mfma_f32_16x16x32_bf16 v[0:3], v[144:147], v[200:203], v[0:3]
	v_mfma_f32_16x16x32_bf16 v[4:7], v[158:161], v[200:203], v[4:7]
	v_mfma_f32_16x16x32_bf16 v[8:11], v[144:147], v[208:211], v[8:11]
	v_mfma_f32_16x16x32_bf16 v[16:19], v[158:161], v[208:211], v[16:19]
	v_mfma_f32_16x16x32_bf16 v[48:51], v[154:157], v[188:191], v[48:51]
	v_mfma_f32_16x16x32_bf16 v[56:59], v[162:165], v[188:191], v[56:59]
	v_mfma_f32_16x16x32_bf16 v[24:27], v[154:157], v[196:199], v[24:27]
	v_mfma_f32_16x16x32_bf16 v[32:35], v[162:165], v[196:199], v[32:35]
	v_mfma_f32_16x16x32_bf16 v[0:3], v[154:157], v[204:207], v[0:3]
	v_mfma_f32_16x16x32_bf16 v[4:7], v[162:165], v[204:207], v[4:7]
	v_mfma_f32_16x16x32_bf16 v[8:11], v[154:157], v[212:215], v[8:11]
	v_mfma_f32_16x16x32_bf16 v[16:19], v[162:165], v[212:215], v[16:19]
	s_setprio 0
	s_setprio 1
	v_mfma_f32_16x16x32_bf16 v[52:55], v[166:169], v[182:185], v[52:55]
	v_mfma_f32_16x16x32_bf16 v[60:63], v[174:177], v[182:185], v[60:63]
	v_mfma_f32_16x16x32_bf16 v[28:31], v[166:169], v[192:195], v[28:31]
	v_mfma_f32_16x16x32_bf16 v[36:39], v[174:177], v[192:195], v[36:39]
	v_mfma_f32_16x16x32_bf16 v[40:43], v[166:169], v[200:203], v[40:43]
	v_mfma_f32_16x16x32_bf16 v[44:47], v[174:177], v[200:203], v[44:47]
	v_mfma_f32_16x16x32_bf16 v[12:15], v[166:169], v[208:211], v[12:15]
	v_mfma_f32_16x16x32_bf16 v[20:23], v[174:177], v[208:211], v[20:23]
	v_mfma_f32_16x16x32_bf16 v[52:55], v[170:173], v[188:191], v[52:55]
	v_mfma_f32_16x16x32_bf16 v[60:63], v[178:181], v[188:191], v[60:63]
	v_mfma_f32_16x16x32_bf16 v[28:31], v[170:173], v[196:199], v[28:31]
	v_mfma_f32_16x16x32_bf16 v[36:39], v[178:181], v[196:199], v[36:39]
	v_mfma_f32_16x16x32_bf16 v[40:43], v[170:173], v[204:207], v[40:43]
	v_mfma_f32_16x16x32_bf16 v[44:47], v[178:181], v[204:207], v[44:47]
	v_mfma_f32_16x16x32_bf16 v[12:15], v[170:173], v[212:215], v[12:15]
	v_mfma_f32_16x16x32_bf16 v[20:23], v[178:181], v[212:215], v[20:23]
	s_setprio 0
	s_barrier
	s_add_i32 s75, s75, 2
	s_add_u32 s73, s73, 0x100
	s_addc_u32 s74, s74, 0
	s_cmp_gt_u32 s75, 13
	s_mov_b64 s[38:39], s[6:7]
	s_cbranch_scc0 .LBB0_672
	s_and_b64 vcc, exec, s[24:25]
	s_cbranch_vccz .LBB0_675
	s_barrier

; #define PG8_STAGE(bufoff, gbase, voff) do { _Pragma("unroll") for (int _i = 0; _i < 2; ++_i) \
;         __builtin_amdgcn_global_load_lds((const unsigned*)((const char*)(gbase) + (voff)[_i]), (PG8_LAS unsigned*)(lds + (bufoff) + ldsw + _i * 8192), 16, 0, 0); } while (0)
; #define PG8_LDA(dst, b, h) do { _Pragma("unroll") for (int m = 0; m < 4; ++m) _Pragma("unroll") for (int k = 0; k < 2; ++k) dst[m][k] = *(const PG8_LAS bf16x8*)(lds + PG8_SA(b, h) + aoff + m * 2048 + k * 1024); } while (0)
; #define PG8_LDB(dst, b, h) do { _Pragma("unroll") for (int n = 0; n < 2; ++n) _Pragma("unroll") for (int k = 0; k < 2; ++k) dst[n][k] = *(const PG8_LAS bf16x8*)(lds + PG8_SB(b, h) + boff + n * 2048 + k * 1024); } while (0)
; #define PG8_MMA(ai, bj, At, Bt) do { __builtin_amdgcn_s_setprio(1); _Pragma("unroll") for (int m = 0; m < 4; ++m) _Pragma("unroll") for (int n = 0; n < 2; ++n) _Pragma("unroll") for (int k = 0; k < 2; ++k) \
;         acc[ai][bj][m][n] = __builtin_amdgcn_mfma_f32_16x16x32_bf16(Bt[n][k], At[m][k], acc[ai][bj][m][n], 0, 0, 0); __builtin_amdgcn_s_setprio(0); } while (0)
; #define PG8_WAIT_V(n) asm volatile("s_waitcnt vmcnt(" #n ")" ::: "memory")
; #define PG8_WAIT_L(n) asm volatile("s_waitcnt lgkmcnt(" #n ")" ::: "memory")
; template <class Epi, class Sched, bool ALIGN_EPI = false, bool SP2 = false>
; __device__ __forceinline__ void gemm_phase(PG8_LAS unsigned char* lds, const Gemm g, const Sched S, const Epi E, const int tid) {
;     ...
;             const bool last = (t == nt - 2);
;             const char* a1 = cA + (size_t)(t + 1) * kstep;
;             const char* a2 = last ? nA : cA + (size_t)(t + 2) * kstep; const char* b2 = last ? nB : cB + (size_t)(t + 2) * kstep;
;             const char* a3 = a2 + kstep; const char* b3 = b2 + kstep;
;             if (last && has_next) S.a_ready(nxt);
;             if constexpr (SP2) {
;             PG8_LDB(B0, 0, 0); PG8_LDB(B1, 0, 1); PG8_SCHED; PG8_LDA(At, 0, 0); PG8_STAGE(PG8_SA(1, 1), a1 + hstepA, voffA);
;             PG8_WAIT_V(8); PG8_WAIT_L(0); PG8_BAR; PG8_MMA(0, 0, At, B0); PG8_MMA(0, 1, At, B1); PG8_BAR; PG8_SCHED;
;             PG8_LDA(At, 0, 1); PG8_STAGE(PG8_SB(0, 0), b2, voffB); PG8_STAGE(PG8_SB(0, 1), b2 + hstepB, voffB); PG8_STAGE(PG8_SA(0, 0), a2, voffA);
;             PG8_WAIT_V(8); PG8_WAIT_L(0); PG8_BAR; PG8_MMA(1, 0, At, B0); PG8_MMA(1, 1, At, B1); PG8_BAR; PG8_SCHED;
.LBB0_757:
	ds_read_b128 v[128:131], v206
	ds_read_b128 v[132:135], v206 offset:1024
	ds_read_b128 v[136:139], v206 offset:2048
	ds_read_b128 v[156:159], v206 offset:3072
	ds_read_b128 v[160:163], v207
	ds_read_b128 v[164:167], v207 offset:1024
	ds_read_b128 v[168:171], v207 offset:2048
	ds_read_b128 v[172:175], v207 offset:3072
	s_add_u32 s38, s36, 0xfffc0080
	s_addc_u32 s39, s37, -1
	s_cmp_eq_u32 s61, 12
	s_cselect_b32 s41, s5, s39
	s_cselect_b32 s40, s29, s38
	s_cselect_b32 s39, s27, s60
	s_cselect_b32 s38, s58, s59
	s_add_i32 m0, s47, 0xc000
	ds_read_b128 v[210:213], v208
	ds_read_b128 v[214:217], v208 offset:1024
	ds_read_b128 v[218:221], v208 offset:2048
	ds_read_b128 v[222:225], v208 offset:3072
	ds_read_b128 v[226:229], v208 offset:4096
	ds_read_b128 v[230:233], v208 offset:5120
	ds_read_b128 v[234:237], v208 offset:6144
	ds_read_b128 v[238:241], v208 offset:7168
	global_load_lds_dwordx4 v148, s[36:37]
	s_add_i32 m0, s47, 0xe000
	s_nop 0
	global_load_lds_dwordx4 v150, s[36:37]
	s_waitcnt vmcnt(8)
	s_waitcnt lgkmcnt(0)
	s_barrier
	s_setprio 1
	s_waitcnt lgkmcnt(0)
	v_mfma_f32_16x16x32_bf16 v[124:127], v[128:131], v[210:213], v[124:127]
	v_mfma_f32_16x16x32_bf16 v[120:123], v[136:139], v[210:213], v[120:123]
	v_mfma_f32_16x16x32_bf16 v[112:115], v[128:131], v[218:221], v[112:115]
	v_mfma_f32_16x16x32_bf16 v[104:107], v[136:139], v[218:221], v[104:107]
	v_mfma_f32_16x16x32_bf16 v[96:99], v[128:131], v[226:229], v[96:99]
	v_mfma_f32_16x16x32_bf16 v[88:91], v[136:139], v[226:229], v[88:91]
	v_mfma_f32_16x16x32_bf16 v[80:83], v[128:131], v[234:237], v[80:83]
	v_mfma_f32_16x16x32_bf16 v[72:75], v[136:139], v[234:237], v[72:75]
	v_mfma_f32_16x16x32_bf16 v[124:127], v[132:135], v[214:217], v[124:127]
	v_mfma_f32_16x16x32_bf16 v[120:123], v[156:159], v[214:217], v[120:123]
	v_mfma_f32_16x16x32_bf16 v[112:115], v[132:135], v[222:225], v[112:115]
	v_mfma_f32_16x16x32_bf16 v[104:107], v[156:159], v[222:225], v[104:107]
	v_mfma_f32_16x16x32_bf16 v[96:99], v[132:135], v[230:233], v[96:99]
	v_mfma_f32_16x16x32_bf16 v[88:91], v[156:159], v[230:233], v[88:91]
	v_mfma_f32_16x16x32_bf16 v[80:83], v[132:135], v[238:241], v[80:83]
	v_mfma_f32_16x16x32_bf16 v[72:75], v[156:159], v[238:241], v[72:75]
	s_setprio 0
	s_setprio 1
	v_mfma_f32_16x16x32_bf16 v[116:119], v[160:163], v[210:213], v[116:119]
	v_mfma_f32_16x16x32_bf16 v[108:111], v[168:171], v[210:213], v[108:111]
	v_mfma_f32_16x16x32_bf16 v[100:103], v[160:163], v[218:221], v[100:103]
	v_mfma_f32_16x16x32_bf16 v[92:95], v[168:171], v[218:221], v[92:95]
	v_mfma_f32_16x16x32_bf16 v[84:87], v[160:163], v[226:229], v[84:87]
	v_mfma_f32_16x16x32_bf16 v[76:79], v[168:171], v[226:229], v[76:79]
	v_mfma_f32_16x16x32_bf16 v[68:71], v[160:163], v[234:237], v[68:71]
	v_mfma_f32_16x16x32_bf16 v[64:67], v[168:171], v[234:237], v[64:67]
	v_mfma_f32_16x16x32_bf16 v[116:119], v[164:167], v[214:217], v[116:119]
	v_mfma_f32_16x16x32_bf16 v[108:111], v[172:175], v[214:217], v[108:111]
	v_mfma_f32_16x16x32_bf16 v[100:103], v[164:167], v[222:225], v[100:103]
	v_mfma_f32_16x16x32_bf16 v[92:95], v[172:175], v[222:225], v[92:95]
	v_mfma_f32_16x16x32_bf16 v[84:87], v[164:167], v[230:233], v[84:87]
	v_mfma_f32_16x16x32_bf16 v[76:79], v[172:175], v[230:233], v[76:79]
	v_mfma_f32_16x16x32_bf16 v[68:71], v[164:167], v[238:241], v[68:71]
	v_mfma_f32_16x16x32_bf16 v[64:67], v[172:175], v[238:241], v[64:67]
	s_setprio 0
	s_barrier
	s_add_u32 s98, s38, 0x80
	s_addc_u32 s99, s39, 0
	s_add_u32 s100, s40, 0x80
	s_addc_u32 s101, s41, 0
	s_add_i32 s62, s55, s46
	s_mov_b32 m0, s62
	ds_read_b128 v[210:213], v208 offset:16384
	ds_read_b128 v[214:217], v208 offset:17408
	ds_read_b128 v[218:221], v208 offset:18432
	ds_read_b128 v[222:225], v208 offset:19456
	ds_read_b128 v[226:229], v208 offset:20480
	ds_read_b128 v[230:233], v208 offset:21504
	ds_read_b128 v[234:237], v208 offset:22528
	ds_read_b128 v[238:241], v208 offset:23552
	global_load_lds_dwordx4 v142, s[38:39]
	s_add_i32 m0, s62, 0x2000
	s_add_u32 s62, s38, 0x40000
	s_addc_u32 s63, s39, 0
	s_add_i32 s64, s56, s46
	global_load_lds_dwordx4 v146, s[38:39]
	s_mov_b32 m0, s64
	s_nop 0
	global_load_lds_dwordx4 v142, s[62:63]
	s_add_i32 m0, s64, 0x2000
	s_nop 0
	global_load_lds_dwordx4 v146, s[62:63]
	s_waitcnt vmcnt(6)
	s_waitcnt lgkmcnt(0)
	s_barrier
	s_setprio 1
	s_waitcnt lgkmcnt(0)
	v_mfma_f32_16x16x32_bf16 v[60:63], v[128:131], v[210:213], v[60:63]
	v_mfma_f32_16x16x32_bf16 v[56:59], v[136:139], v[210:213], v[56:59]
	v_mfma_f32_16x16x32_bf16 v[48:51], v[128:131], v[218:221], v[48:51]
	v_mfma_f32_16x16x32_bf16 v[40:43], v[136:139], v[218:221], v[40:43]
	v_mfma_f32_16x16x32_bf16 v[32:35], v[128:131], v[226:229], v[32:35]
	v_mfma_f32_16x16x32_bf16 v[24:27], v[136:139], v[226:229], v[24:27]
	v_mfma_f32_16x16x32_bf16 v[16:19], v[128:131], v[234:237], v[16:19]
	v_mfma_f32_16x16x32_bf16 v[8:11], v[136:139], v[234:237], v[8:11]
	v_mfma_f32_16x16x32_bf16 v[60:63], v[132:135], v[214:217], v[60:63]
	v_mfma_f32_16x16x32_bf16 v[56:59], v[156:159], v[214:217], v[56:59]
	v_mfma_f32_16x16x32_bf16 v[48:51], v[132:135], v[222:225], v[48:51]
	v_mfma_f32_16x16x32_bf16 v[40:43], v[156:159], v[222:225], v[40:43]
	v_mfma_f32_16x16x32_bf16 v[32:35], v[132:135], v[230:233], v[32:35]
	v_mfma_f32_16x16x32_bf16 v[24:27], v[156:159], v[230:233], v[24:27]
	v_mfma_f32_16x16x32_bf16 v[16:19], v[132:135], v[238:241], v[16:19]
	v_mfma_f32_16x16x32_bf16 v[8:11], v[156:159], v[238:241], v[8:11]
	s_setprio 0
	s_setprio 1
	v_mfma_f32_16x16x32_bf16 v[52:55], v[160:163], v[210:213], v[52:55]
	v_mfma_f32_16x16x32_bf16 v[44:47], v[168:171], v[210:213], v[44:47]
	v_mfma_f32_16x16x32_bf16 v[36:39], v[160:163], v[218:221], v[36:39]
	v_mfma_f32_16x16x32_bf16 v[28:31], v[168:171], v[218:221], v[28:31]
	v_mfma_f32_16x16x32_bf16 v[20:23], v[160:163], v[226:229], v[20:23]
	v_mfma_f32_16x16x32_bf16 v[12:15], v[168:171], v[226:229], v[12:15]
	v_mfma_f32_16x16x32_bf16 v[4:7], v[160:163], v[234:237], v[4:7]
	v_mfma_f32_16x16x32_bf16 v[0:3], v[168:171], v[234:237], v[0:3]
	v_mfma_f32_16x16x32_bf16 v[52:55], v[164:167], v[214:217], v[52:55]
	v_mfma_f32_16x16x32_bf16 v[44:47], v[172:175], v[214:217], v[44:47]
	v_mfma_f32_16x16x32_bf16 v[36:39], v[164:167], v[222:225], v[36:39]
	v_mfma_f32_16x16x32_bf16 v[28:31], v[172:175], v[222:225], v[28:31]
	v_mfma_f32_16x16x32_bf16 v[20:23], v[164:167], v[230:233], v[20:23]
	v_mfma_f32_16x16x32_bf16 v[12:15], v[172:175], v[230:233], v[12:15]
	v_mfma_f32_16x16x32_bf16 v[4:7], v[164:167], v[238:241], v[4:7]
	v_mfma_f32_16x16x32_bf16 v[0:3], v[172:175], v[238:241], v[0:3]
	s_setprio 0
	s_barrier
; #define PG8_STAGE(bufoff, gbase, voff) do { _Pragma("unroll") for (int _i = 0; _i < 2; ++_i) \
;         __builtin_amdgcn_global_load_lds((const unsigned*)((const char*)(gbase) + (voff)[_i]), (PG8_LAS unsigned*)(lds + (bufoff) + ldsw + _i * 8192), 16, 0, 0); } while (0)
; #define PG8_LDA(dst, b, h) do { _Pragma("unroll") for (int m = 0; m < 4; ++m) _Pragma("unroll") for (int k = 0; k < 2; ++k) dst[m][k] = *(const PG8_LAS bf16x8*)(lds + PG8_SA(b, h) + aoff + m * 2048 + k * 1024); } while (0)
; #define PG8_LDB(dst, b, h) do { _Pragma("unroll") for (int n = 0; n < 2; ++n) _Pragma("unroll") for (int k = 0; k < 2; ++k) dst[n][k] = *(const PG8_LAS bf16x8*)(lds + PG8_SB(b, h) + boff + n * 2048 + k * 1024); } while (0)
; #define PG8_MMA(ai, bj, At, Bt) do { __builtin_amdgcn_s_setprio(1); _Pragma("unroll") for (int m = 0; m < 4; ++m) _Pragma("unroll") for (int n = 0; n < 2; ++n) _Pragma("unroll") for (int k = 0; k < 2; ++k) \
;         acc[ai][bj][m][n] = __builtin_amdgcn_mfma_f32_16x16x32_bf16(Bt[n][k], At[m][k], acc[ai][bj][m][n], 0, 0, 0); __builtin_amdgcn_s_setprio(0); } while (0)
; #define PG8_WAIT_V(n) asm volatile("s_waitcnt vmcnt(" #n ")" ::: "memory")
; #define PG8_WAIT_L(n) asm volatile("s_waitcnt lgkmcnt(" #n ")" ::: "memory")
; #define PG8_BAR __builtin_amdgcn_s_barrier()
; #define PG8_SCHED __builtin_amdgcn_sched_barrier(0)
; template <class Epi, class Sched, bool ALIGN_EPI = false, bool SP2 = false>
; __device__ __forceinline__ void gemm_phase(PG8_LAS unsigned char* lds, const Gemm g, const Sched S, const Epi E, const int tid) {
;     ...
;             PG8_LDB(B0, 1, 0); PG8_LDB(B1, 1, 1); PG8_SCHED; PG8_LDA(At, 1, 0); PG8_STAGE(PG8_SA(0, 1), a2 + hstepA, voffA);
;             PG8_WAIT_V(8); PG8_WAIT_L(0); PG8_BAR; PG8_MMA(0, 0, At, B0); PG8_MMA(0, 1, At, B1); PG8_BAR; PG8_SCHED;
;             PG8_LDA(At, 1, 1); PG8_STAGE(PG8_SB(1, 0), b3, voffB); PG8_STAGE(PG8_SB(1, 1), b3 + hstepB, voffB); PG8_STAGE(PG8_SA(1, 0), a3, voffA);
;             PG8_WAIT_V(8); PG8_WAIT_L(0); PG8_BAR; PG8_MMA(1, 0, At, B0); PG8_MMA(1, 1, At, B1); PG8_BAR; PG8_SCHED;
	s_add_i32 s62, 0, 0x18000
	s_add_i32 s63, 0, 0x1c000
	v_add_u32_e32 v156, s62, v204
	v_add_u32_e32 v172, s63, v204
	ds_read_b128 v[128:131], v156
	ds_read_b128 v[132:135], v156 offset:1024
	ds_read_b128 v[136:139], v156 offset:2048
	ds_read_b128 v[156:159], v156 offset:3072
	ds_read_b128 v[160:163], v172
	ds_read_b128 v[164:167], v172 offset:1024
	ds_read_b128 v[168:171], v172 offset:2048
	ds_read_b128 v[172:175], v172 offset:3072
	s_mov_b32 m0, s47
	s_nop 0
	global_load_lds_dwordx4 v140, s[40:41]
	s_mov_b32 m0, s48
	s_nop 0
	global_load_lds_dwordx4 v144, s[40:41]
	s_add_u32 s40, s40, 0x40000
	s_addc_u32 s41, s41, 0
	s_mov_b32 m0, s49
	ds_read_b128 v[210:213], v208 offset:32768
	ds_read_b128 v[214:217], v208 offset:33792
	ds_read_b128 v[218:221], v208 offset:34816
	ds_read_b128 v[222:225], v208 offset:35840
	ds_read_b128 v[226:229], v208 offset:36864
	ds_read_b128 v[230:233], v208 offset:37888
	ds_read_b128 v[234:237], v208 offset:38912
	ds_read_b128 v[238:241], v208 offset:39936
	global_load_lds_dwordx4 v140, s[40:41]
	s_mov_b32 m0, s50
	s_nop 0
	global_load_lds_dwordx4 v144, s[40:41]
	s_waitcnt vmcnt(8)
	s_waitcnt lgkmcnt(0)
	s_barrier
	s_setprio 1
	s_waitcnt lgkmcnt(0)
	v_mfma_f32_16x16x32_bf16 v[124:127], v[128:131], v[210:213], v[124:127]
	v_mfma_f32_16x16x32_bf16 v[120:123], v[136:139], v[210:213], v[120:123]
	v_mfma_f32_16x16x32_bf16 v[112:115], v[128:131], v[218:221], v[112:115]
	v_mfma_f32_16x16x32_bf16 v[104:107], v[136:139], v[218:221], v[104:107]
	v_mfma_f32_16x16x32_bf16 v[96:99], v[128:131], v[226:229], v[96:99]
	v_mfma_f32_16x16x32_bf16 v[88:91], v[136:139], v[226:229], v[88:91]
	v_mfma_f32_16x16x32_bf16 v[80:83], v[128:131], v[234:237], v[80:83]
	v_mfma_f32_16x16x32_bf16 v[72:75], v[136:139], v[234:237], v[72:75]
	v_mfma_f32_16x16x32_bf16 v[124:127], v[132:135], v[214:217], v[124:127]
	v_mfma_f32_16x16x32_bf16 v[120:123], v[156:159], v[214:217], v[120:123]
	v_mfma_f32_16x16x32_bf16 v[112:115], v[132:135], v[222:225], v[112:115]
	v_mfma_f32_16x16x32_bf16 v[104:107], v[156:159], v[222:225], v[104:107]
	v_mfma_f32_16x16x32_bf16 v[96:99], v[132:135], v[230:233], v[96:99]
	v_mfma_f32_16x16x32_bf16 v[88:91], v[156:159], v[230:233], v[88:91]
	v_mfma_f32_16x16x32_bf16 v[80:83], v[132:135], v[238:241], v[80:83]
	v_mfma_f32_16x16x32_bf16 v[72:75], v[156:159], v[238:241], v[72:75]
	s_setprio 0
	s_setprio 1
	v_mfma_f32_16x16x32_bf16 v[116:119], v[160:163], v[210:213], v[116:119]
	v_mfma_f32_16x16x32_bf16 v[108:111], v[168:171], v[210:213], v[108:111]
	v_mfma_f32_16x16x32_bf16 v[100:103], v[160:163], v[218:221], v[100:103]
	v_mfma_f32_16x16x32_bf16 v[92:95], v[168:171], v[218:221], v[92:95]
	v_mfma_f32_16x16x32_bf16 v[84:87], v[160:163], v[226:229], v[84:87]
	v_mfma_f32_16x16x32_bf16 v[76:79], v[168:171], v[226:229], v[76:79]
	v_mfma_f32_16x16x32_bf16 v[68:71], v[160:163], v[234:237], v[68:71]
	v_mfma_f32_16x16x32_bf16 v[64:67], v[168:171], v[234:237], v[64:67]
	v_mfma_f32_16x16x32_bf16 v[116:119], v[164:167], v[214:217], v[116:119]
	v_mfma_f32_16x16x32_bf16 v[108:111], v[172:175], v[214:217], v[108:111]
	v_mfma_f32_16x16x32_bf16 v[100:103], v[164:167], v[222:225], v[100:103]
	v_mfma_f32_16x16x32_bf16 v[92:95], v[172:175], v[222:225], v[92:95]
	v_mfma_f32_16x16x32_bf16 v[84:87], v[164:167], v[230:233], v[84:87]
	v_mfma_f32_16x16x32_bf16 v[76:79], v[172:175], v[230:233], v[76:79]
	v_mfma_f32_16x16x32_bf16 v[68:71], v[164:167], v[238:241], v[68:71]
	v_mfma_f32_16x16x32_bf16 v[64:67], v[172:175], v[238:241], v[64:67]
	s_setprio 0
	s_barrier
	s_add_i32 s40, s62, s46
	s_mov_b32 m0, s40
	ds_read_b128 v[210:213], v208 offset:49152
	ds_read_b128 v[214:217], v208 offset:50176
	ds_read_b128 v[218:221], v208 offset:51200
	ds_read_b128 v[222:225], v208 offset:52224
	ds_read_b128 v[226:229], v208 offset:53248
	ds_read_b128 v[230:233], v208 offset:54272
	ds_read_b128 v[234:237], v208 offset:55296
	ds_read_b128 v[238:241], v208 offset:56320
	global_load_lds_dwordx4 v142, s[98:99]
	s_add_i32 m0, s40, 0x2000
	s_add_u32 s38, s38, 0x40080
	s_addc_u32 s39, s39, 0
	s_add_i32 s40, s63, s46
	global_load_lds_dwordx4 v146, s[98:99]
	s_mov_b32 m0, s40
	s_nop 0
	global_load_lds_dwordx4 v142, s[38:39]
	s_add_i32 m0, s40, 0x2000
	s_nop 0
	global_load_lds_dwordx4 v146, s[38:39]
	s_mov_b32 m0, s52
	s_nop 0
	global_load_lds_dwordx4 v140, s[100:101]
	s_mov_b32 m0, s53
	s_nop 0
	global_load_lds_dwordx4 v144, s[100:101]
	s_waitcnt vmcnt(8)
	s_waitcnt lgkmcnt(0)
	s_barrier
	s_setprio 1
	s_waitcnt lgkmcnt(0)
	v_mfma_f32_16x16x32_bf16 v[60:63], v[128:131], v[210:213], v[60:63]
	v_mfma_f32_16x16x32_bf16 v[56:59], v[136:139], v[210:213], v[56:59]
	v_mfma_f32_16x16x32_bf16 v[48:51], v[128:131], v[218:221], v[48:51]
	v_mfma_f32_16x16x32_bf16 v[40:43], v[136:139], v[218:221], v[40:43]
	v_mfma_f32_16x16x32_bf16 v[32:35], v[128:131], v[226:229], v[32:35]
	v_mfma_f32_16x16x32_bf16 v[24:27], v[136:139], v[226:229], v[24:27]
	v_mfma_f32_16x16x32_bf16 v[16:19], v[128:131], v[234:237], v[16:19]
	v_mfma_f32_16x16x32_bf16 v[8:11], v[136:139], v[234:237], v[8:11]
	v_mfma_f32_16x16x32_bf16 v[60:63], v[132:135], v[214:217], v[60:63]
	v_mfma_f32_16x16x32_bf16 v[56:59], v[156:159], v[214:217], v[56:59]
	v_mfma_f32_16x16x32_bf16 v[48:51], v[132:135], v[222:225], v[48:51]
	v_mfma_f32_16x16x32_bf16 v[40:43], v[156:159], v[222:225], v[40:43]
	v_mfma_f32_16x16x32_bf16 v[32:35], v[132:135], v[230:233], v[32:35]
	v_mfma_f32_16x16x32_bf16 v[24:27], v[156:159], v[230:233], v[24:27]
	v_mfma_f32_16x16x32_bf16 v[16:19], v[132:135], v[238:241], v[16:19]
	v_mfma_f32_16x16x32_bf16 v[8:11], v[156:159], v[238:241], v[8:11]
	s_setprio 0
	s_setprio 1
	v_mfma_f32_16x16x32_bf16 v[52:55], v[160:163], v[210:213], v[52:55]
	v_mfma_f32_16x16x32_bf16 v[44:47], v[168:171], v[210:213], v[44:47]
	v_mfma_f32_16x16x32_bf16 v[36:39], v[160:163], v[218:221], v[36:39]
	v_mfma_f32_16x16x32_bf16 v[28:31], v[168:171], v[218:221], v[28:31]
	v_mfma_f32_16x16x32_bf16 v[20:23], v[160:163], v[226:229], v[20:23]
	v_mfma_f32_16x16x32_bf16 v[12:15], v[168:171], v[226:229], v[12:15]
	v_mfma_f32_16x16x32_bf16 v[4:7], v[160:163], v[234:237], v[4:7]
	v_mfma_f32_16x16x32_bf16 v[0:3], v[168:171], v[234:237], v[0:3]
	v_mfma_f32_16x16x32_bf16 v[52:55], v[164:167], v[214:217], v[52:55]
	v_mfma_f32_16x16x32_bf16 v[44:47], v[172:175], v[214:217], v[44:47]
	v_mfma_f32_16x16x32_bf16 v[36:39], v[164:167], v[222:225], v[36:39]
	v_mfma_f32_16x16x32_bf16 v[28:31], v[172:175], v[222:225], v[28:31]
	v_mfma_f32_16x16x32_bf16 v[20:23], v[164:167], v[230:233], v[20:23]
	v_mfma_f32_16x16x32_bf16 v[12:15], v[172:175], v[230:233], v[12:15]
	v_mfma_f32_16x16x32_bf16 v[4:7], v[164:167], v[238:241], v[4:7]
	v_mfma_f32_16x16x32_bf16 v[0:3], v[172:175], v[238:241], v[0:3]
	s_setprio 0
	s_barrier
	s_add_i32 s61, s61, 2
	s_add_u32 s36, s36, 0x100
	s_addc_u32 s37, s37, 0
	s_add_u32 s59, s59, 0x100
	s_addc_u32 s60, s60, 0
	s_cmp_gt_u32 s61, 13
	s_cbranch_scc0 .LBB0_757
	s_and_b64 vcc, exec, s[20:21]
	s_cbranch_vccz .LBB0_760
	s_barrier

; #define PG8_STAGE(bufoff, gbase, voff) do { _Pragma("unroll") for (int _i = 0; _i < 2; ++_i) \
;         __builtin_amdgcn_global_load_lds((const unsigned*)((const char*)(gbase) + (voff)[_i]), (PG8_LAS unsigned*)(lds + (bufoff) + ldsw + _i * 8192), 16, 0, 0); } while (0)
; #define PG8_LDA(dst, b, h) do { _Pragma("unroll") for (int m = 0; m < 4; ++m) _Pragma("unroll") for (int k = 0; k < 2; ++k) dst[m][k] = *(const PG8_LAS bf16x8*)(lds + PG8_SA(b, h) + aoff + m * 2048 + k * 1024); } while (0)
; #define PG8_LDB(dst, b, h) do { _Pragma("unroll") for (int n = 0; n < 2; ++n) _Pragma("unroll") for (int k = 0; k < 2; ++k) dst[n][k] = *(const PG8_LAS bf16x8*)(lds + PG8_SB(b, h) + boff + n * 2048 + k * 1024); } while (0)
; #define PG8_MMA(ai, bj, At, Bt) do { __builtin_amdgcn_s_setprio(1); _Pragma("unroll") for (int m = 0; m < 4; ++m) _Pragma("unroll") for (int n = 0; n < 2; ++n) _Pragma("unroll") for (int k = 0; k < 2; ++k) \
;         acc[ai][bj][m][n] = __builtin_amdgcn_mfma_f32_16x16x32_bf16(Bt[n][k], At[m][k], acc[ai][bj][m][n], 0, 0, 0); __builtin_amdgcn_s_setprio(0); } while (0)
; #define PG8_WAIT_V(n) asm volatile("s_waitcnt vmcnt(" #n ")" ::: "memory")
; #define PG8_WAIT_L(n) asm volatile("s_waitcnt lgkmcnt(" #n ")" ::: "memory")
; template <class Epi, class Sched, bool ALIGN_EPI = false, bool SP2 = false>
; __device__ __forceinline__ void gemm_phase(PG8_LAS unsigned char* lds, const Gemm g, const Sched S, const Epi E, const int tid) {
;     ...
;             const bool last = (t == nt - 2);
;             const char* a1 = cA + (size_t)(t + 1) * kstep;
;             const char* a2 = last ? nA : cA + (size_t)(t + 2) * kstep; const char* b2 = last ? nB : cB + (size_t)(t + 2) * kstep;
;             const char* a3 = a2 + kstep; const char* b3 = b2 + kstep;
;             if (last && has_next) S.a_ready(nxt);
;             if constexpr (SP2) {
;             PG8_LDB(B0, 0, 0); PG8_LDB(B1, 0, 1); PG8_SCHED; PG8_LDA(At, 0, 0); PG8_STAGE(PG8_SA(1, 1), a1 + hstepA, voffA);
;             PG8_WAIT_V(8); PG8_WAIT_L(0); PG8_BAR; PG8_MMA(0, 0, At, B0); PG8_MMA(0, 1, At, B1); PG8_BAR; PG8_SCHED;
;             PG8_LDA(At, 0, 1); PG8_STAGE(PG8_SB(0, 0), b2, voffB); PG8_STAGE(PG8_SB(0, 1), b2 + hstepB, voffB); PG8_STAGE(PG8_SA(0, 0), a2, voffA);
;             PG8_WAIT_V(8); PG8_WAIT_L(0); PG8_BAR; PG8_MMA(1, 0, At, B0); PG8_MMA(1, 1, At, B1); PG8_BAR; PG8_SCHED;
.LBB0_886:
	v_add_u32_e32 v162, s66, v149
	v_add_u32_e32 v178, s67, v149
	ds_read_b128 v[136:139], v162
	ds_read_b128 v[154:157], v162 offset:1024
	ds_read_b128 v[158:161], v162 offset:2048
	ds_read_b128 v[162:165], v162 offset:3072
	ds_read_b128 v[166:169], v178
	ds_read_b128 v[170:173], v178 offset:1024
	ds_read_b128 v[174:177], v178 offset:2048
	ds_read_b128 v[178:181], v178 offset:3072
	s_add_u32 s46, s48, 0xfffc0080
	s_addc_u32 s47, s49, -1
	s_cmp_eq_u32 s75, 12
	s_cselect_b32 s51, s31, s47
	s_cselect_b32 s50, s39, s46
	s_cselect_b32 s47, s29, s74
	s_cselect_b32 s46, s41, s69
	s_add_i32 m0, s56, 0xc000
	ds_read_b128 v[182:185], v153
	ds_read_b128 v[188:191], v153 offset:1024
	ds_read_b128 v[192:195], v153 offset:2048
	ds_read_b128 v[196:199], v153 offset:3072
	ds_read_b128 v[200:203], v153 offset:4096
	ds_read_b128 v[204:207], v153 offset:5120
	ds_read_b128 v[208:211], v153 offset:6144
	ds_read_b128 v[212:215], v153 offset:7168
	global_load_lds_dwordx4 v128, s[48:49]
	s_add_i32 m0, s56, 0xe000
	s_nop 0
	global_load_lds_dwordx4 v130, s[48:49]
	s_waitcnt vmcnt(8)
	s_waitcnt lgkmcnt(0)
	s_barrier
	s_setprio 1
	s_waitcnt lgkmcnt(0)
	v_mfma_f32_16x16x32_bf16 v[112:115], v[136:139], v[182:185], v[112:115]
	v_mfma_f32_16x16x32_bf16 v[120:123], v[158:161], v[182:185], v[120:123]
	v_mfma_f32_16x16x32_bf16 v[96:99], v[136:139], v[192:195], v[96:99]
	v_mfma_f32_16x16x32_bf16 v[104:107], v[158:161], v[192:195], v[104:107]
	v_mfma_f32_16x16x32_bf16 v[80:83], v[136:139], v[200:203], v[80:83]
	v_mfma_f32_16x16x32_bf16 v[88:91], v[158:161], v[200:203], v[88:91]
	v_mfma_f32_16x16x32_bf16 v[64:67], v[136:139], v[208:211], v[64:67]
	v_mfma_f32_16x16x32_bf16 v[72:75], v[158:161], v[208:211], v[72:75]
	v_mfma_f32_16x16x32_bf16 v[112:115], v[154:157], v[188:191], v[112:115]
	v_mfma_f32_16x16x32_bf16 v[120:123], v[162:165], v[188:191], v[120:123]
	v_mfma_f32_16x16x32_bf16 v[96:99], v[154:157], v[196:199], v[96:99]
	v_mfma_f32_16x16x32_bf16 v[104:107], v[162:165], v[196:199], v[104:107]
	v_mfma_f32_16x16x32_bf16 v[80:83], v[154:157], v[204:207], v[80:83]
	v_mfma_f32_16x16x32_bf16 v[88:91], v[162:165], v[204:207], v[88:91]
	v_mfma_f32_16x16x32_bf16 v[64:67], v[154:157], v[212:215], v[64:67]
	v_mfma_f32_16x16x32_bf16 v[72:75], v[162:165], v[212:215], v[72:75]
	s_setprio 0
	s_setprio 1
	v_mfma_f32_16x16x32_bf16 v[116:119], v[166:169], v[182:185], v[116:119]
	v_mfma_f32_16x16x32_bf16 v[124:127], v[174:177], v[182:185], v[124:127]
	v_mfma_f32_16x16x32_bf16 v[100:103], v[166:169], v[192:195], v[100:103]
	v_mfma_f32_16x16x32_bf16 v[108:111], v[174:177], v[192:195], v[108:111]
	v_mfma_f32_16x16x32_bf16 v[84:87], v[166:169], v[200:203], v[84:87]
	v_mfma_f32_16x16x32_bf16 v[92:95], v[174:177], v[200:203], v[92:95]
	v_mfma_f32_16x16x32_bf16 v[68:71], v[166:169], v[208:211], v[68:71]
	v_mfma_f32_16x16x32_bf16 v[76:79], v[174:177], v[208:211], v[76:79]
	v_mfma_f32_16x16x32_bf16 v[116:119], v[170:173], v[188:191], v[116:119]
	v_mfma_f32_16x16x32_bf16 v[124:127], v[178:181], v[188:191], v[124:127]
	v_mfma_f32_16x16x32_bf16 v[100:103], v[170:173], v[196:199], v[100:103]
	v_mfma_f32_16x16x32_bf16 v[108:111], v[178:181], v[196:199], v[108:111]
	v_mfma_f32_16x16x32_bf16 v[84:87], v[170:173], v[204:207], v[84:87]
	v_mfma_f32_16x16x32_bf16 v[92:95], v[178:181], v[204:207], v[92:95]
	v_mfma_f32_16x16x32_bf16 v[68:71], v[170:173], v[212:215], v[68:71]
	v_mfma_f32_16x16x32_bf16 v[76:79], v[178:181], v[212:215], v[76:79]
	s_setprio 0
	s_barrier
	s_add_u32 s98, s46, 0x80
	s_addc_u32 s99, s47, 0
	s_add_u32 s100, s50, 0x80
	s_addc_u32 s101, s51, 0
	s_add_i32 s70, s66, s53
	s_mov_b32 m0, s70
	ds_read_b128 v[182:185], v153 offset:16384
	ds_read_b128 v[188:191], v153 offset:17408
	ds_read_b128 v[192:195], v153 offset:18432
	ds_read_b128 v[196:199], v153 offset:19456
	ds_read_b128 v[200:203], v153 offset:20480
	ds_read_b128 v[204:207], v153 offset:21504
	ds_read_b128 v[208:211], v153 offset:22528
	ds_read_b128 v[212:215], v153 offset:23552
	global_load_lds_dwordx4 v142, s[46:47]
	s_add_i32 m0, s70, 0x2000
	s_add_u32 s76, s46, 0x40000
	s_addc_u32 s77, s47, 0
	s_add_i32 s70, s67, s53
	global_load_lds_dwordx4 v146, s[46:47]
	s_mov_b32 m0, s70
	s_nop 0
	global_load_lds_dwordx4 v142, s[76:77]
	s_add_i32 m0, s70, 0x2000
	s_nop 0
	global_load_lds_dwordx4 v146, s[76:77]
	s_waitcnt vmcnt(6)
	s_waitcnt lgkmcnt(0)
	s_barrier
	s_setprio 1
	s_waitcnt lgkmcnt(0)
	v_mfma_f32_16x16x32_bf16 v[48:51], v[136:139], v[182:185], v[48:51]
	v_mfma_f32_16x16x32_bf16 v[56:59], v[158:161], v[182:185], v[56:59]
	v_mfma_f32_16x16x32_bf16 v[16:19], v[136:139], v[192:195], v[16:19]
	v_mfma_f32_16x16x32_bf16 v[24:27], v[158:161], v[192:195], v[24:27]
	v_mfma_f32_16x16x32_bf16 v[32:35], v[136:139], v[200:203], v[32:35]
	v_mfma_f32_16x16x32_bf16 v[40:43], v[158:161], v[200:203], v[40:43]
	v_mfma_f32_16x16x32_bf16 v[0:3], v[136:139], v[208:211], v[0:3]
	v_mfma_f32_16x16x32_bf16 v[8:11], v[158:161], v[208:211], v[8:11]
	v_mfma_f32_16x16x32_bf16 v[48:51], v[154:157], v[188:191], v[48:51]
	v_mfma_f32_16x16x32_bf16 v[56:59], v[162:165], v[188:191], v[56:59]
	v_mfma_f32_16x16x32_bf16 v[16:19], v[154:157], v[196:199], v[16:19]
	v_mfma_f32_16x16x32_bf16 v[24:27], v[162:165], v[196:199], v[24:27]
	v_mfma_f32_16x16x32_bf16 v[32:35], v[154:157], v[204:207], v[32:35]
	v_mfma_f32_16x16x32_bf16 v[40:43], v[162:165], v[204:207], v[40:43]
	v_mfma_f32_16x16x32_bf16 v[0:3], v[154:157], v[212:215], v[0:3]
	v_mfma_f32_16x16x32_bf16 v[8:11], v[162:165], v[212:215], v[8:11]
	s_setprio 0
	s_setprio 1
	v_mfma_f32_16x16x32_bf16 v[52:55], v[166:169], v[182:185], v[52:55]
	v_mfma_f32_16x16x32_bf16 v[60:63], v[174:177], v[182:185], v[60:63]
	v_mfma_f32_16x16x32_bf16 v[20:23], v[166:169], v[192:195], v[20:23]
	v_mfma_f32_16x16x32_bf16 v[28:31], v[174:177], v[192:195], v[28:31]
	v_mfma_f32_16x16x32_bf16 v[36:39], v[166:169], v[200:203], v[36:39]
	v_mfma_f32_16x16x32_bf16 v[44:47], v[174:177], v[200:203], v[44:47]
	v_mfma_f32_16x16x32_bf16 v[4:7], v[166:169], v[208:211], v[4:7]
	v_mfma_f32_16x16x32_bf16 v[12:15], v[174:177], v[208:211], v[12:15]
	v_mfma_f32_16x16x32_bf16 v[52:55], v[170:173], v[188:191], v[52:55]
	v_mfma_f32_16x16x32_bf16 v[60:63], v[178:181], v[188:191], v[60:63]
	v_mfma_f32_16x16x32_bf16 v[20:23], v[170:173], v[196:199], v[20:23]
	v_mfma_f32_16x16x32_bf16 v[28:31], v[178:181], v[196:199], v[28:31]
	v_mfma_f32_16x16x32_bf16 v[36:39], v[170:173], v[204:207], v[36:39]
	v_mfma_f32_16x16x32_bf16 v[44:47], v[178:181], v[204:207], v[44:47]
	v_mfma_f32_16x16x32_bf16 v[4:7], v[170:173], v[212:215], v[4:7]
	v_mfma_f32_16x16x32_bf16 v[12:15], v[178:181], v[212:215], v[12:15]
	s_setprio 0
	s_barrier
; #define PG8_STAGE(bufoff, gbase, voff) do { _Pragma("unroll") for (int _i = 0; _i < 2; ++_i) \
;         __builtin_amdgcn_global_load_lds((const unsigned*)((const char*)(gbase) + (voff)[_i]), (PG8_LAS unsigned*)(lds + (bufoff) + ldsw + _i * 8192), 16, 0, 0); } while (0)
; #define PG8_LDA(dst, b, h) do { _Pragma("unroll") for (int m = 0; m < 4; ++m) _Pragma("unroll") for (int k = 0; k < 2; ++k) dst[m][k] = *(const PG8_LAS bf16x8*)(lds + PG8_SA(b, h) + aoff + m * 2048 + k * 1024); } while (0)
; #define PG8_LDB(dst, b, h) do { _Pragma("unroll") for (int n = 0; n < 2; ++n) _Pragma("unroll") for (int k = 0; k < 2; ++k) dst[n][k] = *(const PG8_LAS bf16x8*)(lds + PG8_SB(b, h) + boff + n * 2048 + k * 1024); } while (0)
; #define PG8_MMA(ai, bj, At, Bt) do { __builtin_amdgcn_s_setprio(1); _Pragma("unroll") for (int m = 0; m < 4; ++m) _Pragma("unroll") for (int n = 0; n < 2; ++n) _Pragma("unroll") for (int k = 0; k < 2; ++k) \
;         acc[ai][bj][m][n] = __builtin_amdgcn_mfma_f32_16x16x32_bf16(Bt[n][k], At[m][k], acc[ai][bj][m][n], 0, 0, 0); __builtin_amdgcn_s_setprio(0); } while (0)
; #define PG8_WAIT_V(n) asm volatile("s_waitcnt vmcnt(" #n ")" ::: "memory")
; #define PG8_WAIT_L(n) asm volatile("s_waitcnt lgkmcnt(" #n ")" ::: "memory")
; #define PG8_BAR __builtin_amdgcn_s_barrier()
; #define PG8_SCHED __builtin_amdgcn_sched_barrier(0)
; template <class Epi, class Sched, bool ALIGN_EPI = false, bool SP2 = false>
; __device__ __forceinline__ void gemm_phase(PG8_LAS unsigned char* lds, const Gemm g, const Sched S, const Epi E, const int tid) {
;     ...
;             PG8_LDB(B0, 1, 0); PG8_LDB(B1, 1, 1); PG8_SCHED; PG8_LDA(At, 1, 0); PG8_STAGE(PG8_SA(0, 1), a2 + hstepA, voffA);
;             PG8_WAIT_V(8); PG8_WAIT_L(0); PG8_BAR; PG8_MMA(0, 0, At, B0); PG8_MMA(0, 1, At, B1); PG8_BAR; PG8_SCHED;
;             PG8_LDA(At, 1, 1); PG8_STAGE(PG8_SB(1, 0), b3, voffB); PG8_STAGE(PG8_SB(1, 1), b3 + hstepB, voffB); PG8_STAGE(PG8_SA(1, 0), a3, voffA);
;             PG8_WAIT_V(8); PG8_WAIT_L(0); PG8_BAR; PG8_MMA(1, 0, At, B0); PG8_MMA(1, 1, At, B1); PG8_BAR; PG8_SCHED;
	s_add_i32 s70, 0, 0x18000
	s_add_i32 s76, 0, 0x1c000
	v_add_u32_e32 v162, s70, v149
	v_add_u32_e32 v178, s76, v149
	ds_read_b128 v[136:139], v162
	ds_read_b128 v[154:157], v162 offset:1024
	ds_read_b128 v[158:161], v162 offset:2048
	ds_read_b128 v[162:165], v162 offset:3072
	ds_read_b128 v[166:169], v178
	ds_read_b128 v[170:173], v178 offset:1024
	ds_read_b128 v[174:177], v178 offset:2048
	ds_read_b128 v[178:181], v178 offset:3072
	s_mov_b32 m0, s56
	s_nop 0
	global_load_lds_dwordx4 v140, s[50:51]
	s_mov_b32 m0, s57
	s_nop 0
	global_load_lds_dwordx4 v144, s[50:51]
	s_add_u32 s50, s50, 0x40000
	s_addc_u32 s51, s51, 0
	s_mov_b32 m0, s58
	ds_read_b128 v[182:185], v153 offset:32768
	ds_read_b128 v[188:191], v153 offset:33792
	ds_read_b128 v[192:195], v153 offset:34816
	ds_read_b128 v[196:199], v153 offset:35840
	ds_read_b128 v[200:203], v153 offset:36864
	ds_read_b128 v[204:207], v153 offset:37888
	ds_read_b128 v[208:211], v153 offset:38912
	ds_read_b128 v[212:215], v153 offset:39936
	global_load_lds_dwordx4 v140, s[50:51]
	s_mov_b32 m0, s59
	s_nop 0
	global_load_lds_dwordx4 v144, s[50:51]
	s_waitcnt vmcnt(8)
	s_waitcnt lgkmcnt(0)
	s_barrier
	s_setprio 1
	s_waitcnt lgkmcnt(0)
	v_mfma_f32_16x16x32_bf16 v[112:115], v[136:139], v[182:185], v[112:115]
	v_mfma_f32_16x16x32_bf16 v[120:123], v[158:161], v[182:185], v[120:123]
	v_mfma_f32_16x16x32_bf16 v[96:99], v[136:139], v[192:195], v[96:99]
	v_mfma_f32_16x16x32_bf16 v[104:107], v[158:161], v[192:195], v[104:107]
	v_mfma_f32_16x16x32_bf16 v[80:83], v[136:139], v[200:203], v[80:83]
	v_mfma_f32_16x16x32_bf16 v[88:91], v[158:161], v[200:203], v[88:91]
	v_mfma_f32_16x16x32_bf16 v[64:67], v[136:139], v[208:211], v[64:67]
	v_mfma_f32_16x16x32_bf16 v[72:75], v[158:161], v[208:211], v[72:75]
	v_mfma_f32_16x16x32_bf16 v[112:115], v[154:157], v[188:191], v[112:115]
	v_mfma_f32_16x16x32_bf16 v[120:123], v[162:165], v[188:191], v[120:123]
	v_mfma_f32_16x16x32_bf16 v[96:99], v[154:157], v[196:199], v[96:99]
	v_mfma_f32_16x16x32_bf16 v[104:107], v[162:165], v[196:199], v[104:107]
	v_mfma_f32_16x16x32_bf16 v[80:83], v[154:157], v[204:207], v[80:83]
	v_mfma_f32_16x16x32_bf16 v[88:91], v[162:165], v[204:207], v[88:91]
	v_mfma_f32_16x16x32_bf16 v[64:67], v[154:157], v[212:215], v[64:67]
	v_mfma_f32_16x16x32_bf16 v[72:75], v[162:165], v[212:215], v[72:75]
	s_setprio 0
	s_setprio 1
	v_mfma_f32_16x16x32_bf16 v[116:119], v[166:169], v[182:185], v[116:119]
	v_mfma_f32_16x16x32_bf16 v[124:127], v[174:177], v[182:185], v[124:127]
	v_mfma_f32_16x16x32_bf16 v[100:103], v[166:169], v[192:195], v[100:103]
	v_mfma_f32_16x16x32_bf16 v[108:111], v[174:177], v[192:195], v[108:111]
	v_mfma_f32_16x16x32_bf16 v[84:87], v[166:169], v[200:203], v[84:87]
	v_mfma_f32_16x16x32_bf16 v[92:95], v[174:177], v[200:203], v[92:95]
	v_mfma_f32_16x16x32_bf16 v[68:71], v[166:169], v[208:211], v[68:71]
	v_mfma_f32_16x16x32_bf16 v[76:79], v[174:177], v[208:211], v[76:79]
	v_mfma_f32_16x16x32_bf16 v[116:119], v[170:173], v[188:191], v[116:119]
	v_mfma_f32_16x16x32_bf16 v[124:127], v[178:181], v[188:191], v[124:127]
	v_mfma_f32_16x16x32_bf16 v[100:103], v[170:173], v[196:199], v[100:103]
	v_mfma_f32_16x16x32_bf16 v[108:111], v[178:181], v[196:199], v[108:111]
	v_mfma_f32_16x16x32_bf16 v[84:87], v[170:173], v[204:207], v[84:87]
	v_mfma_f32_16x16x32_bf16 v[92:95], v[178:181], v[204:207], v[92:95]
	v_mfma_f32_16x16x32_bf16 v[68:71], v[170:173], v[212:215], v[68:71]
	v_mfma_f32_16x16x32_bf16 v[76:79], v[178:181], v[212:215], v[76:79]
	s_setprio 0
	s_barrier
	s_add_i32 s50, s70, s53
	s_mov_b32 m0, s50
	ds_read_b128 v[182:185], v153 offset:49152
	ds_read_b128 v[188:191], v153 offset:50176
	ds_read_b128 v[192:195], v153 offset:51200
	ds_read_b128 v[196:199], v153 offset:52224
	ds_read_b128 v[200:203], v153 offset:53248
	ds_read_b128 v[204:207], v153 offset:54272
	ds_read_b128 v[208:211], v153 offset:55296
	ds_read_b128 v[212:215], v153 offset:56320
	global_load_lds_dwordx4 v142, s[98:99]
	s_add_i32 m0, s50, 0x2000
	s_add_u32 s46, s46, 0x40080
	s_addc_u32 s47, s47, 0
	s_add_i32 s50, s76, s53
	global_load_lds_dwordx4 v146, s[98:99]
	s_mov_b32 m0, s50
	s_nop 0
	global_load_lds_dwordx4 v142, s[46:47]
	s_add_i32 m0, s50, 0x2000
	s_nop 0
	global_load_lds_dwordx4 v146, s[46:47]
	s_mov_b32 m0, s61
	s_nop 0
	global_load_lds_dwordx4 v140, s[100:101]
	s_mov_b32 m0, s62
	s_nop 0
	global_load_lds_dwordx4 v144, s[100:101]
	s_waitcnt vmcnt(8)
	s_waitcnt lgkmcnt(0)
	s_barrier
	s_setprio 1
	s_waitcnt lgkmcnt(0)
	v_mfma_f32_16x16x32_bf16 v[48:51], v[136:139], v[182:185], v[48:51]
	v_mfma_f32_16x16x32_bf16 v[56:59], v[158:161], v[182:185], v[56:59]
	v_mfma_f32_16x16x32_bf16 v[16:19], v[136:139], v[192:195], v[16:19]
	v_mfma_f32_16x16x32_bf16 v[24:27], v[158:161], v[192:195], v[24:27]
	v_mfma_f32_16x16x32_bf16 v[32:35], v[136:139], v[200:203], v[32:35]
	v_mfma_f32_16x16x32_bf16 v[40:43], v[158:161], v[200:203], v[40:43]
	v_mfma_f32_16x16x32_bf16 v[0:3], v[136:139], v[208:211], v[0:3]
	v_mfma_f32_16x16x32_bf16 v[8:11], v[158:161], v[208:211], v[8:11]
	v_mfma_f32_16x16x32_bf16 v[48:51], v[154:157], v[188:191], v[48:51]
	v_mfma_f32_16x16x32_bf16 v[56:59], v[162:165], v[188:191], v[56:59]
	v_mfma_f32_16x16x32_bf16 v[16:19], v[154:157], v[196:199], v[16:19]
	v_mfma_f32_16x16x32_bf16 v[24:27], v[162:165], v[196:199], v[24:27]
	v_mfma_f32_16x16x32_bf16 v[32:35], v[154:157], v[204:207], v[32:35]
	v_mfma_f32_16x16x32_bf16 v[40:43], v[162:165], v[204:207], v[40:43]
	v_mfma_f32_16x16x32_bf16 v[0:3], v[154:157], v[212:215], v[0:3]
	v_mfma_f32_16x16x32_bf16 v[8:11], v[162:165], v[212:215], v[8:11]
	s_setprio 0
	s_setprio 1
	v_mfma_f32_16x16x32_bf16 v[52:55], v[166:169], v[182:185], v[52:55]
	v_mfma_f32_16x16x32_bf16 v[60:63], v[174:177], v[182:185], v[60:63]
	v_mfma_f32_16x16x32_bf16 v[20:23], v[166:169], v[192:195], v[20:23]
	v_mfma_f32_16x16x32_bf16 v[28:31], v[174:177], v[192:195], v[28:31]
	v_mfma_f32_16x16x32_bf16 v[36:39], v[166:169], v[200:203], v[36:39]
	v_mfma_f32_16x16x32_bf16 v[44:47], v[174:177], v[200:203], v[44:47]
	v_mfma_f32_16x16x32_bf16 v[4:7], v[166:169], v[208:211], v[4:7]
	v_mfma_f32_16x16x32_bf16 v[12:15], v[174:177], v[208:211], v[12:15]
	v_mfma_f32_16x16x32_bf16 v[52:55], v[170:173], v[188:191], v[52:55]
	v_mfma_f32_16x16x32_bf16 v[60:63], v[178:181], v[188:191], v[60:63]
	v_mfma_f32_16x16x32_bf16 v[20:23], v[170:173], v[196:199], v[20:23]
	v_mfma_f32_16x16x32_bf16 v[28:31], v[178:181], v[196:199], v[28:31]
	v_mfma_f32_16x16x32_bf16 v[36:39], v[170:173], v[204:207], v[36:39]
	v_mfma_f32_16x16x32_bf16 v[44:47], v[178:181], v[204:207], v[44:47]
	v_mfma_f32_16x16x32_bf16 v[4:7], v[170:173], v[212:215], v[4:7]
	v_mfma_f32_16x16x32_bf16 v[12:15], v[178:181], v[212:215], v[12:15]
	s_setprio 0
	s_barrier
	s_add_i32 s75, s75, 2
	s_add_u32 s48, s48, 0x100
	s_addc_u32 s49, s49, 0
	s_add_u32 s69, s69, 0x100
	s_addc_u32 s74, s74, 0
	s_cmp_gt_u32 s75, 13
	s_cbranch_scc0 .LBB0_886
	s_and_b64 vcc, exec, s[26:27]
	s_cbranch_vccz .LBB0_889
	s_barrier

; #define PG8_STAGE(bufoff, gbase, voff) do { _Pragma("unroll") for (int _i = 0; _i < 2; ++_i) \
;         __builtin_amdgcn_global_load_lds((const unsigned*)((const char*)(gbase) + (voff)[_i]), (PG8_LAS unsigned*)(lds + (bufoff) + ldsw + _i * 8192), 16, 0, 0); } while (0)
; #define PG8_LDA(dst, b, h) do { _Pragma("unroll") for (int m = 0; m < 4; ++m) _Pragma("unroll") for (int k = 0; k < 2; ++k) dst[m][k] = *(const PG8_LAS bf16x8*)(lds + PG8_SA(b, h) + aoff + m * 2048 + k * 1024); } while (0)
; #define PG8_LDB(dst, b, h) do { _Pragma("unroll") for (int n = 0; n < 2; ++n) _Pragma("unroll") for (int k = 0; k < 2; ++k) dst[n][k] = *(const PG8_LAS bf16x8*)(lds + PG8_SB(b, h) + boff + n * 2048 + k * 1024); } while (0)
; #define PG8_MMA(ai, bj, At, Bt) do { __builtin_amdgcn_s_setprio(1); _Pragma("unroll") for (int m = 0; m < 4; ++m) _Pragma("unroll") for (int n = 0; n < 2; ++n) _Pragma("unroll") for (int k = 0; k < 2; ++k) \
;         acc[ai][bj][m][n] = __builtin_amdgcn_mfma_f32_16x16x32_bf16(Bt[n][k], At[m][k], acc[ai][bj][m][n], 0, 0, 0); __builtin_amdgcn_s_setprio(0); } while (0)
; #define PG8_WAIT_V(n) asm volatile("s_waitcnt vmcnt(" #n ")" ::: "memory")
; #define PG8_WAIT_L(n) asm volatile("s_waitcnt lgkmcnt(" #n ")" ::: "memory")
; template <class Epi, class Sched, bool ALIGN_EPI = false, bool SP2 = false>
; __device__ __forceinline__ void gemm_phase(PG8_LAS unsigned char* lds, const Gemm g, const Sched S, const Epi E, const int tid) {
;     ...
;             const bool last = (t == nt - 2);
;             const char* a1 = cA + (size_t)(t + 1) * kstep;
;             const char* a2 = last ? nA : cA + (size_t)(t + 2) * kstep; const char* b2 = last ? nB : cB + (size_t)(t + 2) * kstep;
;             const char* a3 = a2 + kstep; const char* b3 = b2 + kstep;
;             if (last && has_next) S.a_ready(nxt);
;             if constexpr (SP2) {
;             PG8_LDB(B0, 0, 0); PG8_LDB(B1, 0, 1); PG8_SCHED; PG8_LDA(At, 0, 0); PG8_STAGE(PG8_SA(1, 1), a1 + hstepA, voffA);
;             PG8_WAIT_V(8); PG8_WAIT_L(0); PG8_BAR; PG8_MMA(0, 0, At, B0); PG8_MMA(0, 1, At, B1); PG8_BAR; PG8_SCHED;
;             PG8_LDA(At, 0, 1); PG8_STAGE(PG8_SB(0, 0), b2, voffB); PG8_STAGE(PG8_SB(0, 1), b2 + hstepB, voffB); PG8_STAGE(PG8_SA(0, 0), a2, voffA);
;             PG8_WAIT_V(8); PG8_WAIT_L(0); PG8_BAR; PG8_MMA(1, 0, At, B0); PG8_MMA(1, 1, At, B1); PG8_BAR; PG8_SCHED;
.LBB0_991:
	ds_read_b128 v[144:147], v159
	ds_read_b128 v[148:151], v159 offset:1024
	ds_read_b128 v[162:165], v159 offset:2048
	ds_read_b128 v[166:169], v159 offset:3072
	ds_read_b128 v[170:173], v160
	ds_read_b128 v[174:177], v160 offset:1024
	ds_read_b128 v[178:181], v160 offset:2048
	ds_read_b128 v[182:185], v160 offset:3072
	s_add_u32 s34, s30, 0xfffc0080
	s_addc_u32 s35, s31, -1
	s_cmp_eq_u32 s65, 12
	s_cselect_b32 s37, s23, s35
	s_cselect_b32 s36, s61, s34
	s_cselect_b32 s35, s21, s64
	s_cselect_b32 s34, s62, s63
	s_add_i32 m0, s29, 0xc000
	ds_read_b128 v[188:191], v161
	ds_read_b128 v[192:195], v161 offset:1024
	ds_read_b128 v[196:199], v161 offset:2048
	ds_read_b128 v[200:203], v161 offset:3072
	ds_read_b128 v[204:207], v161 offset:4096
	ds_read_b128 v[208:211], v161 offset:5120
	ds_read_b128 v[212:215], v161 offset:6144
	ds_read_b128 v[216:219], v161 offset:7168
	global_load_lds_dwordx4 v136, s[30:31]
	s_add_i32 m0, s29, 0xe000
	s_nop 0
	global_load_lds_dwordx4 v138, s[30:31]
	s_waitcnt vmcnt(8)
	s_waitcnt lgkmcnt(0)
	s_barrier
	s_setprio 1
	s_waitcnt lgkmcnt(0)
	v_mfma_f32_16x16x32_bf16 v[124:127], v[144:147], v[188:191], v[124:127]
	v_mfma_f32_16x16x32_bf16 v[120:123], v[162:165], v[188:191], v[120:123]
	v_mfma_f32_16x16x32_bf16 v[108:111], v[144:147], v[196:199], v[108:111]
	v_mfma_f32_16x16x32_bf16 v[104:107], v[162:165], v[196:199], v[104:107]
	v_mfma_f32_16x16x32_bf16 v[92:95], v[144:147], v[204:207], v[92:95]
	v_mfma_f32_16x16x32_bf16 v[88:91], v[162:165], v[204:207], v[88:91]
	v_mfma_f32_16x16x32_bf16 v[76:79], v[144:147], v[212:215], v[76:79]
	v_mfma_f32_16x16x32_bf16 v[72:75], v[162:165], v[212:215], v[72:75]
	v_mfma_f32_16x16x32_bf16 v[124:127], v[148:151], v[192:195], v[124:127]
	v_mfma_f32_16x16x32_bf16 v[120:123], v[166:169], v[192:195], v[120:123]
	v_mfma_f32_16x16x32_bf16 v[108:111], v[148:151], v[200:203], v[108:111]
	v_mfma_f32_16x16x32_bf16 v[104:107], v[166:169], v[200:203], v[104:107]
	v_mfma_f32_16x16x32_bf16 v[92:95], v[148:151], v[208:211], v[92:95]
	v_mfma_f32_16x16x32_bf16 v[88:91], v[166:169], v[208:211], v[88:91]
	v_mfma_f32_16x16x32_bf16 v[76:79], v[148:151], v[216:219], v[76:79]
	v_mfma_f32_16x16x32_bf16 v[72:75], v[166:169], v[216:219], v[72:75]
	s_setprio 0
	s_setprio 1
	v_mfma_f32_16x16x32_bf16 v[116:119], v[170:173], v[188:191], v[116:119]
	v_mfma_f32_16x16x32_bf16 v[112:115], v[178:181], v[188:191], v[112:115]
	v_mfma_f32_16x16x32_bf16 v[100:103], v[170:173], v[196:199], v[100:103]
	v_mfma_f32_16x16x32_bf16 v[96:99], v[178:181], v[196:199], v[96:99]
	v_mfma_f32_16x16x32_bf16 v[84:87], v[170:173], v[204:207], v[84:87]
	v_mfma_f32_16x16x32_bf16 v[80:83], v[178:181], v[204:207], v[80:83]
	v_mfma_f32_16x16x32_bf16 v[68:71], v[170:173], v[212:215], v[68:71]
	v_mfma_f32_16x16x32_bf16 v[64:67], v[178:181], v[212:215], v[64:67]
	v_mfma_f32_16x16x32_bf16 v[116:119], v[174:177], v[192:195], v[116:119]
	v_mfma_f32_16x16x32_bf16 v[112:115], v[182:185], v[192:195], v[112:115]
	v_mfma_f32_16x16x32_bf16 v[100:103], v[174:177], v[200:203], v[100:103]
	v_mfma_f32_16x16x32_bf16 v[96:99], v[182:185], v[200:203], v[96:99]
	v_mfma_f32_16x16x32_bf16 v[84:87], v[174:177], v[208:211], v[84:87]
	v_mfma_f32_16x16x32_bf16 v[80:83], v[182:185], v[208:211], v[80:83]
	v_mfma_f32_16x16x32_bf16 v[68:71], v[174:177], v[216:219], v[68:71]
	v_mfma_f32_16x16x32_bf16 v[64:67], v[182:185], v[216:219], v[64:67]
	s_setprio 0
	s_barrier
	s_add_u32 s98, s34, 0x80
	s_addc_u32 s99, s35, 0
	s_add_u32 s100, s36, 0x80
	s_addc_u32 s101, s37, 0
	s_add_i32 s66, s55, s19
	s_mov_b32 m0, s66
	ds_read_b128 v[188:191], v161 offset:16384
	ds_read_b128 v[192:195], v161 offset:17408
	ds_read_b128 v[196:199], v161 offset:18432
	ds_read_b128 v[200:203], v161 offset:19456
	ds_read_b128 v[204:207], v161 offset:20480
	ds_read_b128 v[208:211], v161 offset:21504
	ds_read_b128 v[212:215], v161 offset:22528
	ds_read_b128 v[216:219], v161 offset:23552
	global_load_lds_dwordx4 v132, s[34:35]
	s_add_i32 m0, s66, 0x2000
	s_add_u32 s66, s34, 0x40000
	s_addc_u32 s67, s35, 0
	s_add_i32 s69, s56, s19
	global_load_lds_dwordx4 v128, s[34:35]
	s_mov_b32 m0, s69
	s_nop 0
	global_load_lds_dwordx4 v132, s[66:67]
	s_add_i32 m0, s69, 0x2000
	s_nop 0
	global_load_lds_dwordx4 v128, s[66:67]
	s_waitcnt vmcnt(6)
	s_waitcnt lgkmcnt(0)
	s_barrier
	s_setprio 1
	s_waitcnt lgkmcnt(0)
	v_mfma_f32_16x16x32_bf16 v[60:63], v[144:147], v[188:191], v[60:63]
	v_mfma_f32_16x16x32_bf16 v[56:59], v[162:165], v[188:191], v[56:59]
	v_mfma_f32_16x16x32_bf16 v[44:47], v[144:147], v[196:199], v[44:47]
	v_mfma_f32_16x16x32_bf16 v[40:43], v[162:165], v[196:199], v[40:43]
	v_mfma_f32_16x16x32_bf16 v[28:31], v[144:147], v[204:207], v[28:31]
	v_mfma_f32_16x16x32_bf16 v[24:27], v[162:165], v[204:207], v[24:27]
	v_mfma_f32_16x16x32_bf16 v[12:15], v[144:147], v[212:215], v[12:15]
	v_mfma_f32_16x16x32_bf16 v[8:11], v[162:165], v[212:215], v[8:11]
	v_mfma_f32_16x16x32_bf16 v[60:63], v[148:151], v[192:195], v[60:63]
	v_mfma_f32_16x16x32_bf16 v[56:59], v[166:169], v[192:195], v[56:59]
	v_mfma_f32_16x16x32_bf16 v[44:47], v[148:151], v[200:203], v[44:47]
	v_mfma_f32_16x16x32_bf16 v[40:43], v[166:169], v[200:203], v[40:43]
	v_mfma_f32_16x16x32_bf16 v[28:31], v[148:151], v[208:211], v[28:31]
	v_mfma_f32_16x16x32_bf16 v[24:27], v[166:169], v[208:211], v[24:27]
	v_mfma_f32_16x16x32_bf16 v[12:15], v[148:151], v[216:219], v[12:15]
	v_mfma_f32_16x16x32_bf16 v[8:11], v[166:169], v[216:219], v[8:11]
	s_setprio 0
	s_setprio 1
	v_mfma_f32_16x16x32_bf16 v[52:55], v[170:173], v[188:191], v[52:55]
	v_mfma_f32_16x16x32_bf16 v[48:51], v[178:181], v[188:191], v[48:51]
	v_mfma_f32_16x16x32_bf16 v[36:39], v[170:173], v[196:199], v[36:39]
	v_mfma_f32_16x16x32_bf16 v[32:35], v[178:181], v[196:199], v[32:35]
	v_mfma_f32_16x16x32_bf16 v[20:23], v[170:173], v[204:207], v[20:23]
	v_mfma_f32_16x16x32_bf16 v[16:19], v[178:181], v[204:207], v[16:19]
	v_mfma_f32_16x16x32_bf16 v[4:7], v[170:173], v[212:215], v[4:7]
	v_mfma_f32_16x16x32_bf16 v[0:3], v[178:181], v[212:215], v[0:3]
	v_mfma_f32_16x16x32_bf16 v[52:55], v[174:177], v[192:195], v[52:55]
	v_mfma_f32_16x16x32_bf16 v[48:51], v[182:185], v[192:195], v[48:51]
	v_mfma_f32_16x16x32_bf16 v[36:39], v[174:177], v[200:203], v[36:39]
	v_mfma_f32_16x16x32_bf16 v[32:35], v[182:185], v[200:203], v[32:35]
	v_mfma_f32_16x16x32_bf16 v[20:23], v[174:177], v[208:211], v[20:23]
	v_mfma_f32_16x16x32_bf16 v[16:19], v[182:185], v[208:211], v[16:19]
	v_mfma_f32_16x16x32_bf16 v[4:7], v[174:177], v[216:219], v[4:7]
	v_mfma_f32_16x16x32_bf16 v[0:3], v[182:185], v[216:219], v[0:3]
	s_setprio 0
	s_barrier
; #define PG8_STAGE(bufoff, gbase, voff) do { _Pragma("unroll") for (int _i = 0; _i < 2; ++_i) \
;         __builtin_amdgcn_global_load_lds((const unsigned*)((const char*)(gbase) + (voff)[_i]), (PG8_LAS unsigned*)(lds + (bufoff) + ldsw + _i * 8192), 16, 0, 0); } while (0)
; #define PG8_LDA(dst, b, h) do { _Pragma("unroll") for (int m = 0; m < 4; ++m) _Pragma("unroll") for (int k = 0; k < 2; ++k) dst[m][k] = *(const PG8_LAS bf16x8*)(lds + PG8_SA(b, h) + aoff + m * 2048 + k * 1024); } while (0)
; #define PG8_LDB(dst, b, h) do { _Pragma("unroll") for (int n = 0; n < 2; ++n) _Pragma("unroll") for (int k = 0; k < 2; ++k) dst[n][k] = *(const PG8_LAS bf16x8*)(lds + PG8_SB(b, h) + boff + n * 2048 + k * 1024); } while (0)
; #define PG8_MMA(ai, bj, At, Bt) do { __builtin_amdgcn_s_setprio(1); _Pragma("unroll") for (int m = 0; m < 4; ++m) _Pragma("unroll") for (int n = 0; n < 2; ++n) _Pragma("unroll") for (int k = 0; k < 2; ++k) \
;         acc[ai][bj][m][n] = __builtin_amdgcn_mfma_f32_16x16x32_bf16(Bt[n][k], At[m][k], acc[ai][bj][m][n], 0, 0, 0); __builtin_amdgcn_s_setprio(0); } while (0)
; #define PG8_WAIT_V(n) asm volatile("s_waitcnt vmcnt(" #n ")" ::: "memory")
; #define PG8_WAIT_L(n) asm volatile("s_waitcnt lgkmcnt(" #n ")" ::: "memory")
; #define PG8_BAR __builtin_amdgcn_s_barrier()
; #define PG8_SCHED __builtin_amdgcn_sched_barrier(0)
; template <class Epi, class Sched, bool ALIGN_EPI = false, bool SP2 = false>
; __device__ __forceinline__ void gemm_phase(PG8_LAS unsigned char* lds, const Gemm g, const Sched S, const Epi E, const int tid) {
;     ...
;             PG8_LDB(B0, 1, 0); PG8_LDB(B1, 1, 1); PG8_SCHED; PG8_LDA(At, 1, 0); PG8_STAGE(PG8_SA(0, 1), a2 + hstepA, voffA);
;             PG8_WAIT_V(8); PG8_WAIT_L(0); PG8_BAR; PG8_MMA(0, 0, At, B0); PG8_MMA(0, 1, At, B1); PG8_BAR; PG8_SCHED;
;             PG8_LDA(At, 1, 1); PG8_STAGE(PG8_SB(1, 0), b3, voffB); PG8_STAGE(PG8_SB(1, 1), b3 + hstepB, voffB); PG8_STAGE(PG8_SA(1, 0), a3, voffA);
;             PG8_WAIT_V(8); PG8_WAIT_L(0); PG8_BAR; PG8_MMA(1, 0, At, B0); PG8_MMA(1, 1, At, B1); PG8_BAR; PG8_SCHED;
	s_add_i32 s66, 0, 0x18000
	s_add_i32 s67, 0, 0x1c000
	v_add_u32_e32 v166, s66, v156
	v_add_u32_e32 v182, s67, v156
	ds_read_b128 v[144:147], v166
	ds_read_b128 v[148:151], v166 offset:1024
	ds_read_b128 v[162:165], v166 offset:2048
	ds_read_b128 v[166:169], v166 offset:3072
	ds_read_b128 v[170:173], v182
	ds_read_b128 v[174:177], v182 offset:1024
	ds_read_b128 v[178:181], v182 offset:2048
	ds_read_b128 v[182:185], v182 offset:3072
	s_mov_b32 m0, s29
	s_nop 0
	global_load_lds_dwordx4 v134, s[36:37]
	s_mov_b32 m0, s50
	s_nop 0
	global_load_lds_dwordx4 v130, s[36:37]
	s_add_u32 s36, s36, 0x40000
	s_addc_u32 s37, s37, 0
	s_mov_b32 m0, s51
	ds_read_b128 v[188:191], v161 offset:32768
	ds_read_b128 v[192:195], v161 offset:33792
	ds_read_b128 v[196:199], v161 offset:34816
	ds_read_b128 v[200:203], v161 offset:35840
	ds_read_b128 v[204:207], v161 offset:36864
	ds_read_b128 v[208:211], v161 offset:37888
	ds_read_b128 v[212:215], v161 offset:38912
	ds_read_b128 v[216:219], v161 offset:39936
	global_load_lds_dwordx4 v134, s[36:37]
	s_mov_b32 m0, s52
	s_nop 0
	global_load_lds_dwordx4 v130, s[36:37]
	s_waitcnt vmcnt(8)
	s_waitcnt lgkmcnt(0)
	s_barrier
	s_setprio 1
	s_waitcnt lgkmcnt(0)
	v_mfma_f32_16x16x32_bf16 v[124:127], v[144:147], v[188:191], v[124:127]
	v_mfma_f32_16x16x32_bf16 v[120:123], v[162:165], v[188:191], v[120:123]
	v_mfma_f32_16x16x32_bf16 v[108:111], v[144:147], v[196:199], v[108:111]
	v_mfma_f32_16x16x32_bf16 v[104:107], v[162:165], v[196:199], v[104:107]
	v_mfma_f32_16x16x32_bf16 v[92:95], v[144:147], v[204:207], v[92:95]
	v_mfma_f32_16x16x32_bf16 v[88:91], v[162:165], v[204:207], v[88:91]
	v_mfma_f32_16x16x32_bf16 v[76:79], v[144:147], v[212:215], v[76:79]
	v_mfma_f32_16x16x32_bf16 v[72:75], v[162:165], v[212:215], v[72:75]
	v_mfma_f32_16x16x32_bf16 v[124:127], v[148:151], v[192:195], v[124:127]
	v_mfma_f32_16x16x32_bf16 v[120:123], v[166:169], v[192:195], v[120:123]
	v_mfma_f32_16x16x32_bf16 v[108:111], v[148:151], v[200:203], v[108:111]
	v_mfma_f32_16x16x32_bf16 v[104:107], v[166:169], v[200:203], v[104:107]
	v_mfma_f32_16x16x32_bf16 v[92:95], v[148:151], v[208:211], v[92:95]
	v_mfma_f32_16x16x32_bf16 v[88:91], v[166:169], v[208:211], v[88:91]
	v_mfma_f32_16x16x32_bf16 v[76:79], v[148:151], v[216:219], v[76:79]
	v_mfma_f32_16x16x32_bf16 v[72:75], v[166:169], v[216:219], v[72:75]
	s_setprio 0
	s_setprio 1
	v_mfma_f32_16x16x32_bf16 v[116:119], v[170:173], v[188:191], v[116:119]
	v_mfma_f32_16x16x32_bf16 v[112:115], v[178:181], v[188:191], v[112:115]
	v_mfma_f32_16x16x32_bf16 v[100:103], v[170:173], v[196:199], v[100:103]
	v_mfma_f32_16x16x32_bf16 v[96:99], v[178:181], v[196:199], v[96:99]
	v_mfma_f32_16x16x32_bf16 v[84:87], v[170:173], v[204:207], v[84:87]
	v_mfma_f32_16x16x32_bf16 v[80:83], v[178:181], v[204:207], v[80:83]
	v_mfma_f32_16x16x32_bf16 v[68:71], v[170:173], v[212:215], v[68:71]
	v_mfma_f32_16x16x32_bf16 v[64:67], v[178:181], v[212:215], v[64:67]
	v_mfma_f32_16x16x32_bf16 v[116:119], v[174:177], v[192:195], v[116:119]
	v_mfma_f32_16x16x32_bf16 v[112:115], v[182:185], v[192:195], v[112:115]
	v_mfma_f32_16x16x32_bf16 v[100:103], v[174:177], v[200:203], v[100:103]
	v_mfma_f32_16x16x32_bf16 v[96:99], v[182:185], v[200:203], v[96:99]
	v_mfma_f32_16x16x32_bf16 v[84:87], v[174:177], v[208:211], v[84:87]
	v_mfma_f32_16x16x32_bf16 v[80:83], v[182:185], v[208:211], v[80:83]
	v_mfma_f32_16x16x32_bf16 v[68:71], v[174:177], v[216:219], v[68:71]
	v_mfma_f32_16x16x32_bf16 v[64:67], v[182:185], v[216:219], v[64:67]
	s_setprio 0
	s_barrier
	s_add_i32 s36, s66, s19
	s_mov_b32 m0, s36
	ds_read_b128 v[188:191], v161 offset:49152
	ds_read_b128 v[192:195], v161 offset:50176
	ds_read_b128 v[196:199], v161 offset:51200
	ds_read_b128 v[200:203], v161 offset:52224
	ds_read_b128 v[204:207], v161 offset:53248
	ds_read_b128 v[208:211], v161 offset:54272
	ds_read_b128 v[212:215], v161 offset:55296
	ds_read_b128 v[216:219], v161 offset:56320
	global_load_lds_dwordx4 v132, s[98:99]
	s_add_i32 m0, s36, 0x2000
	s_add_u32 s34, s34, 0x40080
	s_addc_u32 s35, s35, 0
	s_add_i32 s36, s67, s19
	global_load_lds_dwordx4 v128, s[98:99]
	s_mov_b32 m0, s36
	s_nop 0
	global_load_lds_dwordx4 v132, s[34:35]
	s_add_i32 m0, s36, 0x2000
	s_nop 0
	global_load_lds_dwordx4 v128, s[34:35]
	s_mov_b32 m0, s53
	s_nop 0
	global_load_lds_dwordx4 v134, s[100:101]
	s_mov_b32 m0, s54
	s_nop 0
	global_load_lds_dwordx4 v130, s[100:101]
	s_waitcnt vmcnt(8)
	s_waitcnt lgkmcnt(0)
	s_barrier
	s_setprio 1
	s_waitcnt lgkmcnt(0)
	v_mfma_f32_16x16x32_bf16 v[60:63], v[144:147], v[188:191], v[60:63]
	v_mfma_f32_16x16x32_bf16 v[56:59], v[162:165], v[188:191], v[56:59]
	v_mfma_f32_16x16x32_bf16 v[44:47], v[144:147], v[196:199], v[44:47]
	v_mfma_f32_16x16x32_bf16 v[40:43], v[162:165], v[196:199], v[40:43]
	v_mfma_f32_16x16x32_bf16 v[28:31], v[144:147], v[204:207], v[28:31]
	v_mfma_f32_16x16x32_bf16 v[24:27], v[162:165], v[204:207], v[24:27]
	v_mfma_f32_16x16x32_bf16 v[12:15], v[144:147], v[212:215], v[12:15]
	v_mfma_f32_16x16x32_bf16 v[8:11], v[162:165], v[212:215], v[8:11]
	v_mfma_f32_16x16x32_bf16 v[60:63], v[148:151], v[192:195], v[60:63]
	v_mfma_f32_16x16x32_bf16 v[56:59], v[166:169], v[192:195], v[56:59]
	v_mfma_f32_16x16x32_bf16 v[44:47], v[148:151], v[200:203], v[44:47]
	v_mfma_f32_16x16x32_bf16 v[40:43], v[166:169], v[200:203], v[40:43]
	v_mfma_f32_16x16x32_bf16 v[28:31], v[148:151], v[208:211], v[28:31]
	v_mfma_f32_16x16x32_bf16 v[24:27], v[166:169], v[208:211], v[24:27]
	v_mfma_f32_16x16x32_bf16 v[12:15], v[148:151], v[216:219], v[12:15]
	v_mfma_f32_16x16x32_bf16 v[8:11], v[166:169], v[216:219], v[8:11]
	s_setprio 0
	s_setprio 1
	v_mfma_f32_16x16x32_bf16 v[52:55], v[170:173], v[188:191], v[52:55]
	v_mfma_f32_16x16x32_bf16 v[48:51], v[178:181], v[188:191], v[48:51]
	v_mfma_f32_16x16x32_bf16 v[36:39], v[170:173], v[196:199], v[36:39]
	v_mfma_f32_16x16x32_bf16 v[32:35], v[178:181], v[196:199], v[32:35]
	v_mfma_f32_16x16x32_bf16 v[20:23], v[170:173], v[204:207], v[20:23]
	v_mfma_f32_16x16x32_bf16 v[16:19], v[178:181], v[204:207], v[16:19]
	v_mfma_f32_16x16x32_bf16 v[4:7], v[170:173], v[212:215], v[4:7]
	v_mfma_f32_16x16x32_bf16 v[0:3], v[178:181], v[212:215], v[0:3]
	v_mfma_f32_16x16x32_bf16 v[52:55], v[174:177], v[192:195], v[52:55]
	v_mfma_f32_16x16x32_bf16 v[48:51], v[182:185], v[192:195], v[48:51]
	v_mfma_f32_16x16x32_bf16 v[36:39], v[174:177], v[200:203], v[36:39]
	v_mfma_f32_16x16x32_bf16 v[32:35], v[182:185], v[200:203], v[32:35]
	v_mfma_f32_16x16x32_bf16 v[20:23], v[174:177], v[208:211], v[20:23]
	v_mfma_f32_16x16x32_bf16 v[16:19], v[182:185], v[208:211], v[16:19]
	v_mfma_f32_16x16x32_bf16 v[4:7], v[174:177], v[216:219], v[4:7]
	v_mfma_f32_16x16x32_bf16 v[0:3], v[182:185], v[216:219], v[0:3]
	s_setprio 0
	s_barrier
	s_add_i32 s65, s65, 2
	s_add_u32 s30, s30, 0x100
	s_addc_u32 s31, s31, 0
	s_add_u32 s63, s63, 0x100
	s_addc_u32 s64, s64, 0
	s_cmp_gt_u32 s65, 13
	s_cbranch_scc0 .LBB0_991
	s_and_b64 vcc, exec, s[16:17]
	s_cbranch_vccz .LBB0_994
	s_barrier

; #define PG8_STAGE(bufoff, gbase, voff) do { _Pragma("unroll") for (int _i = 0; _i < 2; ++_i) \
;         __builtin_amdgcn_global_load_lds((const unsigned*)((const char*)(gbase) + (voff)[_i]), (PG8_LAS unsigned*)(lds + (bufoff) + ldsw + _i * 8192), 16, 0, 0); } while (0)
; #define PG8_LDA(dst, b, h) do { _Pragma("unroll") for (int m = 0; m < 4; ++m) _Pragma("unroll") for (int k = 0; k < 2; ++k) dst[m][k] = *(const PG8_LAS bf16x8*)(lds + PG8_SA(b, h) + aoff + m * 2048 + k * 1024); } while (0)
; #define PG8_LDB(dst, b, h) do { _Pragma("unroll") for (int n = 0; n < 2; ++n) _Pragma("unroll") for (int k = 0; k < 2; ++k) dst[n][k] = *(const PG8_LAS bf16x8*)(lds + PG8_SB(b, h) + boff + n * 2048 + k * 1024); } while (0)
; #define PG8_MMA(ai, bj, At, Bt) do { __builtin_amdgcn_s_setprio(1); _Pragma("unroll") for (int m = 0; m < 4; ++m) _Pragma("unroll") for (int n = 0; n < 2; ++n) _Pragma("unroll") for (int k = 0; k < 2; ++k) \
;         acc[ai][bj][m][n] = __builtin_amdgcn_mfma_f32_16x16x32_bf16(Bt[n][k], At[m][k], acc[ai][bj][m][n], 0, 0, 0); __builtin_amdgcn_s_setprio(0); } while (0)
; #define PG8_WAIT_V(n) asm volatile("s_waitcnt vmcnt(" #n ")" ::: "memory")
; #define PG8_WAIT_L(n) asm volatile("s_waitcnt lgkmcnt(" #n ")" ::: "memory")
; template <class Epi, class Sched, bool ALIGN_EPI = false, bool SP2 = false>
; __device__ __forceinline__ void gemm_phase(PG8_LAS unsigned char* lds, const Gemm g, const Sched S, const Epi E, const int tid) {
;     ...
;             const bool last = (t == nt - 2);
;             const char* a1 = cA + (size_t)(t + 1) * kstep;
;             const char* a2 = last ? nA : cA + (size_t)(t + 2) * kstep; const char* b2 = last ? nB : cB + (size_t)(t + 2) * kstep;
;             const char* a3 = a2 + kstep; const char* b3 = b2 + kstep;
;             if (last && has_next) S.a_ready(nxt);
;             if constexpr (SP2) {
;             PG8_LDB(B0, 0, 0); PG8_LDB(B1, 0, 1); PG8_SCHED; PG8_LDA(At, 0, 0); PG8_STAGE(PG8_SA(1, 1), a1 + hstepA, voffA);
;             PG8_WAIT_V(8); PG8_WAIT_L(0); PG8_BAR; PG8_MMA(0, 0, At, B0); PG8_MMA(0, 1, At, B1); PG8_BAR; PG8_SCHED;
;             PG8_LDA(At, 0, 1); PG8_STAGE(PG8_SB(0, 0), b2, voffB); PG8_STAGE(PG8_SB(0, 1), b2 + hstepB, voffB); PG8_STAGE(PG8_SA(0, 0), a2, voffA);
;             PG8_WAIT_V(8); PG8_WAIT_L(0); PG8_BAR; PG8_MMA(1, 0, At, B0); PG8_MMA(1, 1, At, B1); PG8_BAR; PG8_SCHED;
.LBB0_1196:
	ds_read_b128 v[146:149], v169
	ds_read_b128 v[150:153], v169 offset:1024
	ds_read_b128 v[172:175], v169 offset:2048
	ds_read_b128 v[176:179], v169 offset:3072
	ds_read_b128 v[180:183], v170
	ds_read_b128 v[188:191], v170 offset:1024
	ds_read_b128 v[192:195], v170 offset:2048
	ds_read_b128 v[196:199], v170 offset:3072
	s_add_u32 s34, s30, 0xfffc0080
	s_addc_u32 s35, s31, -1
	s_cmp_eq_u32 s64, 12
	s_cselect_b32 s37, s23, s35
	s_cselect_b32 s36, s60, s34
	s_cselect_b32 s35, s15, s63
	s_cselect_b32 s34, s61, s62
	s_add_i32 m0, s29, 0xc000
	ds_read_b128 v[200:203], v171
	ds_read_b128 v[204:207], v171 offset:1024
	ds_read_b128 v[208:211], v171 offset:2048
	ds_read_b128 v[212:215], v171 offset:3072
	ds_read_b128 v[216:219], v171 offset:4096
	ds_read_b128 v[220:223], v171 offset:5120
	ds_read_b128 v[224:227], v171 offset:6144
	ds_read_b128 v[228:231], v171 offset:7168
	global_load_lds_dwordx4 v138, s[30:31]
	s_add_i32 m0, s29, 0xe000
	s_nop 0
	global_load_lds_dwordx4 v140, s[30:31]
	s_waitcnt vmcnt(8)
	s_waitcnt lgkmcnt(0)
	s_barrier
	s_setprio 1
	s_waitcnt lgkmcnt(0)
	v_mfma_f32_16x16x32_bf16 v[124:127], v[146:149], v[200:203], v[124:127]
	v_mfma_f32_16x16x32_bf16 v[120:123], v[172:175], v[200:203], v[120:123]
	v_mfma_f32_16x16x32_bf16 v[108:111], v[146:149], v[208:211], v[108:111]
	v_mfma_f32_16x16x32_bf16 v[104:107], v[172:175], v[208:211], v[104:107]
	v_mfma_f32_16x16x32_bf16 v[92:95], v[146:149], v[216:219], v[92:95]
	v_mfma_f32_16x16x32_bf16 v[88:91], v[172:175], v[216:219], v[88:91]
	v_mfma_f32_16x16x32_bf16 v[76:79], v[146:149], v[224:227], v[76:79]
	v_mfma_f32_16x16x32_bf16 v[72:75], v[172:175], v[224:227], v[72:75]
	v_mfma_f32_16x16x32_bf16 v[124:127], v[150:153], v[204:207], v[124:127]
	v_mfma_f32_16x16x32_bf16 v[120:123], v[176:179], v[204:207], v[120:123]
	v_mfma_f32_16x16x32_bf16 v[108:111], v[150:153], v[212:215], v[108:111]
	v_mfma_f32_16x16x32_bf16 v[104:107], v[176:179], v[212:215], v[104:107]
	v_mfma_f32_16x16x32_bf16 v[92:95], v[150:153], v[220:223], v[92:95]
	v_mfma_f32_16x16x32_bf16 v[88:91], v[176:179], v[220:223], v[88:91]
	v_mfma_f32_16x16x32_bf16 v[76:79], v[150:153], v[228:231], v[76:79]
	v_mfma_f32_16x16x32_bf16 v[72:75], v[176:179], v[228:231], v[72:75]
	s_setprio 0
	s_setprio 1
	v_mfma_f32_16x16x32_bf16 v[116:119], v[180:183], v[200:203], v[116:119]
	v_mfma_f32_16x16x32_bf16 v[112:115], v[192:195], v[200:203], v[112:115]
	v_mfma_f32_16x16x32_bf16 v[100:103], v[180:183], v[208:211], v[100:103]
	v_mfma_f32_16x16x32_bf16 v[96:99], v[192:195], v[208:211], v[96:99]
	v_mfma_f32_16x16x32_bf16 v[84:87], v[180:183], v[216:219], v[84:87]
	v_mfma_f32_16x16x32_bf16 v[80:83], v[192:195], v[216:219], v[80:83]
	v_mfma_f32_16x16x32_bf16 v[68:71], v[180:183], v[224:227], v[68:71]
	v_mfma_f32_16x16x32_bf16 v[64:67], v[192:195], v[224:227], v[64:67]
	v_mfma_f32_16x16x32_bf16 v[116:119], v[188:191], v[204:207], v[116:119]
	v_mfma_f32_16x16x32_bf16 v[112:115], v[196:199], v[204:207], v[112:115]
	v_mfma_f32_16x16x32_bf16 v[100:103], v[188:191], v[212:215], v[100:103]
	v_mfma_f32_16x16x32_bf16 v[96:99], v[196:199], v[212:215], v[96:99]
	v_mfma_f32_16x16x32_bf16 v[84:87], v[188:191], v[220:223], v[84:87]
	v_mfma_f32_16x16x32_bf16 v[80:83], v[196:199], v[220:223], v[80:83]
	v_mfma_f32_16x16x32_bf16 v[68:71], v[188:191], v[228:231], v[68:71]
	v_mfma_f32_16x16x32_bf16 v[64:67], v[196:199], v[228:231], v[64:67]
	s_setprio 0
	s_barrier
	s_add_u32 s98, s34, 0x80
	s_addc_u32 s99, s35, 0
	s_add_u32 s100, s36, 0x80
	s_addc_u32 s101, s37, 0
	s_add_i32 s65, s52, s13
	s_mov_b32 m0, s65
	ds_read_b128 v[200:203], v171 offset:16384
	ds_read_b128 v[204:207], v171 offset:17408
	ds_read_b128 v[208:211], v171 offset:18432
	ds_read_b128 v[212:215], v171 offset:19456
	ds_read_b128 v[216:219], v171 offset:20480
	ds_read_b128 v[220:223], v171 offset:21504
	ds_read_b128 v[224:227], v171 offset:22528
	ds_read_b128 v[228:231], v171 offset:23552
	global_load_lds_dwordx4 v130, s[34:35]
	s_add_i32 m0, s65, 0x2000
	s_add_u32 s66, s34, 0x40000
	s_addc_u32 s67, s35, 0
	s_add_i32 s65, s53, s13
	global_load_lds_dwordx4 v134, s[34:35]
	s_mov_b32 m0, s65
	s_nop 0
	global_load_lds_dwordx4 v130, s[66:67]
	s_add_i32 m0, s65, 0x2000
	s_nop 0
	global_load_lds_dwordx4 v134, s[66:67]
	s_waitcnt vmcnt(6)
	s_waitcnt lgkmcnt(0)
	s_barrier
	s_setprio 1
	s_waitcnt lgkmcnt(0)
	v_mfma_f32_16x16x32_bf16 v[60:63], v[146:149], v[200:203], v[60:63]
	v_mfma_f32_16x16x32_bf16 v[56:59], v[172:175], v[200:203], v[56:59]
	v_mfma_f32_16x16x32_bf16 v[44:47], v[146:149], v[208:211], v[44:47]
	v_mfma_f32_16x16x32_bf16 v[40:43], v[172:175], v[208:211], v[40:43]
	v_mfma_f32_16x16x32_bf16 v[28:31], v[146:149], v[216:219], v[28:31]
	v_mfma_f32_16x16x32_bf16 v[24:27], v[172:175], v[216:219], v[24:27]
	v_mfma_f32_16x16x32_bf16 v[12:15], v[146:149], v[224:227], v[12:15]
	v_mfma_f32_16x16x32_bf16 v[8:11], v[172:175], v[224:227], v[8:11]
	v_mfma_f32_16x16x32_bf16 v[60:63], v[150:153], v[204:207], v[60:63]
	v_mfma_f32_16x16x32_bf16 v[56:59], v[176:179], v[204:207], v[56:59]
	v_mfma_f32_16x16x32_bf16 v[44:47], v[150:153], v[212:215], v[44:47]
	v_mfma_f32_16x16x32_bf16 v[40:43], v[176:179], v[212:215], v[40:43]
	v_mfma_f32_16x16x32_bf16 v[28:31], v[150:153], v[220:223], v[28:31]
	v_mfma_f32_16x16x32_bf16 v[24:27], v[176:179], v[220:223], v[24:27]
	v_mfma_f32_16x16x32_bf16 v[12:15], v[150:153], v[228:231], v[12:15]
	v_mfma_f32_16x16x32_bf16 v[8:11], v[176:179], v[228:231], v[8:11]
	s_setprio 0
	s_setprio 1
	v_mfma_f32_16x16x32_bf16 v[52:55], v[180:183], v[200:203], v[52:55]
	v_mfma_f32_16x16x32_bf16 v[48:51], v[192:195], v[200:203], v[48:51]
	v_mfma_f32_16x16x32_bf16 v[36:39], v[180:183], v[208:211], v[36:39]
	v_mfma_f32_16x16x32_bf16 v[32:35], v[192:195], v[208:211], v[32:35]
	v_mfma_f32_16x16x32_bf16 v[20:23], v[180:183], v[216:219], v[20:23]
	v_mfma_f32_16x16x32_bf16 v[16:19], v[192:195], v[216:219], v[16:19]
	v_mfma_f32_16x16x32_bf16 v[4:7], v[180:183], v[224:227], v[4:7]
	v_mfma_f32_16x16x32_bf16 v[0:3], v[192:195], v[224:227], v[0:3]
	v_mfma_f32_16x16x32_bf16 v[52:55], v[188:191], v[204:207], v[52:55]
	v_mfma_f32_16x16x32_bf16 v[48:51], v[196:199], v[204:207], v[48:51]
	v_mfma_f32_16x16x32_bf16 v[36:39], v[188:191], v[212:215], v[36:39]
	v_mfma_f32_16x16x32_bf16 v[32:35], v[196:199], v[212:215], v[32:35]
	v_mfma_f32_16x16x32_bf16 v[20:23], v[188:191], v[220:223], v[20:23]
	v_mfma_f32_16x16x32_bf16 v[16:19], v[196:199], v[220:223], v[16:19]
	v_mfma_f32_16x16x32_bf16 v[4:7], v[188:191], v[228:231], v[4:7]
	v_mfma_f32_16x16x32_bf16 v[0:3], v[196:199], v[228:231], v[0:3]
	s_setprio 0
	s_barrier
; #define PG8_STAGE(bufoff, gbase, voff) do { _Pragma("unroll") for (int _i = 0; _i < 2; ++_i) \
;         __builtin_amdgcn_global_load_lds((const unsigned*)((const char*)(gbase) + (voff)[_i]), (PG8_LAS unsigned*)(lds + (bufoff) + ldsw + _i * 8192), 16, 0, 0); } while (0)
; #define PG8_LDA(dst, b, h) do { _Pragma("unroll") for (int m = 0; m < 4; ++m) _Pragma("unroll") for (int k = 0; k < 2; ++k) dst[m][k] = *(const PG8_LAS bf16x8*)(lds + PG8_SA(b, h) + aoff + m * 2048 + k * 1024); } while (0)
; #define PG8_LDB(dst, b, h) do { _Pragma("unroll") for (int n = 0; n < 2; ++n) _Pragma("unroll") for (int k = 0; k < 2; ++k) dst[n][k] = *(const PG8_LAS bf16x8*)(lds + PG8_SB(b, h) + boff + n * 2048 + k * 1024); } while (0)
; #define PG8_MMA(ai, bj, At, Bt) do { __builtin_amdgcn_s_setprio(1); _Pragma("unroll") for (int m = 0; m < 4; ++m) _Pragma("unroll") for (int n = 0; n < 2; ++n) _Pragma("unroll") for (int k = 0; k < 2; ++k) \
;         acc[ai][bj][m][n] = __builtin_amdgcn_mfma_f32_16x16x32_bf16(Bt[n][k], At[m][k], acc[ai][bj][m][n], 0, 0, 0); __builtin_amdgcn_s_setprio(0); } while (0)
; #define PG8_WAIT_V(n) asm volatile("s_waitcnt vmcnt(" #n ")" ::: "memory")
; #define PG8_WAIT_L(n) asm volatile("s_waitcnt lgkmcnt(" #n ")" ::: "memory")
; #define PG8_BAR __builtin_amdgcn_s_barrier()
; #define PG8_SCHED __builtin_amdgcn_sched_barrier(0)
; template <class Epi, class Sched, bool ALIGN_EPI = false, bool SP2 = false>
; __device__ __forceinline__ void gemm_phase(PG8_LAS unsigned char* lds, const Gemm g, const Sched S, const Epi E, const int tid) {
;     ...
;             PG8_LDB(B0, 1, 0); PG8_LDB(B1, 1, 1); PG8_SCHED; PG8_LDA(At, 1, 0); PG8_STAGE(PG8_SA(0, 1), a2 + hstepA, voffA);
;             PG8_WAIT_V(8); PG8_WAIT_L(0); PG8_BAR; PG8_MMA(0, 0, At, B0); PG8_MMA(0, 1, At, B1); PG8_BAR; PG8_SCHED;
;             PG8_LDA(At, 1, 1); PG8_STAGE(PG8_SB(1, 0), b3, voffB); PG8_STAGE(PG8_SB(1, 1), b3 + hstepB, voffB); PG8_STAGE(PG8_SA(1, 0), a3, voffA);
;             PG8_WAIT_V(8); PG8_WAIT_L(0); PG8_BAR; PG8_MMA(1, 0, At, B0); PG8_MMA(1, 1, At, B1); PG8_BAR; PG8_SCHED;
	s_add_i32 s65, 0, 0x18000
	s_add_i32 s66, 0, 0x1c000
	v_add_u32_e32 v176, s65, v166
	v_add_u32_e32 v187, s66, v166
	ds_read_b128 v[146:149], v176
	ds_read_b128 v[150:153], v176 offset:1024
	ds_read_b128 v[172:175], v176 offset:2048
	ds_read_b128 v[176:179], v176 offset:3072
	ds_read_b128 v[180:183], v187
	ds_read_b128 v[188:191], v187 offset:1024
	ds_read_b128 v[192:195], v187 offset:2048
	ds_read_b128 v[196:199], v187 offset:3072
	s_mov_b32 m0, s29
	s_nop 0
	global_load_lds_dwordx4 v128, s[36:37]
	s_mov_b32 m0, s47
	s_nop 0
	global_load_lds_dwordx4 v132, s[36:37]
	s_add_u32 s36, s36, 0x40000
	s_addc_u32 s37, s37, 0
	s_mov_b32 m0, s48
	ds_read_b128 v[200:203], v171 offset:32768
	ds_read_b128 v[204:207], v171 offset:33792
	ds_read_b128 v[208:211], v171 offset:34816
	ds_read_b128 v[212:215], v171 offset:35840
	ds_read_b128 v[216:219], v171 offset:36864
	ds_read_b128 v[220:223], v171 offset:37888
	ds_read_b128 v[224:227], v171 offset:38912
	ds_read_b128 v[228:231], v171 offset:39936
	global_load_lds_dwordx4 v128, s[36:37]
	s_mov_b32 m0, s49
	s_nop 0
	global_load_lds_dwordx4 v132, s[36:37]
	s_waitcnt vmcnt(8)
	s_waitcnt lgkmcnt(0)
	s_barrier
	s_setprio 1
	s_waitcnt lgkmcnt(0)
	v_mfma_f32_16x16x32_bf16 v[124:127], v[146:149], v[200:203], v[124:127]
	v_mfma_f32_16x16x32_bf16 v[120:123], v[172:175], v[200:203], v[120:123]
	v_mfma_f32_16x16x32_bf16 v[108:111], v[146:149], v[208:211], v[108:111]
	v_mfma_f32_16x16x32_bf16 v[104:107], v[172:175], v[208:211], v[104:107]
	v_mfma_f32_16x16x32_bf16 v[92:95], v[146:149], v[216:219], v[92:95]
	v_mfma_f32_16x16x32_bf16 v[88:91], v[172:175], v[216:219], v[88:91]
	v_mfma_f32_16x16x32_bf16 v[76:79], v[146:149], v[224:227], v[76:79]
	v_mfma_f32_16x16x32_bf16 v[72:75], v[172:175], v[224:227], v[72:75]
	v_mfma_f32_16x16x32_bf16 v[124:127], v[150:153], v[204:207], v[124:127]
	v_mfma_f32_16x16x32_bf16 v[120:123], v[176:179], v[204:207], v[120:123]
	v_mfma_f32_16x16x32_bf16 v[108:111], v[150:153], v[212:215], v[108:111]
	v_mfma_f32_16x16x32_bf16 v[104:107], v[176:179], v[212:215], v[104:107]
	v_mfma_f32_16x16x32_bf16 v[92:95], v[150:153], v[220:223], v[92:95]
	v_mfma_f32_16x16x32_bf16 v[88:91], v[176:179], v[220:223], v[88:91]
	v_mfma_f32_16x16x32_bf16 v[76:79], v[150:153], v[228:231], v[76:79]
	v_mfma_f32_16x16x32_bf16 v[72:75], v[176:179], v[228:231], v[72:75]
	s_setprio 0
	s_setprio 1
	v_mfma_f32_16x16x32_bf16 v[116:119], v[180:183], v[200:203], v[116:119]
	v_mfma_f32_16x16x32_bf16 v[112:115], v[192:195], v[200:203], v[112:115]
	v_mfma_f32_16x16x32_bf16 v[100:103], v[180:183], v[208:211], v[100:103]
	v_mfma_f32_16x16x32_bf16 v[96:99], v[192:195], v[208:211], v[96:99]
	v_mfma_f32_16x16x32_bf16 v[84:87], v[180:183], v[216:219], v[84:87]
	v_mfma_f32_16x16x32_bf16 v[80:83], v[192:195], v[216:219], v[80:83]
	v_mfma_f32_16x16x32_bf16 v[68:71], v[180:183], v[224:227], v[68:71]
	v_mfma_f32_16x16x32_bf16 v[64:67], v[192:195], v[224:227], v[64:67]
	v_mfma_f32_16x16x32_bf16 v[116:119], v[188:191], v[204:207], v[116:119]
	v_mfma_f32_16x16x32_bf16 v[112:115], v[196:199], v[204:207], v[112:115]
	v_mfma_f32_16x16x32_bf16 v[100:103], v[188:191], v[212:215], v[100:103]
	v_mfma_f32_16x16x32_bf16 v[96:99], v[196:199], v[212:215], v[96:99]
	v_mfma_f32_16x16x32_bf16 v[84:87], v[188:191], v[220:223], v[84:87]
	v_mfma_f32_16x16x32_bf16 v[80:83], v[196:199], v[220:223], v[80:83]
	v_mfma_f32_16x16x32_bf16 v[68:71], v[188:191], v[228:231], v[68:71]
	v_mfma_f32_16x16x32_bf16 v[64:67], v[196:199], v[228:231], v[64:67]
	s_setprio 0
	s_barrier
	s_add_i32 s36, s65, s13
	s_mov_b32 m0, s36
	ds_read_b128 v[200:203], v171 offset:49152
	ds_read_b128 v[204:207], v171 offset:50176
	ds_read_b128 v[208:211], v171 offset:51200
	ds_read_b128 v[212:215], v171 offset:52224
	ds_read_b128 v[216:219], v171 offset:53248
	ds_read_b128 v[220:223], v171 offset:54272
	ds_read_b128 v[224:227], v171 offset:55296
	ds_read_b128 v[228:231], v171 offset:56320
	global_load_lds_dwordx4 v130, s[98:99]
	s_add_i32 m0, s36, 0x2000
	s_add_u32 s34, s34, 0x40080
	s_addc_u32 s35, s35, 0
	s_add_i32 s36, s66, s13
	global_load_lds_dwordx4 v134, s[98:99]
	s_mov_b32 m0, s36
	s_nop 0
	global_load_lds_dwordx4 v130, s[34:35]
	s_add_i32 m0, s36, 0x2000
	s_nop 0
	global_load_lds_dwordx4 v134, s[34:35]
	s_mov_b32 m0, s50
	s_nop 0
	global_load_lds_dwordx4 v128, s[100:101]
	s_mov_b32 m0, s51
	s_nop 0
	global_load_lds_dwordx4 v132, s[100:101]
	s_waitcnt vmcnt(8)
	s_waitcnt lgkmcnt(0)
	s_barrier
	s_setprio 1
	s_waitcnt lgkmcnt(0)
	v_mfma_f32_16x16x32_bf16 v[60:63], v[146:149], v[200:203], v[60:63]
	v_mfma_f32_16x16x32_bf16 v[56:59], v[172:175], v[200:203], v[56:59]
	v_mfma_f32_16x16x32_bf16 v[44:47], v[146:149], v[208:211], v[44:47]
	v_mfma_f32_16x16x32_bf16 v[40:43], v[172:175], v[208:211], v[40:43]
	v_mfma_f32_16x16x32_bf16 v[28:31], v[146:149], v[216:219], v[28:31]
	v_mfma_f32_16x16x32_bf16 v[24:27], v[172:175], v[216:219], v[24:27]
	v_mfma_f32_16x16x32_bf16 v[12:15], v[146:149], v[224:227], v[12:15]
	v_mfma_f32_16x16x32_bf16 v[8:11], v[172:175], v[224:227], v[8:11]
	v_mfma_f32_16x16x32_bf16 v[60:63], v[150:153], v[204:207], v[60:63]
	v_mfma_f32_16x16x32_bf16 v[56:59], v[176:179], v[204:207], v[56:59]
	v_mfma_f32_16x16x32_bf16 v[44:47], v[150:153], v[212:215], v[44:47]
	v_mfma_f32_16x16x32_bf16 v[40:43], v[176:179], v[212:215], v[40:43]
	v_mfma_f32_16x16x32_bf16 v[28:31], v[150:153], v[220:223], v[28:31]
	v_mfma_f32_16x16x32_bf16 v[24:27], v[176:179], v[220:223], v[24:27]
	v_mfma_f32_16x16x32_bf16 v[12:15], v[150:153], v[228:231], v[12:15]
	v_mfma_f32_16x16x32_bf16 v[8:11], v[176:179], v[228:231], v[8:11]
	s_setprio 0
	s_setprio 1
	v_mfma_f32_16x16x32_bf16 v[52:55], v[180:183], v[200:203], v[52:55]
	v_mfma_f32_16x16x32_bf16 v[48:51], v[192:195], v[200:203], v[48:51]
	v_mfma_f32_16x16x32_bf16 v[36:39], v[180:183], v[208:211], v[36:39]
	v_mfma_f32_16x16x32_bf16 v[32:35], v[192:195], v[208:211], v[32:35]
	v_mfma_f32_16x16x32_bf16 v[20:23], v[180:183], v[216:219], v[20:23]
	v_mfma_f32_16x16x32_bf16 v[16:19], v[192:195], v[216:219], v[16:19]
	v_mfma_f32_16x16x32_bf16 v[4:7], v[180:183], v[224:227], v[4:7]
	v_mfma_f32_16x16x32_bf16 v[0:3], v[192:195], v[224:227], v[0:3]
	v_mfma_f32_16x16x32_bf16 v[52:55], v[188:191], v[204:207], v[52:55]
	v_mfma_f32_16x16x32_bf16 v[48:51], v[196:199], v[204:207], v[48:51]
	v_mfma_f32_16x16x32_bf16 v[36:39], v[188:191], v[212:215], v[36:39]
	v_mfma_f32_16x16x32_bf16 v[32:35], v[196:199], v[212:215], v[32:35]
	v_mfma_f32_16x16x32_bf16 v[20:23], v[188:191], v[220:223], v[20:23]
	v_mfma_f32_16x16x32_bf16 v[16:19], v[196:199], v[220:223], v[16:19]
	v_mfma_f32_16x16x32_bf16 v[4:7], v[188:191], v[228:231], v[4:7]
	v_mfma_f32_16x16x32_bf16 v[0:3], v[196:199], v[228:231], v[0:3]
	s_setprio 0
	s_barrier
	s_add_i32 s64, s64, 2
	s_add_u32 s30, s30, 0x100
	s_addc_u32 s31, s31, 0
	s_add_u32 s62, s62, 0x100
	s_addc_u32 s63, s63, 0
	s_cmp_gt_u32 s64, 13
	s_cbranch_scc0 .LBB0_1196
	s_and_b64 vcc, exec, s[10:11]
	s_cbranch_vccz .LBB0_1199
	s_barrier

; #define PG8_STAGE(bufoff, gbase, voff) do { _Pragma("unroll") for (int _i = 0; _i < 2; ++_i) \
;         __builtin_amdgcn_global_load_lds((const unsigned*)((const char*)(gbase) + (voff)[_i]), (PG8_LAS unsigned*)(lds + (bufoff) + ldsw + _i * 8192), 16, 0, 0); } while (0)
; #define PG8_LDA(dst, b, h) do { _Pragma("unroll") for (int m = 0; m < 4; ++m) _Pragma("unroll") for (int k = 0; k < 2; ++k) dst[m][k] = *(const PG8_LAS bf16x8*)(lds + PG8_SA(b, h) + aoff + m * 2048 + k * 1024); } while (0)
; #define PG8_LDB(dst, b, h) do { _Pragma("unroll") for (int n = 0; n < 2; ++n) _Pragma("unroll") for (int k = 0; k < 2; ++k) dst[n][k] = *(const PG8_LAS bf16x8*)(lds + PG8_SB(b, h) + boff + n * 2048 + k * 1024); } while (0)
; #define PG8_MMA(ai, bj, At, Bt) do { __builtin_amdgcn_s_setprio(1); _Pragma("unroll") for (int m = 0; m < 4; ++m) _Pragma("unroll") for (int n = 0; n < 2; ++n) _Pragma("unroll") for (int k = 0; k < 2; ++k) \
;         acc[ai][bj][m][n] = __builtin_amdgcn_mfma_f32_16x16x32_bf16(Bt[n][k], At[m][k], acc[ai][bj][m][n], 0, 0, 0); __builtin_amdgcn_s_setprio(0); } while (0)
; #define PG8_WAIT_V(n) asm volatile("s_waitcnt vmcnt(" #n ")" ::: "memory")
; #define PG8_WAIT_L(n) asm volatile("s_waitcnt lgkmcnt(" #n ")" ::: "memory")
; template <class Epi, class Sched, bool ALIGN_EPI = false, bool SP2 = false>
; __device__ __forceinline__ void gemm_phase(PG8_LAS unsigned char* lds, const Gemm g, const Sched S, const Epi E, const int tid) {
;     ...
;             const bool last = (t == nt - 2);
;             const char* a1 = cA + (size_t)(t + 1) * kstep;
;             const char* a2 = last ? nA : cA + (size_t)(t + 2) * kstep; const char* b2 = last ? nB : cB + (size_t)(t + 2) * kstep;
;             const char* a3 = a2 + kstep; const char* b3 = b2 + kstep;
;             if (last && has_next) S.a_ready(nxt);
;             if constexpr (SP2) {
;             PG8_LDB(B0, 0, 0); PG8_LDB(B1, 0, 1); PG8_SCHED; PG8_LDA(At, 0, 0); PG8_STAGE(PG8_SA(1, 1), a1 + hstepA, voffA);
;             PG8_WAIT_V(8); PG8_WAIT_L(0); PG8_BAR; PG8_MMA(0, 0, At, B0); PG8_MMA(0, 1, At, B1); PG8_BAR; PG8_SCHED;
;             PG8_LDA(At, 0, 1); PG8_STAGE(PG8_SB(0, 0), b2, voffB); PG8_STAGE(PG8_SB(0, 1), b2 + hstepB, voffB); PG8_STAGE(PG8_SA(0, 0), a2, voffA);
;             PG8_WAIT_V(8); PG8_WAIT_L(0); PG8_BAR; PG8_MMA(1, 0, At, B0); PG8_MMA(1, 1, At, B1); PG8_BAR; PG8_SCHED;
.LBB0_1239:
	ds_read_b128 v[150:153], v147
	ds_read_b128 v[166:169], v147 offset:1024
	ds_read_b128 v[170:173], v147 offset:2048
	ds_read_b128 v[174:177], v147 offset:3072
	ds_read_b128 v[178:181], v148
	ds_read_b128 v[182:185], v148 offset:1024
	ds_read_b128 v[188:191], v148 offset:2048
	ds_read_b128 v[192:195], v148 offset:3072
	s_add_u32 s52, s50, 0xfffc0080
	s_addc_u32 s53, s51, -1
	s_cmp_eq_u32 s79, 12
	s_cselect_b32 s55, s37, s53
	s_cselect_b32 s54, s75, s52
	s_cselect_b32 s53, s35, s78
	s_cselect_b32 s52, s76, s77
	s_add_i32 m0, s49, 0xc000
	ds_read_b128 v[196:199], v149
	ds_read_b128 v[200:203], v149 offset:1024
	ds_read_b128 v[204:207], v149 offset:2048
	ds_read_b128 v[208:211], v149 offset:3072
	ds_read_b128 v[212:215], v149 offset:4096
	ds_read_b128 v[216:219], v149 offset:5120
	ds_read_b128 v[220:223], v149 offset:6144
	ds_read_b128 v[224:227], v149 offset:7168
	global_load_lds_dwordx4 v138, s[50:51]
	s_add_i32 m0, s49, 0xe000
	s_nop 0
	global_load_lds_dwordx4 v140, s[50:51]
	s_waitcnt vmcnt(8)
	s_waitcnt lgkmcnt(0)
	s_barrier
	s_setprio 1
	s_waitcnt lgkmcnt(0)
	v_mfma_f32_16x16x32_bf16 v[124:127], v[150:153], v[196:199], v[124:127]
	v_mfma_f32_16x16x32_bf16 v[120:123], v[170:173], v[196:199], v[120:123]
	v_mfma_f32_16x16x32_bf16 v[112:115], v[150:153], v[204:207], v[112:115]
	v_mfma_f32_16x16x32_bf16 v[104:107], v[170:173], v[204:207], v[104:107]
	v_mfma_f32_16x16x32_bf16 v[96:99], v[150:153], v[212:215], v[96:99]
	v_mfma_f32_16x16x32_bf16 v[88:91], v[170:173], v[212:215], v[88:91]
	v_mfma_f32_16x16x32_bf16 v[80:83], v[150:153], v[220:223], v[80:83]
	v_mfma_f32_16x16x32_bf16 v[72:75], v[170:173], v[220:223], v[72:75]
	v_mfma_f32_16x16x32_bf16 v[124:127], v[166:169], v[200:203], v[124:127]
	v_mfma_f32_16x16x32_bf16 v[120:123], v[174:177], v[200:203], v[120:123]
	v_mfma_f32_16x16x32_bf16 v[112:115], v[166:169], v[208:211], v[112:115]
	v_mfma_f32_16x16x32_bf16 v[104:107], v[174:177], v[208:211], v[104:107]
	v_mfma_f32_16x16x32_bf16 v[96:99], v[166:169], v[216:219], v[96:99]
	v_mfma_f32_16x16x32_bf16 v[88:91], v[174:177], v[216:219], v[88:91]
	v_mfma_f32_16x16x32_bf16 v[80:83], v[166:169], v[224:227], v[80:83]
	v_mfma_f32_16x16x32_bf16 v[72:75], v[174:177], v[224:227], v[72:75]
	s_setprio 0
	s_setprio 1
	v_mfma_f32_16x16x32_bf16 v[116:119], v[178:181], v[196:199], v[116:119]
	v_mfma_f32_16x16x32_bf16 v[108:111], v[188:191], v[196:199], v[108:111]
	v_mfma_f32_16x16x32_bf16 v[100:103], v[178:181], v[204:207], v[100:103]
	v_mfma_f32_16x16x32_bf16 v[92:95], v[188:191], v[204:207], v[92:95]
	v_mfma_f32_16x16x32_bf16 v[84:87], v[178:181], v[212:215], v[84:87]
	v_mfma_f32_16x16x32_bf16 v[76:79], v[188:191], v[212:215], v[76:79]
	v_mfma_f32_16x16x32_bf16 v[68:71], v[178:181], v[220:223], v[68:71]
	v_mfma_f32_16x16x32_bf16 v[64:67], v[188:191], v[220:223], v[64:67]
	v_mfma_f32_16x16x32_bf16 v[116:119], v[182:185], v[200:203], v[116:119]
	v_mfma_f32_16x16x32_bf16 v[108:111], v[192:195], v[200:203], v[108:111]
	v_mfma_f32_16x16x32_bf16 v[100:103], v[182:185], v[208:211], v[100:103]
	v_mfma_f32_16x16x32_bf16 v[92:95], v[192:195], v[208:211], v[92:95]
	v_mfma_f32_16x16x32_bf16 v[84:87], v[182:185], v[216:219], v[84:87]
	v_mfma_f32_16x16x32_bf16 v[76:79], v[192:195], v[216:219], v[76:79]
	v_mfma_f32_16x16x32_bf16 v[68:71], v[182:185], v[224:227], v[68:71]
	v_mfma_f32_16x16x32_bf16 v[64:67], v[192:195], v[224:227], v[64:67]
	s_setprio 0
	s_barrier
	s_add_u32 s98, s52, 0x80
	s_addc_u32 s99, s53, 0
	s_add_u32 s100, s54, 0x80
	s_addc_u32 s101, s55, 0
	s_add_i32 s80, s72, s64
	s_mov_b32 m0, s80
	ds_read_b128 v[196:199], v149 offset:16384
	ds_read_b128 v[200:203], v149 offset:17408
	ds_read_b128 v[204:207], v149 offset:18432
	ds_read_b128 v[208:211], v149 offset:19456
	ds_read_b128 v[212:215], v149 offset:20480
	ds_read_b128 v[216:219], v149 offset:21504
	ds_read_b128 v[220:223], v149 offset:22528
	ds_read_b128 v[224:227], v149 offset:23552
	global_load_lds_dwordx4 v130, s[52:53]
	s_add_i32 m0, s80, 0x2000
	s_add_u32 s80, s52, 0x40000
	s_addc_u32 s81, s53, 0
	s_add_i32 s82, s73, s64
	global_load_lds_dwordx4 v134, s[52:53]
	s_mov_b32 m0, s82
	s_nop 0
	global_load_lds_dwordx4 v130, s[80:81]
	s_add_i32 m0, s82, 0x2000
	s_nop 0
	global_load_lds_dwordx4 v134, s[80:81]
	s_waitcnt vmcnt(6)
	s_waitcnt lgkmcnt(0)
	s_barrier
	s_setprio 1
	s_waitcnt lgkmcnt(0)
	v_mfma_f32_16x16x32_bf16 v[60:63], v[150:153], v[196:199], v[60:63]
	v_mfma_f32_16x16x32_bf16 v[56:59], v[170:173], v[196:199], v[56:59]
	v_mfma_f32_16x16x32_bf16 v[52:55], v[150:153], v[204:207], v[52:55]
	v_mfma_f32_16x16x32_bf16 v[44:47], v[170:173], v[204:207], v[44:47]
	v_mfma_f32_16x16x32_bf16 v[36:39], v[150:153], v[212:215], v[36:39]
	v_mfma_f32_16x16x32_bf16 v[28:31], v[170:173], v[212:215], v[28:31]
	v_mfma_f32_16x16x32_bf16 v[20:23], v[150:153], v[220:223], v[20:23]
	v_mfma_f32_16x16x32_bf16 v[12:15], v[170:173], v[220:223], v[12:15]
	v_mfma_f32_16x16x32_bf16 v[60:63], v[166:169], v[200:203], v[60:63]
	v_mfma_f32_16x16x32_bf16 v[56:59], v[174:177], v[200:203], v[56:59]
	v_mfma_f32_16x16x32_bf16 v[52:55], v[166:169], v[208:211], v[52:55]
	v_mfma_f32_16x16x32_bf16 v[44:47], v[174:177], v[208:211], v[44:47]
	v_mfma_f32_16x16x32_bf16 v[36:39], v[166:169], v[216:219], v[36:39]
	v_mfma_f32_16x16x32_bf16 v[28:31], v[174:177], v[216:219], v[28:31]
	v_mfma_f32_16x16x32_bf16 v[20:23], v[166:169], v[224:227], v[20:23]
	v_mfma_f32_16x16x32_bf16 v[12:15], v[174:177], v[224:227], v[12:15]
	s_setprio 0
	s_setprio 1
	v_mfma_f32_16x16x32_bf16 v[48:51], v[178:181], v[196:199], v[48:51]
	v_mfma_f32_16x16x32_bf16 v[40:43], v[188:191], v[196:199], v[40:43]
	v_mfma_f32_16x16x32_bf16 v[32:35], v[178:181], v[204:207], v[32:35]
	v_mfma_f32_16x16x32_bf16 v[24:27], v[188:191], v[204:207], v[24:27]
	v_mfma_f32_16x16x32_bf16 v[16:19], v[178:181], v[212:215], v[16:19]
	v_mfma_f32_16x16x32_bf16 v[8:11], v[188:191], v[212:215], v[8:11]
	v_mfma_f32_16x16x32_bf16 v[4:7], v[178:181], v[220:223], v[4:7]
	v_mfma_f32_16x16x32_bf16 v[0:3], v[188:191], v[220:223], v[0:3]
	v_mfma_f32_16x16x32_bf16 v[48:51], v[182:185], v[200:203], v[48:51]
	v_mfma_f32_16x16x32_bf16 v[40:43], v[192:195], v[200:203], v[40:43]
	v_mfma_f32_16x16x32_bf16 v[32:35], v[182:185], v[208:211], v[32:35]
	v_mfma_f32_16x16x32_bf16 v[24:27], v[192:195], v[208:211], v[24:27]
	v_mfma_f32_16x16x32_bf16 v[16:19], v[182:185], v[216:219], v[16:19]
	v_mfma_f32_16x16x32_bf16 v[8:11], v[192:195], v[216:219], v[8:11]
	v_mfma_f32_16x16x32_bf16 v[4:7], v[182:185], v[224:227], v[4:7]
	v_mfma_f32_16x16x32_bf16 v[0:3], v[192:195], v[224:227], v[0:3]
	s_setprio 0
	s_barrier
; #define PG8_STAGE(bufoff, gbase, voff) do { _Pragma("unroll") for (int _i = 0; _i < 2; ++_i) \
;         __builtin_amdgcn_global_load_lds((const unsigned*)((const char*)(gbase) + (voff)[_i]), (PG8_LAS unsigned*)(lds + (bufoff) + ldsw + _i * 8192), 16, 0, 0); } while (0)
; #define PG8_LDA(dst, b, h) do { _Pragma("unroll") for (int m = 0; m < 4; ++m) _Pragma("unroll") for (int k = 0; k < 2; ++k) dst[m][k] = *(const PG8_LAS bf16x8*)(lds + PG8_SA(b, h) + aoff + m * 2048 + k * 1024); } while (0)
; #define PG8_LDB(dst, b, h) do { _Pragma("unroll") for (int n = 0; n < 2; ++n) _Pragma("unroll") for (int k = 0; k < 2; ++k) dst[n][k] = *(const PG8_LAS bf16x8*)(lds + PG8_SB(b, h) + boff + n * 2048 + k * 1024); } while (0)
; #define PG8_MMA(ai, bj, At, Bt) do { __builtin_amdgcn_s_setprio(1); _Pragma("unroll") for (int m = 0; m < 4; ++m) _Pragma("unroll") for (int n = 0; n < 2; ++n) _Pragma("unroll") for (int k = 0; k < 2; ++k) \
;         acc[ai][bj][m][n] = __builtin_amdgcn_mfma_f32_16x16x32_bf16(Bt[n][k], At[m][k], acc[ai][bj][m][n], 0, 0, 0); __builtin_amdgcn_s_setprio(0); } while (0)
; #define PG8_WAIT_V(n) asm volatile("s_waitcnt vmcnt(" #n ")" ::: "memory")
; #define PG8_WAIT_L(n) asm volatile("s_waitcnt lgkmcnt(" #n ")" ::: "memory")
; #define PG8_BAR __builtin_amdgcn_s_barrier()
; #define PG8_SCHED __builtin_amdgcn_sched_barrier(0)
; template <class Epi, class Sched, bool ALIGN_EPI = false, bool SP2 = false>
; __device__ __forceinline__ void gemm_phase(PG8_LAS unsigned char* lds, const Gemm g, const Sched S, const Epi E, const int tid) {
;     ...
;             PG8_LDB(B0, 1, 0); PG8_LDB(B1, 1, 1); PG8_SCHED; PG8_LDA(At, 1, 0); PG8_STAGE(PG8_SA(0, 1), a2 + hstepA, voffA);
;             PG8_WAIT_V(8); PG8_WAIT_L(0); PG8_BAR; PG8_MMA(0, 0, At, B0); PG8_MMA(0, 1, At, B1); PG8_BAR; PG8_SCHED;
;             PG8_LDA(At, 1, 1); PG8_STAGE(PG8_SB(1, 0), b3, voffB); PG8_STAGE(PG8_SB(1, 1), b3 + hstepB, voffB); PG8_STAGE(PG8_SA(1, 0), a3, voffA);
;             PG8_WAIT_V(8); PG8_WAIT_L(0); PG8_BAR; PG8_MMA(1, 0, At, B0); PG8_MMA(1, 1, At, B1); PG8_BAR; PG8_SCHED;
	s_add_i32 s80, 0, 0x18000
	v_add_u32_e32 v165, s80, v145
	s_add_i32 s81, 0, 0x1c000
	ds_read_b128 v[150:153], v165
	ds_read_b128 v[166:169], v165 offset:1024
	ds_read_b128 v[170:173], v165 offset:2048
	ds_read_b128 v[174:177], v165 offset:3072
	v_add_u32_e32 v165, s81, v145
	ds_read_b128 v[178:181], v165
	ds_read_b128 v[182:185], v165 offset:1024
	ds_read_b128 v[188:191], v165 offset:2048
	ds_read_b128 v[192:195], v165 offset:3072
	s_mov_b32 m0, s49
	s_nop 0
	global_load_lds_dwordx4 v128, s[54:55]
	s_mov_b32 m0, s65
	s_nop 0
	global_load_lds_dwordx4 v132, s[54:55]
	s_add_u32 s54, s54, 0x40000
	s_addc_u32 s55, s55, 0
	s_mov_b32 m0, s66
	ds_read_b128 v[196:199], v149 offset:32768
	ds_read_b128 v[200:203], v149 offset:33792
	ds_read_b128 v[204:207], v149 offset:34816
	ds_read_b128 v[208:211], v149 offset:35840
	ds_read_b128 v[212:215], v149 offset:36864
	ds_read_b128 v[216:219], v149 offset:37888
	ds_read_b128 v[220:223], v149 offset:38912
	ds_read_b128 v[224:227], v149 offset:39936
	global_load_lds_dwordx4 v128, s[54:55]
	s_mov_b32 m0, s67
	s_nop 0
	global_load_lds_dwordx4 v132, s[54:55]
	s_waitcnt vmcnt(8)
	s_waitcnt lgkmcnt(0)
	s_barrier
	s_setprio 1
	s_waitcnt lgkmcnt(0)
	v_mfma_f32_16x16x32_bf16 v[124:127], v[150:153], v[196:199], v[124:127]
	v_mfma_f32_16x16x32_bf16 v[120:123], v[170:173], v[196:199], v[120:123]
	v_mfma_f32_16x16x32_bf16 v[112:115], v[150:153], v[204:207], v[112:115]
	v_mfma_f32_16x16x32_bf16 v[104:107], v[170:173], v[204:207], v[104:107]
	v_mfma_f32_16x16x32_bf16 v[96:99], v[150:153], v[212:215], v[96:99]
	v_mfma_f32_16x16x32_bf16 v[88:91], v[170:173], v[212:215], v[88:91]
	v_mfma_f32_16x16x32_bf16 v[80:83], v[150:153], v[220:223], v[80:83]
	v_mfma_f32_16x16x32_bf16 v[72:75], v[170:173], v[220:223], v[72:75]
	v_mfma_f32_16x16x32_bf16 v[124:127], v[166:169], v[200:203], v[124:127]
	v_mfma_f32_16x16x32_bf16 v[120:123], v[174:177], v[200:203], v[120:123]
	v_mfma_f32_16x16x32_bf16 v[112:115], v[166:169], v[208:211], v[112:115]
	v_mfma_f32_16x16x32_bf16 v[104:107], v[174:177], v[208:211], v[104:107]
	v_mfma_f32_16x16x32_bf16 v[96:99], v[166:169], v[216:219], v[96:99]
	v_mfma_f32_16x16x32_bf16 v[88:91], v[174:177], v[216:219], v[88:91]
	v_mfma_f32_16x16x32_bf16 v[80:83], v[166:169], v[224:227], v[80:83]
	v_mfma_f32_16x16x32_bf16 v[72:75], v[174:177], v[224:227], v[72:75]
	s_setprio 0
	s_setprio 1
	v_mfma_f32_16x16x32_bf16 v[116:119], v[178:181], v[196:199], v[116:119]
	v_mfma_f32_16x16x32_bf16 v[108:111], v[188:191], v[196:199], v[108:111]
	v_mfma_f32_16x16x32_bf16 v[100:103], v[178:181], v[204:207], v[100:103]
	v_mfma_f32_16x16x32_bf16 v[92:95], v[188:191], v[204:207], v[92:95]
	v_mfma_f32_16x16x32_bf16 v[84:87], v[178:181], v[212:215], v[84:87]
	v_mfma_f32_16x16x32_bf16 v[76:79], v[188:191], v[212:215], v[76:79]
	v_mfma_f32_16x16x32_bf16 v[68:71], v[178:181], v[220:223], v[68:71]
	v_mfma_f32_16x16x32_bf16 v[64:67], v[188:191], v[220:223], v[64:67]
	v_mfma_f32_16x16x32_bf16 v[116:119], v[182:185], v[200:203], v[116:119]
	v_mfma_f32_16x16x32_bf16 v[108:111], v[192:195], v[200:203], v[108:111]
	v_mfma_f32_16x16x32_bf16 v[100:103], v[182:185], v[208:211], v[100:103]
	v_mfma_f32_16x16x32_bf16 v[92:95], v[192:195], v[208:211], v[92:95]
	v_mfma_f32_16x16x32_bf16 v[84:87], v[182:185], v[216:219], v[84:87]
	v_mfma_f32_16x16x32_bf16 v[76:79], v[192:195], v[216:219], v[76:79]
	v_mfma_f32_16x16x32_bf16 v[68:71], v[182:185], v[224:227], v[68:71]
	v_mfma_f32_16x16x32_bf16 v[64:67], v[192:195], v[224:227], v[64:67]
	s_setprio 0
	s_barrier
	s_add_i32 s54, s80, s64
	s_mov_b32 m0, s54
	ds_read_b128 v[196:199], v149 offset:49152
	ds_read_b128 v[200:203], v149 offset:50176
	ds_read_b128 v[204:207], v149 offset:51200
	ds_read_b128 v[208:211], v149 offset:52224
	ds_read_b128 v[212:215], v149 offset:53248
	ds_read_b128 v[216:219], v149 offset:54272
	ds_read_b128 v[220:223], v149 offset:55296
	ds_read_b128 v[224:227], v149 offset:56320
	global_load_lds_dwordx4 v130, s[98:99]
	s_add_i32 m0, s54, 0x2000
	s_add_u32 s52, s52, 0x40080
	s_addc_u32 s53, s53, 0
	s_add_i32 s54, s81, s64
	global_load_lds_dwordx4 v134, s[98:99]
	s_mov_b32 m0, s54
	s_nop 0
	global_load_lds_dwordx4 v130, s[52:53]
	s_add_i32 m0, s54, 0x2000
	s_nop 0
	global_load_lds_dwordx4 v134, s[52:53]
	s_mov_b32 m0, s70
	s_nop 0
	global_load_lds_dwordx4 v128, s[100:101]
	s_mov_b32 m0, s71
	s_nop 0
	global_load_lds_dwordx4 v132, s[100:101]
	s_waitcnt vmcnt(8)
	s_waitcnt lgkmcnt(0)
	s_barrier
	s_setprio 1
	s_waitcnt lgkmcnt(0)
	v_mfma_f32_16x16x32_bf16 v[60:63], v[150:153], v[196:199], v[60:63]
	v_mfma_f32_16x16x32_bf16 v[56:59], v[170:173], v[196:199], v[56:59]
	v_mfma_f32_16x16x32_bf16 v[52:55], v[150:153], v[204:207], v[52:55]
	v_mfma_f32_16x16x32_bf16 v[44:47], v[170:173], v[204:207], v[44:47]
	v_mfma_f32_16x16x32_bf16 v[36:39], v[150:153], v[212:215], v[36:39]
	v_mfma_f32_16x16x32_bf16 v[28:31], v[170:173], v[212:215], v[28:31]
	v_mfma_f32_16x16x32_bf16 v[20:23], v[150:153], v[220:223], v[20:23]
	v_mfma_f32_16x16x32_bf16 v[12:15], v[170:173], v[220:223], v[12:15]
	v_mfma_f32_16x16x32_bf16 v[60:63], v[166:169], v[200:203], v[60:63]
	v_mfma_f32_16x16x32_bf16 v[56:59], v[174:177], v[200:203], v[56:59]
	v_mfma_f32_16x16x32_bf16 v[52:55], v[166:169], v[208:211], v[52:55]
	v_mfma_f32_16x16x32_bf16 v[44:47], v[174:177], v[208:211], v[44:47]
	v_mfma_f32_16x16x32_bf16 v[36:39], v[166:169], v[216:219], v[36:39]
	v_mfma_f32_16x16x32_bf16 v[28:31], v[174:177], v[216:219], v[28:31]
	v_mfma_f32_16x16x32_bf16 v[20:23], v[166:169], v[224:227], v[20:23]
	v_mfma_f32_16x16x32_bf16 v[12:15], v[174:177], v[224:227], v[12:15]
	s_setprio 0
	s_setprio 1
	v_mfma_f32_16x16x32_bf16 v[48:51], v[178:181], v[196:199], v[48:51]
	v_mfma_f32_16x16x32_bf16 v[40:43], v[188:191], v[196:199], v[40:43]
	v_mfma_f32_16x16x32_bf16 v[32:35], v[178:181], v[204:207], v[32:35]
	v_mfma_f32_16x16x32_bf16 v[24:27], v[188:191], v[204:207], v[24:27]
	v_mfma_f32_16x16x32_bf16 v[16:19], v[178:181], v[212:215], v[16:19]
	v_mfma_f32_16x16x32_bf16 v[8:11], v[188:191], v[212:215], v[8:11]
	v_mfma_f32_16x16x32_bf16 v[4:7], v[178:181], v[220:223], v[4:7]
	v_mfma_f32_16x16x32_bf16 v[0:3], v[188:191], v[220:223], v[0:3]
	v_mfma_f32_16x16x32_bf16 v[48:51], v[182:185], v[200:203], v[48:51]
	v_mfma_f32_16x16x32_bf16 v[40:43], v[192:195], v[200:203], v[40:43]
	v_mfma_f32_16x16x32_bf16 v[32:35], v[182:185], v[208:211], v[32:35]
	v_mfma_f32_16x16x32_bf16 v[24:27], v[192:195], v[208:211], v[24:27]
	v_mfma_f32_16x16x32_bf16 v[16:19], v[182:185], v[216:219], v[16:19]
	v_mfma_f32_16x16x32_bf16 v[8:11], v[192:195], v[216:219], v[8:11]
	v_mfma_f32_16x16x32_bf16 v[4:7], v[182:185], v[224:227], v[4:7]
	v_mfma_f32_16x16x32_bf16 v[0:3], v[192:195], v[224:227], v[0:3]
	s_setprio 0
	s_barrier
	s_add_i32 s79, s79, 2
	s_add_u32 s50, s50, 0x100
	s_addc_u32 s51, s51, 0
	s_add_u32 s77, s77, 0x100
	s_addc_u32 s78, s78, 0
	s_cmp_gt_u32 s79, 13
	s_cbranch_scc0 .LBB0_1239
	s_and_b64 vcc, exec, s[10:11]
	s_cbranch_vccz .LBB0_1242
	s_barrier

; #define PG8_STAGE(bufoff, gbase, voff) do { _Pragma("unroll") for (int _i = 0; _i < 2; ++_i) \
;         __builtin_amdgcn_global_load_lds((const unsigned*)((const char*)(gbase) + (voff)[_i]), (PG8_LAS unsigned*)(lds + (bufoff) + ldsw + _i * 8192), 16, 0, 0); } while (0)
; #define PG8_LDA(dst, b, h) do { _Pragma("unroll") for (int m = 0; m < 4; ++m) _Pragma("unroll") for (int k = 0; k < 2; ++k) dst[m][k] = *(const PG8_LAS bf16x8*)(lds + PG8_SA(b, h) + aoff + m * 2048 + k * 1024); } while (0)
; #define PG8_LDB(dst, b, h) do { _Pragma("unroll") for (int n = 0; n < 2; ++n) _Pragma("unroll") for (int k = 0; k < 2; ++k) dst[n][k] = *(const PG8_LAS bf16x8*)(lds + PG8_SB(b, h) + boff + n * 2048 + k * 1024); } while (0)
; #define PG8_MMA(ai, bj, At, Bt) do { __builtin_amdgcn_s_setprio(1); _Pragma("unroll") for (int m = 0; m < 4; ++m) _Pragma("unroll") for (int n = 0; n < 2; ++n) _Pragma("unroll") for (int k = 0; k < 2; ++k) \
;         acc[ai][bj][m][n] = __builtin_amdgcn_mfma_f32_16x16x32_bf16(Bt[n][k], At[m][k], acc[ai][bj][m][n], 0, 0, 0); __builtin_amdgcn_s_setprio(0); } while (0)
; #define PG8_WAIT_V(n) asm volatile("s_waitcnt vmcnt(" #n ")" ::: "memory")
; #define PG8_WAIT_L(n) asm volatile("s_waitcnt lgkmcnt(" #n ")" ::: "memory")
; #define PG8_BAR __builtin_amdgcn_s_barrier()
; #define PG8_SCHED __builtin_amdgcn_sched_barrier(0)
; template <class Epi, class Sched, bool ALIGN_EPI = false, bool SP2 = false>
; __device__ __forceinline__ void gemm_phase(PG8_LAS unsigned char* lds, const Gemm g, const Sched S, const Epi E, const int tid) {
;     ...
;             PG8_LDB(B0, 0, 0); PG8_LDB(B1, 0, 1); PG8_SCHED; PG8_LDA(At, 0, 0); PG8_STAGE(PG8_SA(1, 1), a1 + hstepA, voffA);
;             PG8_WAIT_V(8); PG8_WAIT_L(0); PG8_BAR; PG8_MMA(0, 0, At, B0); PG8_MMA(0, 1, At, B1); PG8_BAR; PG8_SCHED;
;             PG8_LDA(At, 0, 1); PG8_STAGE(PG8_SB(0, 0), b2, voffB); PG8_STAGE(PG8_SB(0, 1), b2 + hstepB, voffB); PG8_STAGE(PG8_SA(0, 0), a2, voffA);
;             PG8_WAIT_V(8); PG8_WAIT_L(0); PG8_BAR; PG8_MMA(1, 0, At, B0); PG8_MMA(1, 1, At, B1); PG8_BAR; PG8_SCHED;
.LBB0_1255:
	ds_read_b128 v[148:151], v145
	ds_read_b128 v[152:155], v145 offset:1024
	ds_read_b128 v[156:159], v145 offset:2048
	ds_read_b128 v[160:163], v145 offset:3072
	ds_read_b128 v[164:167], v146
	ds_read_b128 v[168:171], v146 offset:1024
	ds_read_b128 v[172:175], v146 offset:2048
	ds_read_b128 v[176:179], v146 offset:3072
	s_add_u32 s52, s50, 0xfffc0080
	s_addc_u32 s53, s51, -1
	s_cmp_eq_u32 s76, 12
	s_cselect_b32 s55, s37, s53
	s_cselect_b32 s54, s72, s52
	s_cselect_b32 s53, s35, s75
	s_cselect_b32 s52, s73, s74
	s_add_i32 m0, s49, 0xc000
	ds_read_b128 v[180:183], v147
	ds_read_b128 v[188:191], v147 offset:1024
	ds_read_b128 v[192:195], v147 offset:2048
	ds_read_b128 v[196:199], v147 offset:3072
	ds_read_b128 v[200:203], v147 offset:4096
	ds_read_b128 v[204:207], v147 offset:5120
	ds_read_b128 v[208:211], v147 offset:6144
	ds_read_b128 v[212:215], v147 offset:7168
	global_load_lds_dwordx4 v136, s[50:51]
	s_add_i32 m0, s49, 0xe000
	s_nop 0
	global_load_lds_dwordx4 v138, s[50:51]
	s_waitcnt vmcnt(8)
	s_waitcnt lgkmcnt(0)
	s_barrier
	s_setprio 1
	s_waitcnt lgkmcnt(0)
	v_mfma_f32_16x16x32_bf16 v[124:127], v[148:151], v[180:183], v[124:127]
	v_mfma_f32_16x16x32_bf16 v[120:123], v[156:159], v[180:183], v[120:123]
	v_mfma_f32_16x16x32_bf16 v[112:115], v[148:151], v[192:195], v[112:115]
	v_mfma_f32_16x16x32_bf16 v[104:107], v[156:159], v[192:195], v[104:107]
	v_mfma_f32_16x16x32_bf16 v[96:99], v[148:151], v[200:203], v[96:99]
	v_mfma_f32_16x16x32_bf16 v[88:91], v[156:159], v[200:203], v[88:91]
	v_mfma_f32_16x16x32_bf16 v[80:83], v[148:151], v[208:211], v[80:83]
	v_mfma_f32_16x16x32_bf16 v[72:75], v[156:159], v[208:211], v[72:75]
	v_mfma_f32_16x16x32_bf16 v[124:127], v[152:155], v[188:191], v[124:127]
	v_mfma_f32_16x16x32_bf16 v[120:123], v[160:163], v[188:191], v[120:123]
	v_mfma_f32_16x16x32_bf16 v[112:115], v[152:155], v[196:199], v[112:115]
	v_mfma_f32_16x16x32_bf16 v[104:107], v[160:163], v[196:199], v[104:107]
	v_mfma_f32_16x16x32_bf16 v[96:99], v[152:155], v[204:207], v[96:99]
	v_mfma_f32_16x16x32_bf16 v[88:91], v[160:163], v[204:207], v[88:91]
	v_mfma_f32_16x16x32_bf16 v[80:83], v[152:155], v[212:215], v[80:83]
	v_mfma_f32_16x16x32_bf16 v[72:75], v[160:163], v[212:215], v[72:75]
	s_setprio 0
	s_setprio 1
	v_mfma_f32_16x16x32_bf16 v[116:119], v[164:167], v[180:183], v[116:119]
	v_mfma_f32_16x16x32_bf16 v[108:111], v[172:175], v[180:183], v[108:111]
	v_mfma_f32_16x16x32_bf16 v[100:103], v[164:167], v[192:195], v[100:103]
	v_mfma_f32_16x16x32_bf16 v[92:95], v[172:175], v[192:195], v[92:95]
	v_mfma_f32_16x16x32_bf16 v[84:87], v[164:167], v[200:203], v[84:87]
	v_mfma_f32_16x16x32_bf16 v[76:79], v[172:175], v[200:203], v[76:79]
	v_mfma_f32_16x16x32_bf16 v[68:71], v[164:167], v[208:211], v[68:71]
	v_mfma_f32_16x16x32_bf16 v[64:67], v[172:175], v[208:211], v[64:67]
	v_mfma_f32_16x16x32_bf16 v[116:119], v[168:171], v[188:191], v[116:119]
	v_mfma_f32_16x16x32_bf16 v[108:111], v[176:179], v[188:191], v[108:111]
	v_mfma_f32_16x16x32_bf16 v[100:103], v[168:171], v[196:199], v[100:103]
	v_mfma_f32_16x16x32_bf16 v[92:95], v[176:179], v[196:199], v[92:95]
	v_mfma_f32_16x16x32_bf16 v[84:87], v[168:171], v[204:207], v[84:87]
	v_mfma_f32_16x16x32_bf16 v[76:79], v[176:179], v[204:207], v[76:79]
	v_mfma_f32_16x16x32_bf16 v[68:71], v[168:171], v[212:215], v[68:71]
	v_mfma_f32_16x16x32_bf16 v[64:67], v[176:179], v[212:215], v[64:67]
	s_setprio 0
	s_barrier
	s_add_u32 s98, s52, 0x80
	s_addc_u32 s99, s53, 0
	s_add_u32 s100, s54, 0x80
	s_addc_u32 s101, s55, 0
	s_add_i32 s77, s69, s61
	s_mov_b32 m0, s77
	ds_read_b128 v[180:183], v147 offset:16384
	ds_read_b128 v[188:191], v147 offset:17408
	ds_read_b128 v[192:195], v147 offset:18432
	ds_read_b128 v[196:199], v147 offset:19456
	ds_read_b128 v[200:203], v147 offset:20480
	ds_read_b128 v[204:207], v147 offset:21504
	ds_read_b128 v[208:211], v147 offset:22528
	ds_read_b128 v[212:215], v147 offset:23552
	global_load_lds_dwordx4 v130, s[52:53]
	s_add_i32 m0, s77, 0x2000
	s_add_u32 s78, s52, 0x40000
	s_addc_u32 s79, s53, 0
	s_add_i32 s77, s70, s61
	global_load_lds_dwordx4 v134, s[52:53]
	s_mov_b32 m0, s77
	s_nop 0
	global_load_lds_dwordx4 v130, s[78:79]
	s_add_i32 m0, s77, 0x2000
	s_nop 0
	global_load_lds_dwordx4 v134, s[78:79]
	s_waitcnt vmcnt(6)
	s_waitcnt lgkmcnt(0)
	s_barrier
	s_setprio 1
	s_waitcnt lgkmcnt(0)
	v_mfma_f32_16x16x32_bf16 v[60:63], v[148:151], v[180:183], v[60:63]
	v_mfma_f32_16x16x32_bf16 v[56:59], v[156:159], v[180:183], v[56:59]
	v_mfma_f32_16x16x32_bf16 v[52:55], v[148:151], v[192:195], v[52:55]
	v_mfma_f32_16x16x32_bf16 v[44:47], v[156:159], v[192:195], v[44:47]
	v_mfma_f32_16x16x32_bf16 v[36:39], v[148:151], v[200:203], v[36:39]
	v_mfma_f32_16x16x32_bf16 v[28:31], v[156:159], v[200:203], v[28:31]
	v_mfma_f32_16x16x32_bf16 v[20:23], v[148:151], v[208:211], v[20:23]
	v_mfma_f32_16x16x32_bf16 v[12:15], v[156:159], v[208:211], v[12:15]
	v_mfma_f32_16x16x32_bf16 v[60:63], v[152:155], v[188:191], v[60:63]
	v_mfma_f32_16x16x32_bf16 v[56:59], v[160:163], v[188:191], v[56:59]
	v_mfma_f32_16x16x32_bf16 v[52:55], v[152:155], v[196:199], v[52:55]
	v_mfma_f32_16x16x32_bf16 v[44:47], v[160:163], v[196:199], v[44:47]
	v_mfma_f32_16x16x32_bf16 v[36:39], v[152:155], v[204:207], v[36:39]
	v_mfma_f32_16x16x32_bf16 v[28:31], v[160:163], v[204:207], v[28:31]
	v_mfma_f32_16x16x32_bf16 v[20:23], v[152:155], v[212:215], v[20:23]
	v_mfma_f32_16x16x32_bf16 v[12:15], v[160:163], v[212:215], v[12:15]
	s_setprio 0
	s_setprio 1
	v_mfma_f32_16x16x32_bf16 v[48:51], v[164:167], v[180:183], v[48:51]
	v_mfma_f32_16x16x32_bf16 v[40:43], v[172:175], v[180:183], v[40:43]
	v_mfma_f32_16x16x32_bf16 v[32:35], v[164:167], v[192:195], v[32:35]
	v_mfma_f32_16x16x32_bf16 v[24:27], v[172:175], v[192:195], v[24:27]
	v_mfma_f32_16x16x32_bf16 v[16:19], v[164:167], v[200:203], v[16:19]
	v_mfma_f32_16x16x32_bf16 v[8:11], v[172:175], v[200:203], v[8:11]
	v_mfma_f32_16x16x32_bf16 v[4:7], v[164:167], v[208:211], v[4:7]
	v_mfma_f32_16x16x32_bf16 v[0:3], v[172:175], v[208:211], v[0:3]
	v_mfma_f32_16x16x32_bf16 v[48:51], v[168:171], v[188:191], v[48:51]
	v_mfma_f32_16x16x32_bf16 v[40:43], v[176:179], v[188:191], v[40:43]
	v_mfma_f32_16x16x32_bf16 v[32:35], v[168:171], v[196:199], v[32:35]
	v_mfma_f32_16x16x32_bf16 v[24:27], v[176:179], v[196:199], v[24:27]
	v_mfma_f32_16x16x32_bf16 v[16:19], v[168:171], v[204:207], v[16:19]
	v_mfma_f32_16x16x32_bf16 v[8:11], v[176:179], v[204:207], v[8:11]
	v_mfma_f32_16x16x32_bf16 v[4:7], v[168:171], v[212:215], v[4:7]
	v_mfma_f32_16x16x32_bf16 v[0:3], v[176:179], v[212:215], v[0:3]
	s_setprio 0
	s_barrier
; #define PG8_STAGE(bufoff, gbase, voff) do { _Pragma("unroll") for (int _i = 0; _i < 2; ++_i) \
;         __builtin_amdgcn_global_load_lds((const unsigned*)((const char*)(gbase) + (voff)[_i]), (PG8_LAS unsigned*)(lds + (bufoff) + ldsw + _i * 8192), 16, 0, 0); } while (0)
; #define PG8_LDA(dst, b, h) do { _Pragma("unroll") for (int m = 0; m < 4; ++m) _Pragma("unroll") for (int k = 0; k < 2; ++k) dst[m][k] = *(const PG8_LAS bf16x8*)(lds + PG8_SA(b, h) + aoff + m * 2048 + k * 1024); } while (0)
; #define PG8_LDB(dst, b, h) do { _Pragma("unroll") for (int n = 0; n < 2; ++n) _Pragma("unroll") for (int k = 0; k < 2; ++k) dst[n][k] = *(const PG8_LAS bf16x8*)(lds + PG8_SB(b, h) + boff + n * 2048 + k * 1024); } while (0)
; #define PG8_MMA(ai, bj, At, Bt) do { __builtin_amdgcn_s_setprio(1); _Pragma("unroll") for (int m = 0; m < 4; ++m) _Pragma("unroll") for (int n = 0; n < 2; ++n) _Pragma("unroll") for (int k = 0; k < 2; ++k) \
;         acc[ai][bj][m][n] = __builtin_amdgcn_mfma_f32_16x16x32_bf16(Bt[n][k], At[m][k], acc[ai][bj][m][n], 0, 0, 0); __builtin_amdgcn_s_setprio(0); } while (0)
; #define PG8_WAIT_V(n) asm volatile("s_waitcnt vmcnt(" #n ")" ::: "memory")
; #define PG8_WAIT_L(n) asm volatile("s_waitcnt lgkmcnt(" #n ")" ::: "memory")
; #define PG8_BAR __builtin_amdgcn_s_barrier()
; template <class Epi, class Sched, bool ALIGN_EPI = false, bool SP2 = false>
; __device__ __forceinline__ void gemm_phase(PG8_LAS unsigned char* lds, const Gemm g, const Sched S, const Epi E, const int tid) {
;     ...
;         for (int t = 0; t < nt; t += 2) {
;             const bool last = (t == nt - 2);
;             const char* a1 = cA + (size_t)(t + 1) * kstep;
;             const char* a2 = last ? nA : cA + (size_t)(t + 2) * kstep; const char* b2 = last ? nB : cB + (size_t)(t + 2) * kstep;
;             const char* a3 = a2 + kstep; const char* b3 = b2 + kstep;
;     ...
;             PG8_LDB(B0, 1, 0); PG8_LDB(B1, 1, 1); PG8_SCHED; PG8_LDA(At, 1, 0); PG8_STAGE(PG8_SA(0, 1), a2 + hstepA, voffA);
;             PG8_WAIT_V(8); PG8_WAIT_L(0); PG8_BAR; PG8_MMA(0, 0, At, B0); PG8_MMA(0, 1, At, B1); PG8_BAR; PG8_SCHED;
;             PG8_LDA(At, 1, 1); PG8_STAGE(PG8_SB(1, 0), b3, voffB); PG8_STAGE(PG8_SB(1, 1), b3 + hstepB, voffB); PG8_STAGE(PG8_SA(1, 0), a3, voffA);
;             PG8_WAIT_V(8); PG8_WAIT_L(0); PG8_BAR; PG8_MMA(1, 0, At, B0); PG8_MMA(1, 1, At, B1); PG8_BAR; PG8_SCHED;
	s_add_i32 s77, 0, 0x18000
	s_add_i32 s78, 0, 0x1c000
	v_add_u32_e32 v160, s77, v143
	v_add_u32_e32 v176, s78, v143
	ds_read_b128 v[148:151], v160
	ds_read_b128 v[152:155], v160 offset:1024
	ds_read_b128 v[156:159], v160 offset:2048
	ds_read_b128 v[160:163], v160 offset:3072
	ds_read_b128 v[164:167], v176
	ds_read_b128 v[168:171], v176 offset:1024
	ds_read_b128 v[172:175], v176 offset:2048
	ds_read_b128 v[176:179], v176 offset:3072
	s_mov_b32 m0, s49
	s_nop 0
	global_load_lds_dwordx4 v128, s[54:55]
	s_mov_b32 m0, s62
	s_nop 0
	global_load_lds_dwordx4 v132, s[54:55]
	s_add_u32 s54, s54, 0x40000
	s_addc_u32 s55, s55, 0
	s_mov_b32 m0, s63
	ds_read_b128 v[180:183], v147 offset:32768
	ds_read_b128 v[188:191], v147 offset:33792
	ds_read_b128 v[192:195], v147 offset:34816
	ds_read_b128 v[196:199], v147 offset:35840
	ds_read_b128 v[200:203], v147 offset:36864
	ds_read_b128 v[204:207], v147 offset:37888
	ds_read_b128 v[208:211], v147 offset:38912
	ds_read_b128 v[212:215], v147 offset:39936
	global_load_lds_dwordx4 v128, s[54:55]
	s_mov_b32 m0, s64
	s_nop 0
	global_load_lds_dwordx4 v132, s[54:55]
	s_waitcnt vmcnt(8)
	s_waitcnt lgkmcnt(0)
	s_barrier
	s_setprio 1
	s_waitcnt lgkmcnt(0)
	v_mfma_f32_16x16x32_bf16 v[124:127], v[148:151], v[180:183], v[124:127]
	v_mfma_f32_16x16x32_bf16 v[120:123], v[156:159], v[180:183], v[120:123]
	v_mfma_f32_16x16x32_bf16 v[112:115], v[148:151], v[192:195], v[112:115]
	v_mfma_f32_16x16x32_bf16 v[104:107], v[156:159], v[192:195], v[104:107]
	v_mfma_f32_16x16x32_bf16 v[96:99], v[148:151], v[200:203], v[96:99]
	v_mfma_f32_16x16x32_bf16 v[88:91], v[156:159], v[200:203], v[88:91]
	v_mfma_f32_16x16x32_bf16 v[80:83], v[148:151], v[208:211], v[80:83]
	v_mfma_f32_16x16x32_bf16 v[72:75], v[156:159], v[208:211], v[72:75]
	v_mfma_f32_16x16x32_bf16 v[124:127], v[152:155], v[188:191], v[124:127]
	v_mfma_f32_16x16x32_bf16 v[120:123], v[160:163], v[188:191], v[120:123]
	v_mfma_f32_16x16x32_bf16 v[112:115], v[152:155], v[196:199], v[112:115]
	v_mfma_f32_16x16x32_bf16 v[104:107], v[160:163], v[196:199], v[104:107]
	v_mfma_f32_16x16x32_bf16 v[96:99], v[152:155], v[204:207], v[96:99]
	v_mfma_f32_16x16x32_bf16 v[88:91], v[160:163], v[204:207], v[88:91]
	v_mfma_f32_16x16x32_bf16 v[80:83], v[152:155], v[212:215], v[80:83]
	v_mfma_f32_16x16x32_bf16 v[72:75], v[160:163], v[212:215], v[72:75]
	s_setprio 0
	s_setprio 1
	v_mfma_f32_16x16x32_bf16 v[116:119], v[164:167], v[180:183], v[116:119]
	v_mfma_f32_16x16x32_bf16 v[108:111], v[172:175], v[180:183], v[108:111]
	v_mfma_f32_16x16x32_bf16 v[100:103], v[164:167], v[192:195], v[100:103]
	v_mfma_f32_16x16x32_bf16 v[92:95], v[172:175], v[192:195], v[92:95]
	v_mfma_f32_16x16x32_bf16 v[84:87], v[164:167], v[200:203], v[84:87]
	v_mfma_f32_16x16x32_bf16 v[76:79], v[172:175], v[200:203], v[76:79]
	v_mfma_f32_16x16x32_bf16 v[68:71], v[164:167], v[208:211], v[68:71]
	v_mfma_f32_16x16x32_bf16 v[64:67], v[172:175], v[208:211], v[64:67]
	v_mfma_f32_16x16x32_bf16 v[116:119], v[168:171], v[188:191], v[116:119]
	v_mfma_f32_16x16x32_bf16 v[108:111], v[176:179], v[188:191], v[108:111]
	v_mfma_f32_16x16x32_bf16 v[100:103], v[168:171], v[196:199], v[100:103]
	v_mfma_f32_16x16x32_bf16 v[92:95], v[176:179], v[196:199], v[92:95]
	v_mfma_f32_16x16x32_bf16 v[84:87], v[168:171], v[204:207], v[84:87]
	v_mfma_f32_16x16x32_bf16 v[76:79], v[176:179], v[204:207], v[76:79]
	v_mfma_f32_16x16x32_bf16 v[68:71], v[168:171], v[212:215], v[68:71]
	v_mfma_f32_16x16x32_bf16 v[64:67], v[176:179], v[212:215], v[64:67]
	s_setprio 0
	s_barrier
	s_add_i32 s54, s77, s61
	s_mov_b32 m0, s54
	ds_read_b128 v[180:183], v147 offset:49152
	ds_read_b128 v[188:191], v147 offset:50176
	ds_read_b128 v[192:195], v147 offset:51200
	ds_read_b128 v[196:199], v147 offset:52224
	ds_read_b128 v[200:203], v147 offset:53248
	ds_read_b128 v[204:207], v147 offset:54272
	ds_read_b128 v[208:211], v147 offset:55296
	ds_read_b128 v[212:215], v147 offset:56320
	global_load_lds_dwordx4 v130, s[98:99]
	s_add_i32 m0, s54, 0x2000
	s_add_u32 s52, s52, 0x40080
	s_addc_u32 s53, s53, 0
	s_add_i32 s54, s78, s61
	global_load_lds_dwordx4 v134, s[98:99]
	s_mov_b32 m0, s54
	s_nop 0
	global_load_lds_dwordx4 v130, s[52:53]
	s_add_i32 m0, s54, 0x2000
	s_nop 0
	global_load_lds_dwordx4 v134, s[52:53]
	s_mov_b32 m0, s66
	s_nop 0
	global_load_lds_dwordx4 v128, s[100:101]
	s_mov_b32 m0, s67
	s_nop 0
	global_load_lds_dwordx4 v132, s[100:101]
	s_waitcnt vmcnt(8)
	s_waitcnt lgkmcnt(0)
	s_barrier
	s_setprio 1
	s_waitcnt lgkmcnt(0)
	v_mfma_f32_16x16x32_bf16 v[60:63], v[148:151], v[180:183], v[60:63]
	v_mfma_f32_16x16x32_bf16 v[56:59], v[156:159], v[180:183], v[56:59]
	v_mfma_f32_16x16x32_bf16 v[52:55], v[148:151], v[192:195], v[52:55]
	v_mfma_f32_16x16x32_bf16 v[44:47], v[156:159], v[192:195], v[44:47]
	v_mfma_f32_16x16x32_bf16 v[36:39], v[148:151], v[200:203], v[36:39]
	v_mfma_f32_16x16x32_bf16 v[28:31], v[156:159], v[200:203], v[28:31]
	v_mfma_f32_16x16x32_bf16 v[20:23], v[148:151], v[208:211], v[20:23]
	v_mfma_f32_16x16x32_bf16 v[12:15], v[156:159], v[208:211], v[12:15]
	v_mfma_f32_16x16x32_bf16 v[60:63], v[152:155], v[188:191], v[60:63]
	v_mfma_f32_16x16x32_bf16 v[56:59], v[160:163], v[188:191], v[56:59]
	v_mfma_f32_16x16x32_bf16 v[52:55], v[152:155], v[196:199], v[52:55]
	v_mfma_f32_16x16x32_bf16 v[44:47], v[160:163], v[196:199], v[44:47]
	v_mfma_f32_16x16x32_bf16 v[36:39], v[152:155], v[204:207], v[36:39]
	v_mfma_f32_16x16x32_bf16 v[28:31], v[160:163], v[204:207], v[28:31]
	v_mfma_f32_16x16x32_bf16 v[20:23], v[152:155], v[212:215], v[20:23]
	v_mfma_f32_16x16x32_bf16 v[12:15], v[160:163], v[212:215], v[12:15]
	s_setprio 0
	s_setprio 1
	v_mfma_f32_16x16x32_bf16 v[48:51], v[164:167], v[180:183], v[48:51]
	v_mfma_f32_16x16x32_bf16 v[40:43], v[172:175], v[180:183], v[40:43]
	v_mfma_f32_16x16x32_bf16 v[32:35], v[164:167], v[192:195], v[32:35]
	v_mfma_f32_16x16x32_bf16 v[24:27], v[172:175], v[192:195], v[24:27]
	v_mfma_f32_16x16x32_bf16 v[16:19], v[164:167], v[200:203], v[16:19]
	v_mfma_f32_16x16x32_bf16 v[8:11], v[172:175], v[200:203], v[8:11]
	v_mfma_f32_16x16x32_bf16 v[4:7], v[164:167], v[208:211], v[4:7]
	v_mfma_f32_16x16x32_bf16 v[0:3], v[172:175], v[208:211], v[0:3]
	v_mfma_f32_16x16x32_bf16 v[48:51], v[168:171], v[188:191], v[48:51]
	v_mfma_f32_16x16x32_bf16 v[40:43], v[176:179], v[188:191], v[40:43]
	v_mfma_f32_16x16x32_bf16 v[32:35], v[168:171], v[196:199], v[32:35]
	v_mfma_f32_16x16x32_bf16 v[24:27], v[176:179], v[196:199], v[24:27]
	v_mfma_f32_16x16x32_bf16 v[16:19], v[168:171], v[204:207], v[16:19]
	v_mfma_f32_16x16x32_bf16 v[8:11], v[176:179], v[204:207], v[8:11]
	v_mfma_f32_16x16x32_bf16 v[4:7], v[168:171], v[212:215], v[4:7]
	v_mfma_f32_16x16x32_bf16 v[0:3], v[176:179], v[212:215], v[0:3]
	s_setprio 0
	s_barrier
	s_add_i32 s76, s76, 2
	s_add_u32 s50, s50, 0x100
	s_addc_u32 s51, s51, 0
	s_add_u32 s74, s74, 0x100
	s_addc_u32 s75, s75, 0
	s_cmp_gt_u32 s76, 13
	s_cbranch_scc0 .LBB0_1255
	s_and_b64 vcc, exec, s[8:9]
	s_cbranch_vccz .LBB0_1258
	s_barrier
